# v81 + P9 K-loops: s_setprio flips and redundant post-barrier waits removed, bursts at phase 4
# baseline (speedup 1.0000x reference)
; #define PG8_STAGE(bufoff, gbase, voff) do { _Pragma("unroll") for (int _i = 0; _i < 2; ++_i) \
;         __builtin_amdgcn_global_load_lds((const unsigned*)((const char*)(gbase) + (voff)[_i]), (PG8_LAS unsigned*)(lds + (bufoff) + ldsw + _i * 8192), 16, 0, 0); } while (0)
; #define PG8_STAGE_NT(bufoff, gbase, voff) do { _Pragma("unroll") for (int _i = 0; _i < 2; ++_i) \
;         __builtin_amdgcn_global_load_lds((const unsigned*)((const char*)(gbase) + (voff)[_i]), (PG8_LAS unsigned*)(lds + (bufoff) + ldsw + _i * 8192), 16, 0, PG8_B_AUX); } while (0)
; #define PG8_LDA(dst, b, h) do { _Pragma("unroll") for (int m = 0; m < 4; ++m) _Pragma("unroll") for (int k = 0; k < 2; ++k) dst[m][k] = *(const PG8_LAS bf16x8*)(lds + PG8_SA(b, h) + aoff + m * 2048 + k * 1024); } while (0)
; #define PG8_LDB(dst, b, h) do { _Pragma("unroll") for (int n = 0; n < 2; ++n) _Pragma("unroll") for (int k = 0; k < 2; ++k) dst[n][k] = *(const PG8_LAS bf16x8*)(lds + PG8_SB(b, h) + boff + n * 2048 + k * 1024); } while (0)
; #define PG8_WAIT_V(n) asm volatile("s_waitcnt vmcnt(" #n ")" ::: "memory")
; #define PG8_WAIT_L(n) asm volatile("s_waitcnt lgkmcnt(" #n ")" ::: "memory")
; #define PG8_BAR __builtin_amdgcn_s_barrier()
; #define PG8_SCHED __builtin_amdgcn_sched_barrier(0)
; template <class Epi, class Sched, bool ALIGN_EPI = false, bool SP2 = false>
; __device__ __forceinline__ void gemm_phase(PG8_LAS unsigned char* lds, const Gemm g, const Sched& S, const Epi& E, int wid) {
;     ...
;             const bool last = (t == nt - 2);
;             const char* a1 = cA + (size_t)(t + 1) * kstep;
;             const char* a2 = last ? nA : cA + (size_t)(t + 2) * kstep; const char* b2 = last ? nB : cB + (size_t)(t + 2) * kstep;
;             const char* a3 = a2 + kstep; const char* b3 = b2 + kstep;
;             if (last && has_next) S.a_ready(nxt);
;             if constexpr (SP2) {
;             PG8_LDB(B0, 0, 0); PG8_LDB(B1, 0, 1); PG8_SCHED; PG8_LDA(At, 0, 0); PG8_STAGE(PG8_SA(1, 1), a1 + hstepA, voffA);
;             PG8_WAIT_V(8); PG8_WAIT_L(0); PG8_BAR; PG8_MMA(0, 0, At, B0); PG8_MMA(0, 1, At, B1); PG8_BAR; PG8_SCHED;
;             PG8_LDA(At, 0, 1); PG8_STAGE_NT(PG8_SB(0, 0), b2, voffB); PG8_STAGE_NT(PG8_SB(0, 1), b2 + hstepB, voffB); PG8_STAGE(PG8_SA(0, 0), a2, voffA);
;             PG8_WAIT_V(8); PG8_WAIT_L(0); PG8_BAR; PG8_MMA(1, 0, At, B0); PG8_MMA(1, 1, At, B1); PG8_BAR; PG8_SCHED;
.LBB0_233:
	ds_read_b128 v[144:147], v155
	ds_read_b128 v[148:151], v155 offset:1024
	ds_read_b128 v[160:163], v155 offset:2048
	ds_read_b128 v[164:167], v155 offset:3072
	ds_read_b128 v[168:171], v156
	ds_read_b128 v[172:175], v156 offset:1024
	ds_read_b128 v[176:179], v156 offset:2048
	ds_read_b128 v[180:183], v156 offset:3072
	s_add_u32 s4, s48, 0x100
	s_addc_u32 s5, s49, 0
	s_add_u32 s98, s48, 0x80
	s_addc_u32 s99, s49, 0
	s_add_u32 s100, s48, 0x104080
	s_addc_u32 s101, s49, 0
	s_cmp_eq_u32 s66, 60
	s_cselect_b32 s53, s45, s5
	s_cselect_b32 s52, s44, s4
	s_cselect_b32 s51, s47, s65
	s_cselect_b32 s50, s46, s64
	s_add_i32 m0, s23, 0xc000
	ds_read_b128 v[184:187], v157
	ds_read_b128 v[188:191], v157 offset:1024
	ds_read_b128 v[192:195], v157 offset:2048
	ds_read_b128 v[196:199], v157 offset:3072
	ds_read_b128 v[200:203], v157 offset:4096
	ds_read_b128 v[204:207], v157 offset:5120
	ds_read_b128 v[208:211], v157 offset:6144
	ds_read_b128 v[212:215], v157 offset:7168
	global_load_lds_dwordx4 v134, s[100:101]
	s_add_i32 m0, s23, 0xe000
	s_nop 0
	global_load_lds_dwordx4 v130, s[100:101]
	s_mov_b32 m0, s55
	s_nop 0
	global_load_lds_dwordx4 v134, s[98:99]
	s_mov_b32 m0, s56
	s_nop 0
	global_load_lds_dwordx4 v130, s[98:99]
	s_nop 0
	s_waitcnt vmcnt(8)
	s_waitcnt lgkmcnt(0)
	s_barrier
	v_mfma_f32_16x16x32_bf16 v[112:115], v[144:147], v[184:187], v[112:115]
	v_mfma_f32_16x16x32_bf16 v[108:111], v[160:163], v[184:187], v[108:111]
	v_mfma_f32_16x16x32_bf16 v[104:107], v[144:147], v[192:195], v[104:107]
	v_mfma_f32_16x16x32_bf16 v[100:103], v[160:163], v[192:195], v[100:103]
	v_mfma_f32_16x16x32_bf16 v[92:95], v[144:147], v[200:203], v[92:95]
	v_mfma_f32_16x16x32_bf16 v[84:87], v[160:163], v[200:203], v[84:87]
	v_mfma_f32_16x16x32_bf16 v[76:79], v[144:147], v[208:211], v[76:79]
	v_mfma_f32_16x16x32_bf16 v[68:71], v[160:163], v[208:211], v[68:71]
	v_mfma_f32_16x16x32_bf16 v[112:115], v[148:151], v[188:191], v[112:115]
	v_mfma_f32_16x16x32_bf16 v[108:111], v[164:167], v[188:191], v[108:111]
	v_mfma_f32_16x16x32_bf16 v[104:107], v[148:151], v[196:199], v[104:107]
	v_mfma_f32_16x16x32_bf16 v[100:103], v[164:167], v[196:199], v[100:103]
	v_mfma_f32_16x16x32_bf16 v[92:95], v[148:151], v[204:207], v[92:95]
	v_mfma_f32_16x16x32_bf16 v[84:87], v[164:167], v[204:207], v[84:87]
	v_mfma_f32_16x16x32_bf16 v[76:79], v[148:151], v[212:215], v[76:79]
	v_mfma_f32_16x16x32_bf16 v[68:71], v[164:167], v[212:215], v[68:71]
	v_mfma_f32_16x16x32_bf16 v[124:127], v[168:171], v[184:187], v[124:127]
	v_mfma_f32_16x16x32_bf16 v[120:123], v[176:179], v[184:187], v[120:123]
	v_mfma_f32_16x16x32_bf16 v[116:119], v[168:171], v[192:195], v[116:119]
	v_mfma_f32_16x16x32_bf16 v[96:99], v[176:179], v[192:195], v[96:99]
	v_mfma_f32_16x16x32_bf16 v[88:91], v[168:171], v[200:203], v[88:91]
	v_mfma_f32_16x16x32_bf16 v[80:83], v[176:179], v[200:203], v[80:83]
	v_mfma_f32_16x16x32_bf16 v[72:75], v[168:171], v[208:211], v[72:75]
	v_mfma_f32_16x16x32_bf16 v[64:67], v[176:179], v[208:211], v[64:67]
	v_mfma_f32_16x16x32_bf16 v[124:127], v[172:175], v[188:191], v[124:127]
	v_mfma_f32_16x16x32_bf16 v[120:123], v[180:183], v[188:191], v[120:123]
	v_mfma_f32_16x16x32_bf16 v[116:119], v[172:175], v[196:199], v[116:119]
	v_mfma_f32_16x16x32_bf16 v[96:99], v[180:183], v[196:199], v[96:99]
	v_mfma_f32_16x16x32_bf16 v[88:91], v[172:175], v[204:207], v[88:91]
	v_mfma_f32_16x16x32_bf16 v[80:83], v[180:183], v[204:207], v[80:83]
	v_mfma_f32_16x16x32_bf16 v[72:75], v[172:175], v[212:215], v[72:75]
	v_mfma_f32_16x16x32_bf16 v[64:67], v[180:183], v[212:215], v[64:67]
	s_barrier
	s_add_i32 s48, s58, s17
	s_mov_b32 m0, s48
	ds_read_b128 v[184:187], v157 offset:16384
	ds_read_b128 v[188:191], v157 offset:17408
	ds_read_b128 v[192:195], v157 offset:18432
	ds_read_b128 v[196:199], v157 offset:19456
	ds_read_b128 v[200:203], v157 offset:20480
	ds_read_b128 v[204:207], v157 offset:21504
	ds_read_b128 v[208:211], v157 offset:22528
	ds_read_b128 v[212:215], v157 offset:23552
	global_load_lds_dwordx4 v132, s[50:51]
	s_add_i32 m0, s48, 0x2000
	s_add_u32 s48, s50, 0x104000
	s_addc_u32 s49, s51, 0
	s_add_i32 s67, s59, s17
	global_load_lds_dwordx4 v128, s[50:51]
	s_mov_b32 m0, s67
	s_nop 0
	global_load_lds_dwordx4 v132, s[48:49]
	s_add_i32 m0, s67, 0x2000
	s_nop 0
	global_load_lds_dwordx4 v128, s[48:49]
	s_nop 0
	s_waitcnt vmcnt(4)
	s_waitcnt lgkmcnt(0)
	s_barrier
	v_mfma_f32_16x16x32_bf16 v[60:63], v[144:147], v[184:187], v[60:63]
	v_mfma_f32_16x16x32_bf16 v[52:55], v[160:163], v[184:187], v[52:55]
	v_mfma_f32_16x16x32_bf16 v[44:47], v[144:147], v[192:195], v[44:47]
	v_mfma_f32_16x16x32_bf16 v[36:39], v[160:163], v[192:195], v[36:39]
	v_mfma_f32_16x16x32_bf16 v[28:31], v[144:147], v[200:203], v[28:31]
	v_mfma_f32_16x16x32_bf16 v[20:23], v[160:163], v[200:203], v[20:23]
	v_mfma_f32_16x16x32_bf16 v[12:15], v[144:147], v[208:211], v[12:15]
	v_mfma_f32_16x16x32_bf16 v[4:7], v[160:163], v[208:211], v[4:7]
	v_mfma_f32_16x16x32_bf16 v[60:63], v[148:151], v[188:191], v[60:63]
	v_mfma_f32_16x16x32_bf16 v[52:55], v[164:167], v[188:191], v[52:55]
	v_mfma_f32_16x16x32_bf16 v[44:47], v[148:151], v[196:199], v[44:47]
	v_mfma_f32_16x16x32_bf16 v[36:39], v[164:167], v[196:199], v[36:39]
	v_mfma_f32_16x16x32_bf16 v[28:31], v[148:151], v[204:207], v[28:31]
	v_mfma_f32_16x16x32_bf16 v[20:23], v[164:167], v[204:207], v[20:23]
	v_mfma_f32_16x16x32_bf16 v[12:15], v[148:151], v[212:215], v[12:15]
	v_mfma_f32_16x16x32_bf16 v[4:7], v[164:167], v[212:215], v[4:7]
	v_mfma_f32_16x16x32_bf16 v[56:59], v[168:171], v[184:187], v[56:59]
	v_mfma_f32_16x16x32_bf16 v[48:51], v[176:179], v[184:187], v[48:51]
	v_mfma_f32_16x16x32_bf16 v[40:43], v[168:171], v[192:195], v[40:43]
	v_mfma_f32_16x16x32_bf16 v[32:35], v[176:179], v[192:195], v[32:35]
	v_mfma_f32_16x16x32_bf16 v[24:27], v[168:171], v[200:203], v[24:27]
	v_mfma_f32_16x16x32_bf16 v[16:19], v[176:179], v[200:203], v[16:19]
	v_mfma_f32_16x16x32_bf16 v[8:11], v[168:171], v[208:211], v[8:11]
	v_mfma_f32_16x16x32_bf16 v[0:3], v[176:179], v[208:211], v[0:3]
	v_mfma_f32_16x16x32_bf16 v[56:59], v[172:175], v[188:191], v[56:59]
	v_mfma_f32_16x16x32_bf16 v[48:51], v[180:183], v[188:191], v[48:51]
	v_mfma_f32_16x16x32_bf16 v[40:43], v[172:175], v[196:199], v[40:43]
	v_mfma_f32_16x16x32_bf16 v[32:35], v[180:183], v[196:199], v[32:35]
	v_mfma_f32_16x16x32_bf16 v[24:27], v[172:175], v[204:207], v[24:27]
	v_mfma_f32_16x16x32_bf16 v[16:19], v[180:183], v[204:207], v[16:19]
	v_mfma_f32_16x16x32_bf16 v[8:11], v[172:175], v[212:215], v[8:11]
	v_mfma_f32_16x16x32_bf16 v[0:3], v[180:183], v[212:215], v[0:3]
	s_barrier
; #define PG8_STAGE(bufoff, gbase, voff) do { _Pragma("unroll") for (int _i = 0; _i < 2; ++_i) \
;         __builtin_amdgcn_global_load_lds((const unsigned*)((const char*)(gbase) + (voff)[_i]), (PG8_LAS unsigned*)(lds + (bufoff) + ldsw + _i * 8192), 16, 0, 0); } while (0)
; #define PG8_STAGE_NT(bufoff, gbase, voff) do { _Pragma("unroll") for (int _i = 0; _i < 2; ++_i) \
;         __builtin_amdgcn_global_load_lds((const unsigned*)((const char*)(gbase) + (voff)[_i]), (PG8_LAS unsigned*)(lds + (bufoff) + ldsw + _i * 8192), 16, 0, PG8_B_AUX); } while (0)
; #define PG8_LDA(dst, b, h) do { _Pragma("unroll") for (int m = 0; m < 4; ++m) _Pragma("unroll") for (int k = 0; k < 2; ++k) dst[m][k] = *(const PG8_LAS bf16x8*)(lds + PG8_SA(b, h) + aoff + m * 2048 + k * 1024); } while (0)
; #define PG8_LDB(dst, b, h) do { _Pragma("unroll") for (int n = 0; n < 2; ++n) _Pragma("unroll") for (int k = 0; k < 2; ++k) dst[n][k] = *(const PG8_LAS bf16x8*)(lds + PG8_SB(b, h) + boff + n * 2048 + k * 1024); } while (0)
; #define PG8_MMA(ai, bj, At, Bt) do { __builtin_amdgcn_s_setprio(1); _Pragma("unroll") for (int m = 0; m < 4; ++m) _Pragma("unroll") for (int n = 0; n < 2; ++n) _Pragma("unroll") for (int k = 0; k < 2; ++k) \
;         acc[ai][bj][m][n] = __builtin_amdgcn_mfma_f32_16x16x32_bf16(Bt[n][k], At[m][k], acc[ai][bj][m][n], 0, 0, 0); __builtin_amdgcn_s_setprio(0); } while (0)
; #define PG8_WAIT_V(n) asm volatile("s_waitcnt vmcnt(" #n ")" ::: "memory")
; #define PG8_WAIT_L(n) asm volatile("s_waitcnt lgkmcnt(" #n ")" ::: "memory")
; #define PG8_BAR __builtin_amdgcn_s_barrier()
; template <class Epi, class Sched, bool ALIGN_EPI = false, bool SP2 = false>
; __device__ __forceinline__ void gemm_phase(PG8_LAS unsigned char* lds, const Gemm g, const Sched& S, const Epi& E, int wid) {
;     ...
;             PG8_LDB(B0, 1, 0); PG8_LDB(B1, 1, 1); PG8_SCHED; PG8_LDA(At, 1, 0); PG8_STAGE(PG8_SA(0, 1), a2 + hstepA, voffA);
;             PG8_WAIT_V(8); PG8_WAIT_L(0); PG8_BAR; PG8_MMA(0, 0, At, B0); PG8_MMA(0, 1, At, B1); PG8_BAR; PG8_SCHED;
;             PG8_LDA(At, 1, 1); PG8_STAGE_NT(PG8_SB(1, 0), b3, voffB); PG8_STAGE_NT(PG8_SB(1, 1), b3 + hstepB, voffB); PG8_STAGE(PG8_SA(1, 0), a3, voffA);
;             PG8_WAIT_V(8); PG8_WAIT_L(0); PG8_BAR; PG8_MMA(1, 0, At, B0); PG8_MMA(1, 1, At, B1); PG8_BAR; PG8_SCHED;
;     ...
;         if constexpr (ALIGN_EPI) { if (wr == 0) PG8_BAR; }
	s_add_i32 s67, 0, 0x18000
	v_add_u32_e32 v159, s67, v153
	s_add_i32 s68, 0, 0x1c000
	ds_read_b128 v[144:147], v159
	ds_read_b128 v[148:151], v159 offset:1024
	ds_read_b128 v[160:163], v159 offset:2048
	ds_read_b128 v[164:167], v159 offset:3072
	v_add_u32_e32 v159, s68, v153
	ds_read_b128 v[168:171], v159
	ds_read_b128 v[172:175], v159 offset:1024
	ds_read_b128 v[176:179], v159 offset:2048
	ds_read_b128 v[180:183], v159 offset:3072
	s_add_u32 s48, s52, 0x104000
	s_addc_u32 s49, s53, 0
	s_mov_b32 m0, s25
	ds_read_b128 v[184:187], v157 offset:32768
	ds_read_b128 v[188:191], v157 offset:33792
	ds_read_b128 v[192:195], v157 offset:34816
	ds_read_b128 v[196:199], v157 offset:35840
	ds_read_b128 v[200:203], v157 offset:36864
	ds_read_b128 v[204:207], v157 offset:37888
	ds_read_b128 v[208:211], v157 offset:38912
	ds_read_b128 v[212:215], v157 offset:39936
	global_load_lds_dwordx4 v134, s[48:49]
	s_mov_b32 m0, s29
	s_nop 0
	global_load_lds_dwordx4 v130, s[48:49]
	s_mov_b32 m0, s23
	s_nop 0
	global_load_lds_dwordx4 v134, s[52:53]
	s_mov_b32 m0, s24
	s_nop 0
	global_load_lds_dwordx4 v130, s[52:53]
	s_waitcnt vmcnt(8)
	s_waitcnt lgkmcnt(0)
	s_barrier
	v_mfma_f32_16x16x32_bf16 v[112:115], v[144:147], v[184:187], v[112:115]
	v_mfma_f32_16x16x32_bf16 v[108:111], v[160:163], v[184:187], v[108:111]
	v_mfma_f32_16x16x32_bf16 v[104:107], v[144:147], v[192:195], v[104:107]
	v_mfma_f32_16x16x32_bf16 v[100:103], v[160:163], v[192:195], v[100:103]
	v_mfma_f32_16x16x32_bf16 v[92:95], v[144:147], v[200:203], v[92:95]
	v_mfma_f32_16x16x32_bf16 v[84:87], v[160:163], v[200:203], v[84:87]
	v_mfma_f32_16x16x32_bf16 v[76:79], v[144:147], v[208:211], v[76:79]
	v_mfma_f32_16x16x32_bf16 v[68:71], v[160:163], v[208:211], v[68:71]
	v_mfma_f32_16x16x32_bf16 v[112:115], v[148:151], v[188:191], v[112:115]
	v_mfma_f32_16x16x32_bf16 v[108:111], v[164:167], v[188:191], v[108:111]
	v_mfma_f32_16x16x32_bf16 v[104:107], v[148:151], v[196:199], v[104:107]
	v_mfma_f32_16x16x32_bf16 v[100:103], v[164:167], v[196:199], v[100:103]
	v_mfma_f32_16x16x32_bf16 v[92:95], v[148:151], v[204:207], v[92:95]
	v_mfma_f32_16x16x32_bf16 v[84:87], v[164:167], v[204:207], v[84:87]
	v_mfma_f32_16x16x32_bf16 v[76:79], v[148:151], v[212:215], v[76:79]
	v_mfma_f32_16x16x32_bf16 v[68:71], v[164:167], v[212:215], v[68:71]
	v_mfma_f32_16x16x32_bf16 v[124:127], v[168:171], v[184:187], v[124:127]
	v_mfma_f32_16x16x32_bf16 v[120:123], v[176:179], v[184:187], v[120:123]
	v_mfma_f32_16x16x32_bf16 v[116:119], v[168:171], v[192:195], v[116:119]
	v_mfma_f32_16x16x32_bf16 v[96:99], v[176:179], v[192:195], v[96:99]
	v_mfma_f32_16x16x32_bf16 v[88:91], v[168:171], v[200:203], v[88:91]
	v_mfma_f32_16x16x32_bf16 v[80:83], v[176:179], v[200:203], v[80:83]
	v_mfma_f32_16x16x32_bf16 v[72:75], v[168:171], v[208:211], v[72:75]
	v_mfma_f32_16x16x32_bf16 v[64:67], v[176:179], v[208:211], v[64:67]
	v_mfma_f32_16x16x32_bf16 v[124:127], v[172:175], v[188:191], v[124:127]
	v_mfma_f32_16x16x32_bf16 v[120:123], v[180:183], v[188:191], v[120:123]
	v_mfma_f32_16x16x32_bf16 v[116:119], v[172:175], v[196:199], v[116:119]
	v_mfma_f32_16x16x32_bf16 v[96:99], v[180:183], v[196:199], v[96:99]
	v_mfma_f32_16x16x32_bf16 v[88:91], v[172:175], v[204:207], v[88:91]
	v_mfma_f32_16x16x32_bf16 v[80:83], v[180:183], v[204:207], v[80:83]
	v_mfma_f32_16x16x32_bf16 v[72:75], v[172:175], v[212:215], v[72:75]
	v_mfma_f32_16x16x32_bf16 v[64:67], v[180:183], v[212:215], v[64:67]
	s_barrier
	s_add_i32 s48, s67, s17
	s_mov_b32 m0, s48
	s_add_u32 s98, s50, 0x80
	s_addc_u32 s99, s51, 0
	ds_read_b128 v[184:187], v157 offset:49152
	ds_read_b128 v[188:191], v157 offset:50176
	ds_read_b128 v[192:195], v157 offset:51200
	ds_read_b128 v[196:199], v157 offset:52224
	ds_read_b128 v[200:203], v157 offset:53248
	ds_read_b128 v[204:207], v157 offset:54272
	ds_read_b128 v[208:211], v157 offset:55296
	ds_read_b128 v[212:215], v157 offset:56320
	global_load_lds_dwordx4 v132, s[98:99]
	s_add_i32 m0, s48, 0x2000
	s_add_u32 s48, s50, 0x104080
	s_addc_u32 s49, s51, 0
	s_add_i32 s50, s68, s17
	global_load_lds_dwordx4 v128, s[98:99]
	s_mov_b32 m0, s50
	s_nop 0
	global_load_lds_dwordx4 v132, s[48:49]
	s_add_i32 m0, s50, 0x2000
	s_nop 0
	global_load_lds_dwordx4 v128, s[48:49]
	s_waitcnt vmcnt(4)
	s_waitcnt lgkmcnt(0)
	s_barrier
	v_mfma_f32_16x16x32_bf16 v[60:63], v[144:147], v[184:187], v[60:63]
	v_mfma_f32_16x16x32_bf16 v[52:55], v[160:163], v[184:187], v[52:55]
	v_mfma_f32_16x16x32_bf16 v[44:47], v[144:147], v[192:195], v[44:47]
	v_mfma_f32_16x16x32_bf16 v[36:39], v[160:163], v[192:195], v[36:39]
	v_mfma_f32_16x16x32_bf16 v[28:31], v[144:147], v[200:203], v[28:31]
	v_mfma_f32_16x16x32_bf16 v[20:23], v[160:163], v[200:203], v[20:23]
	v_mfma_f32_16x16x32_bf16 v[12:15], v[144:147], v[208:211], v[12:15]
	v_mfma_f32_16x16x32_bf16 v[4:7], v[160:163], v[208:211], v[4:7]
	v_mfma_f32_16x16x32_bf16 v[60:63], v[148:151], v[188:191], v[60:63]
	v_mfma_f32_16x16x32_bf16 v[52:55], v[164:167], v[188:191], v[52:55]
	v_mfma_f32_16x16x32_bf16 v[44:47], v[148:151], v[196:199], v[44:47]
	v_mfma_f32_16x16x32_bf16 v[36:39], v[164:167], v[196:199], v[36:39]
	v_mfma_f32_16x16x32_bf16 v[28:31], v[148:151], v[204:207], v[28:31]
	v_mfma_f32_16x16x32_bf16 v[20:23], v[164:167], v[204:207], v[20:23]
	v_mfma_f32_16x16x32_bf16 v[12:15], v[148:151], v[212:215], v[12:15]
	v_mfma_f32_16x16x32_bf16 v[4:7], v[164:167], v[212:215], v[4:7]
	v_mfma_f32_16x16x32_bf16 v[56:59], v[168:171], v[184:187], v[56:59]
	v_mfma_f32_16x16x32_bf16 v[48:51], v[176:179], v[184:187], v[48:51]
	v_mfma_f32_16x16x32_bf16 v[40:43], v[168:171], v[192:195], v[40:43]
	v_mfma_f32_16x16x32_bf16 v[32:35], v[176:179], v[192:195], v[32:35]
	v_mfma_f32_16x16x32_bf16 v[24:27], v[168:171], v[200:203], v[24:27]
	v_mfma_f32_16x16x32_bf16 v[16:19], v[176:179], v[200:203], v[16:19]
	v_mfma_f32_16x16x32_bf16 v[8:11], v[168:171], v[208:211], v[8:11]
	v_mfma_f32_16x16x32_bf16 v[0:3], v[176:179], v[208:211], v[0:3]
	v_mfma_f32_16x16x32_bf16 v[56:59], v[172:175], v[188:191], v[56:59]
	v_mfma_f32_16x16x32_bf16 v[48:51], v[180:183], v[188:191], v[48:51]
	v_mfma_f32_16x16x32_bf16 v[40:43], v[172:175], v[196:199], v[40:43]
	v_mfma_f32_16x16x32_bf16 v[32:35], v[180:183], v[196:199], v[32:35]
	v_mfma_f32_16x16x32_bf16 v[24:27], v[172:175], v[204:207], v[24:27]
	v_mfma_f32_16x16x32_bf16 v[16:19], v[180:183], v[204:207], v[16:19]
	v_mfma_f32_16x16x32_bf16 v[8:11], v[172:175], v[212:215], v[8:11]
	v_mfma_f32_16x16x32_bf16 v[0:3], v[180:183], v[212:215], v[0:3]
	s_barrier
	s_add_i32 s66, s66, 2
	s_add_u32 s64, s64, 0x100
	s_addc_u32 s65, s65, 0
	s_cmp_gt_u32 s66, 61
	s_mov_b64 s[48:49], s[4:5]
	s_cbranch_scc0 .LBB0_233
	s_and_b64 vcc, exec, s[42:43]
	s_cbranch_vccz .LBB0_236
	s_barrier

; #define PG8_STAGE(bufoff, gbase, voff) do { _Pragma("unroll") for (int _i = 0; _i < 2; ++_i) \
;         __builtin_amdgcn_global_load_lds((const unsigned*)((const char*)(gbase) + (voff)[_i]), (PG8_LAS unsigned*)(lds + (bufoff) + ldsw + _i * 8192), 16, 0, 0); } while (0)
; #define PG8_STAGE_NT(bufoff, gbase, voff) do { _Pragma("unroll") for (int _i = 0; _i < 2; ++_i) \
;         __builtin_amdgcn_global_load_lds((const unsigned*)((const char*)(gbase) + (voff)[_i]), (PG8_LAS unsigned*)(lds + (bufoff) + ldsw + _i * 8192), 16, 0, PG8_B_AUX); } while (0)
; #define PG8_LDA(dst, b, h) do { _Pragma("unroll") for (int m = 0; m < 4; ++m) _Pragma("unroll") for (int k = 0; k < 2; ++k) dst[m][k] = *(const PG8_LAS bf16x8*)(lds + PG8_SA(b, h) + aoff + m * 2048 + k * 1024); } while (0)
; #define PG8_LDB(dst, b, h) do { _Pragma("unroll") for (int n = 0; n < 2; ++n) _Pragma("unroll") for (int k = 0; k < 2; ++k) dst[n][k] = *(const PG8_LAS bf16x8*)(lds + PG8_SB(b, h) + boff + n * 2048 + k * 1024); } while (0)
; #define PG8_WAIT_V(n) asm volatile("s_waitcnt vmcnt(" #n ")" ::: "memory")
; #define PG8_WAIT_L(n) asm volatile("s_waitcnt lgkmcnt(" #n ")" ::: "memory")
; #define PG8_BAR __builtin_amdgcn_s_barrier()
; #define PG8_SCHED __builtin_amdgcn_sched_barrier(0)
; template <class Epi, class Sched, bool ALIGN_EPI = false, bool SP2 = false>
; __device__ __forceinline__ void gemm_phase(PG8_LAS unsigned char* lds, const Gemm g, const Sched& S, const Epi& E, int wid) {
;     ...
;             const bool last = (t == nt - 2);
;             const char* a1 = cA + (size_t)(t + 1) * kstep;
;             const char* a2 = last ? nA : cA + (size_t)(t + 2) * kstep; const char* b2 = last ? nB : cB + (size_t)(t + 2) * kstep;
;             const char* a3 = a2 + kstep; const char* b3 = b2 + kstep;
;             if (last && has_next) S.a_ready(nxt);
;             if constexpr (SP2) {
;             PG8_LDB(B0, 0, 0); PG8_LDB(B1, 0, 1); PG8_SCHED; PG8_LDA(At, 0, 0); PG8_STAGE(PG8_SA(1, 1), a1 + hstepA, voffA);
;             PG8_WAIT_V(8); PG8_WAIT_L(0); PG8_BAR; PG8_MMA(0, 0, At, B0); PG8_MMA(0, 1, At, B1); PG8_BAR; PG8_SCHED;
;             PG8_LDA(At, 0, 1); PG8_STAGE_NT(PG8_SB(0, 0), b2, voffB); PG8_STAGE_NT(PG8_SB(0, 1), b2 + hstepB, voffB); PG8_STAGE(PG8_SA(0, 0), a2, voffA);
;             PG8_WAIT_V(8); PG8_WAIT_L(0); PG8_BAR; PG8_MMA(1, 0, At, B0); PG8_MMA(1, 1, At, B1); PG8_BAR; PG8_SCHED;
.LBB0_317:
	ds_read_b128 v[128:131], v205
	ds_read_b128 v[132:135], v205 offset:1024
	ds_read_b128 v[136:139], v205 offset:2048
	ds_read_b128 v[140:143], v205 offset:3072
	ds_read_b128 v[144:147], v206
	ds_read_b128 v[148:151], v206 offset:1024
	ds_read_b128 v[152:155], v206 offset:2048
	ds_read_b128 v[156:159], v206 offset:3072
	s_add_u32 s48, s46, 0x100
	s_addc_u32 s49, s47, 0
	s_add_u32 s98, s46, 0x80
	s_addc_u32 s99, s47, 0
	s_add_u32 s100, s46, 0x2b4080
	s_addc_u32 s101, s47, 0
	s_cmpk_eq_i32 s64, 0xa8
	s_cselect_b32 s53, s7, s49
	s_cselect_b32 s52, s6, s48
	s_cselect_b32 s51, s45, s63
	s_cselect_b32 s50, s44, s62
	s_add_i32 m0, s19, 0xc000
	ds_read_b128 v[160:163], v207
	ds_read_b128 v[164:167], v207 offset:1024
	ds_read_b128 v[184:187], v207 offset:2048
	ds_read_b128 v[188:191], v207 offset:3072
	ds_read_b128 v[192:195], v207 offset:4096
	ds_read_b128 v[196:199], v207 offset:5120
	ds_read_b128 v[210:213], v207 offset:6144
	ds_read_b128 v[214:217], v207 offset:7168
	global_load_lds_dwordx4 v168, s[100:101]
	s_add_i32 m0, s19, 0xe000
	s_nop 0
	global_load_lds_dwordx4 v172, s[100:101]
	s_mov_b32 m0, s29
	s_nop 0
	global_load_lds_dwordx4 v168, s[98:99]
	s_mov_b32 m0, s54
	s_nop 0
	global_load_lds_dwordx4 v172, s[98:99]
	s_nop 0
	s_waitcnt vmcnt(8)
	s_waitcnt lgkmcnt(0)
	s_barrier
	v_mfma_f32_16x16x32_bf16 v[124:127], v[128:131], v[160:163], v[124:127]
	v_mfma_f32_16x16x32_bf16 v[120:123], v[136:139], v[160:163], v[120:123]
	v_mfma_f32_16x16x32_bf16 v[116:119], v[128:131], v[184:187], v[116:119]
	v_mfma_f32_16x16x32_bf16 v[112:115], v[136:139], v[184:187], v[112:115]
	v_mfma_f32_16x16x32_bf16 v[92:95], v[128:131], v[192:195], v[92:95]
	v_mfma_f32_16x16x32_bf16 v[88:91], v[136:139], v[192:195], v[88:91]
	v_mfma_f32_16x16x32_bf16 v[76:79], v[128:131], v[210:213], v[76:79]
	v_mfma_f32_16x16x32_bf16 v[72:75], v[136:139], v[210:213], v[72:75]
	v_mfma_f32_16x16x32_bf16 v[124:127], v[132:135], v[164:167], v[124:127]
	v_mfma_f32_16x16x32_bf16 v[120:123], v[140:143], v[164:167], v[120:123]
	v_mfma_f32_16x16x32_bf16 v[116:119], v[132:135], v[188:191], v[116:119]
	v_mfma_f32_16x16x32_bf16 v[112:115], v[140:143], v[188:191], v[112:115]
	v_mfma_f32_16x16x32_bf16 v[92:95], v[132:135], v[196:199], v[92:95]
	v_mfma_f32_16x16x32_bf16 v[88:91], v[140:143], v[196:199], v[88:91]
	v_mfma_f32_16x16x32_bf16 v[76:79], v[132:135], v[214:217], v[76:79]
	v_mfma_f32_16x16x32_bf16 v[72:75], v[140:143], v[214:217], v[72:75]
	v_mfma_f32_16x16x32_bf16 v[108:111], v[144:147], v[160:163], v[108:111]
	v_mfma_f32_16x16x32_bf16 v[104:107], v[152:155], v[160:163], v[104:107]
	v_mfma_f32_16x16x32_bf16 v[100:103], v[144:147], v[184:187], v[100:103]
	v_mfma_f32_16x16x32_bf16 v[96:99], v[152:155], v[184:187], v[96:99]
	v_mfma_f32_16x16x32_bf16 v[84:87], v[144:147], v[192:195], v[84:87]
	v_mfma_f32_16x16x32_bf16 v[80:83], v[152:155], v[192:195], v[80:83]
	v_mfma_f32_16x16x32_bf16 v[68:71], v[144:147], v[210:213], v[68:71]
	v_mfma_f32_16x16x32_bf16 v[64:67], v[152:155], v[210:213], v[64:67]
	v_mfma_f32_16x16x32_bf16 v[108:111], v[148:151], v[164:167], v[108:111]
	v_mfma_f32_16x16x32_bf16 v[104:107], v[156:159], v[164:167], v[104:107]
	v_mfma_f32_16x16x32_bf16 v[100:103], v[148:151], v[188:191], v[100:103]
	v_mfma_f32_16x16x32_bf16 v[96:99], v[156:159], v[188:191], v[96:99]
	v_mfma_f32_16x16x32_bf16 v[84:87], v[148:151], v[196:199], v[84:87]
	v_mfma_f32_16x16x32_bf16 v[80:83], v[156:159], v[196:199], v[80:83]
	v_mfma_f32_16x16x32_bf16 v[68:71], v[148:151], v[214:217], v[68:71]
	v_mfma_f32_16x16x32_bf16 v[64:67], v[156:159], v[214:217], v[64:67]
	s_barrier
	s_add_i32 s46, s57, s17
	s_mov_b32 m0, s46
	ds_read_b128 v[160:163], v207 offset:16384
	ds_read_b128 v[164:167], v207 offset:17408
	ds_read_b128 v[184:187], v207 offset:18432
	ds_read_b128 v[188:191], v207 offset:19456
	ds_read_b128 v[192:195], v207 offset:20480
	ds_read_b128 v[196:199], v207 offset:21504
	ds_read_b128 v[210:213], v207 offset:22528
	ds_read_b128 v[214:217], v207 offset:23552
	global_load_lds_dwordx4 v170, s[50:51]
	s_add_i32 m0, s46, 0x2000
	s_add_u32 s46, s50, 0x2b4000
	s_addc_u32 s47, s51, 0
	s_add_i32 s65, s58, s17
	global_load_lds_dwordx4 v174, s[50:51]
	s_mov_b32 m0, s65
	s_nop 0
	global_load_lds_dwordx4 v170, s[46:47]
	s_add_i32 m0, s65, 0x2000
	s_nop 0
	global_load_lds_dwordx4 v174, s[46:47]
	s_nop 0
	s_waitcnt vmcnt(4)
	s_waitcnt lgkmcnt(0)
	s_barrier
	v_mfma_f32_16x16x32_bf16 v[60:63], v[128:131], v[160:163], v[60:63]
	v_mfma_f32_16x16x32_bf16 v[56:59], v[136:139], v[160:163], v[56:59]
	v_mfma_f32_16x16x32_bf16 v[44:47], v[128:131], v[184:187], v[44:47]
	v_mfma_f32_16x16x32_bf16 v[40:43], v[136:139], v[184:187], v[40:43]
	v_mfma_f32_16x16x32_bf16 v[28:31], v[128:131], v[192:195], v[28:31]
	v_mfma_f32_16x16x32_bf16 v[24:27], v[136:139], v[192:195], v[24:27]
	v_mfma_f32_16x16x32_bf16 v[12:15], v[128:131], v[210:213], v[12:15]
	v_mfma_f32_16x16x32_bf16 v[8:11], v[136:139], v[210:213], v[8:11]
	v_mfma_f32_16x16x32_bf16 v[60:63], v[132:135], v[164:167], v[60:63]
	v_mfma_f32_16x16x32_bf16 v[56:59], v[140:143], v[164:167], v[56:59]
	v_mfma_f32_16x16x32_bf16 v[44:47], v[132:135], v[188:191], v[44:47]
	v_mfma_f32_16x16x32_bf16 v[40:43], v[140:143], v[188:191], v[40:43]
	v_mfma_f32_16x16x32_bf16 v[28:31], v[132:135], v[196:199], v[28:31]
	v_mfma_f32_16x16x32_bf16 v[24:27], v[140:143], v[196:199], v[24:27]
	v_mfma_f32_16x16x32_bf16 v[12:15], v[132:135], v[214:217], v[12:15]
	v_mfma_f32_16x16x32_bf16 v[8:11], v[140:143], v[214:217], v[8:11]
	v_mfma_f32_16x16x32_bf16 v[52:55], v[144:147], v[160:163], v[52:55]
	v_mfma_f32_16x16x32_bf16 v[48:51], v[152:155], v[160:163], v[48:51]
	v_mfma_f32_16x16x32_bf16 v[36:39], v[144:147], v[184:187], v[36:39]
	v_mfma_f32_16x16x32_bf16 v[32:35], v[152:155], v[184:187], v[32:35]
	v_mfma_f32_16x16x32_bf16 v[20:23], v[144:147], v[192:195], v[20:23]
	v_mfma_f32_16x16x32_bf16 v[16:19], v[152:155], v[192:195], v[16:19]
	v_mfma_f32_16x16x32_bf16 v[4:7], v[144:147], v[210:213], v[4:7]
	v_mfma_f32_16x16x32_bf16 v[0:3], v[152:155], v[210:213], v[0:3]
	v_mfma_f32_16x16x32_bf16 v[52:55], v[148:151], v[164:167], v[52:55]
	v_mfma_f32_16x16x32_bf16 v[48:51], v[156:159], v[164:167], v[48:51]
	v_mfma_f32_16x16x32_bf16 v[36:39], v[148:151], v[188:191], v[36:39]
	v_mfma_f32_16x16x32_bf16 v[32:35], v[156:159], v[188:191], v[32:35]
	v_mfma_f32_16x16x32_bf16 v[20:23], v[148:151], v[196:199], v[20:23]
	v_mfma_f32_16x16x32_bf16 v[16:19], v[156:159], v[196:199], v[16:19]
	v_mfma_f32_16x16x32_bf16 v[4:7], v[148:151], v[214:217], v[4:7]
	v_mfma_f32_16x16x32_bf16 v[0:3], v[156:159], v[214:217], v[0:3]
	s_barrier
; #define PG8_STAGE(bufoff, gbase, voff) do { _Pragma("unroll") for (int _i = 0; _i < 2; ++_i) \
;         __builtin_amdgcn_global_load_lds((const unsigned*)((const char*)(gbase) + (voff)[_i]), (PG8_LAS unsigned*)(lds + (bufoff) + ldsw + _i * 8192), 16, 0, 0); } while (0)
; #define PG8_STAGE_NT(bufoff, gbase, voff) do { _Pragma("unroll") for (int _i = 0; _i < 2; ++_i) \
;         __builtin_amdgcn_global_load_lds((const unsigned*)((const char*)(gbase) + (voff)[_i]), (PG8_LAS unsigned*)(lds + (bufoff) + ldsw + _i * 8192), 16, 0, PG8_B_AUX); } while (0)
; #define PG8_LDA(dst, b, h) do { _Pragma("unroll") for (int m = 0; m < 4; ++m) _Pragma("unroll") for (int k = 0; k < 2; ++k) dst[m][k] = *(const PG8_LAS bf16x8*)(lds + PG8_SA(b, h) + aoff + m * 2048 + k * 1024); } while (0)
; #define PG8_LDB(dst, b, h) do { _Pragma("unroll") for (int n = 0; n < 2; ++n) _Pragma("unroll") for (int k = 0; k < 2; ++k) dst[n][k] = *(const PG8_LAS bf16x8*)(lds + PG8_SB(b, h) + boff + n * 2048 + k * 1024); } while (0)
; #define PG8_MMA(ai, bj, At, Bt) do { __builtin_amdgcn_s_setprio(1); _Pragma("unroll") for (int m = 0; m < 4; ++m) _Pragma("unroll") for (int n = 0; n < 2; ++n) _Pragma("unroll") for (int k = 0; k < 2; ++k) \
;         acc[ai][bj][m][n] = __builtin_amdgcn_mfma_f32_16x16x32_bf16(Bt[n][k], At[m][k], acc[ai][bj][m][n], 0, 0, 0); __builtin_amdgcn_s_setprio(0); } while (0)
; #define PG8_WAIT_V(n) asm volatile("s_waitcnt vmcnt(" #n ")" ::: "memory")
; #define PG8_WAIT_L(n) asm volatile("s_waitcnt lgkmcnt(" #n ")" ::: "memory")
; #define PG8_BAR __builtin_amdgcn_s_barrier()
; template <class Epi, class Sched, bool ALIGN_EPI = false, bool SP2 = false>
; __device__ __forceinline__ void gemm_phase(PG8_LAS unsigned char* lds, const Gemm g, const Sched& S, const Epi& E, int wid) {
;     ...
;             PG8_LDB(B0, 1, 0); PG8_LDB(B1, 1, 1); PG8_SCHED; PG8_LDA(At, 1, 0); PG8_STAGE(PG8_SA(0, 1), a2 + hstepA, voffA);
;             PG8_WAIT_V(8); PG8_WAIT_L(0); PG8_BAR; PG8_MMA(0, 0, At, B0); PG8_MMA(0, 1, At, B1); PG8_BAR; PG8_SCHED;
;             PG8_LDA(At, 1, 1); PG8_STAGE_NT(PG8_SB(1, 0), b3, voffB); PG8_STAGE_NT(PG8_SB(1, 1), b3 + hstepB, voffB); PG8_STAGE(PG8_SA(1, 0), a3, voffA);
;             PG8_WAIT_V(8); PG8_WAIT_L(0); PG8_BAR; PG8_MMA(1, 0, At, B0); PG8_MMA(1, 1, At, B1); PG8_BAR; PG8_SCHED;
;     ...
;         if constexpr (ALIGN_EPI) { if (wr == 0) PG8_BAR; }
	s_add_i32 s65, 0, 0x18000
	v_add_u32_e32 v140, s65, v203
	s_add_i32 s66, 0, 0x1c000
	ds_read_b128 v[128:131], v140
	ds_read_b128 v[132:135], v140 offset:1024
	ds_read_b128 v[136:139], v140 offset:2048
	ds_read_b128 v[140:143], v140 offset:3072
	v_add_u32_e32 v156, s66, v203
	ds_read_b128 v[144:147], v156
	ds_read_b128 v[148:151], v156 offset:1024
	ds_read_b128 v[152:155], v156 offset:2048
	ds_read_b128 v[156:159], v156 offset:3072
	s_add_u32 s46, s52, 0x2b4000
	s_addc_u32 s47, s53, 0
	s_mov_b32 m0, s23
	ds_read_b128 v[160:163], v207 offset:32768
	ds_read_b128 v[164:167], v207 offset:33792
	ds_read_b128 v[184:187], v207 offset:34816
	ds_read_b128 v[188:191], v207 offset:35840
	ds_read_b128 v[192:195], v207 offset:36864
	ds_read_b128 v[196:199], v207 offset:37888
	ds_read_b128 v[210:213], v207 offset:38912
	ds_read_b128 v[214:217], v207 offset:39936
	global_load_lds_dwordx4 v168, s[46:47]
	s_mov_b32 m0, s24
	s_nop 0
	global_load_lds_dwordx4 v172, s[46:47]
	s_mov_b32 m0, s19
	s_nop 0
	global_load_lds_dwordx4 v168, s[52:53]
	s_mov_b32 m0, s22
	s_nop 0
	global_load_lds_dwordx4 v172, s[52:53]
	s_waitcnt vmcnt(8)
	s_waitcnt lgkmcnt(0)
	s_barrier
	v_mfma_f32_16x16x32_bf16 v[124:127], v[128:131], v[160:163], v[124:127]
	v_mfma_f32_16x16x32_bf16 v[120:123], v[136:139], v[160:163], v[120:123]
	v_mfma_f32_16x16x32_bf16 v[116:119], v[128:131], v[184:187], v[116:119]
	v_mfma_f32_16x16x32_bf16 v[112:115], v[136:139], v[184:187], v[112:115]
	v_mfma_f32_16x16x32_bf16 v[92:95], v[128:131], v[192:195], v[92:95]
	v_mfma_f32_16x16x32_bf16 v[88:91], v[136:139], v[192:195], v[88:91]
	v_mfma_f32_16x16x32_bf16 v[76:79], v[128:131], v[210:213], v[76:79]
	v_mfma_f32_16x16x32_bf16 v[72:75], v[136:139], v[210:213], v[72:75]
	v_mfma_f32_16x16x32_bf16 v[124:127], v[132:135], v[164:167], v[124:127]
	v_mfma_f32_16x16x32_bf16 v[120:123], v[140:143], v[164:167], v[120:123]
	v_mfma_f32_16x16x32_bf16 v[116:119], v[132:135], v[188:191], v[116:119]
	v_mfma_f32_16x16x32_bf16 v[112:115], v[140:143], v[188:191], v[112:115]
	v_mfma_f32_16x16x32_bf16 v[92:95], v[132:135], v[196:199], v[92:95]
	v_mfma_f32_16x16x32_bf16 v[88:91], v[140:143], v[196:199], v[88:91]
	v_mfma_f32_16x16x32_bf16 v[76:79], v[132:135], v[214:217], v[76:79]
	v_mfma_f32_16x16x32_bf16 v[72:75], v[140:143], v[214:217], v[72:75]
	v_mfma_f32_16x16x32_bf16 v[108:111], v[144:147], v[160:163], v[108:111]
	v_mfma_f32_16x16x32_bf16 v[104:107], v[152:155], v[160:163], v[104:107]
	v_mfma_f32_16x16x32_bf16 v[100:103], v[144:147], v[184:187], v[100:103]
	v_mfma_f32_16x16x32_bf16 v[96:99], v[152:155], v[184:187], v[96:99]
	v_mfma_f32_16x16x32_bf16 v[84:87], v[144:147], v[192:195], v[84:87]
	v_mfma_f32_16x16x32_bf16 v[80:83], v[152:155], v[192:195], v[80:83]
	v_mfma_f32_16x16x32_bf16 v[68:71], v[144:147], v[210:213], v[68:71]
	v_mfma_f32_16x16x32_bf16 v[64:67], v[152:155], v[210:213], v[64:67]
	v_mfma_f32_16x16x32_bf16 v[108:111], v[148:151], v[164:167], v[108:111]
	v_mfma_f32_16x16x32_bf16 v[104:107], v[156:159], v[164:167], v[104:107]
	v_mfma_f32_16x16x32_bf16 v[100:103], v[148:151], v[188:191], v[100:103]
	v_mfma_f32_16x16x32_bf16 v[96:99], v[156:159], v[188:191], v[96:99]
	v_mfma_f32_16x16x32_bf16 v[84:87], v[148:151], v[196:199], v[84:87]
	v_mfma_f32_16x16x32_bf16 v[80:83], v[156:159], v[196:199], v[80:83]
	v_mfma_f32_16x16x32_bf16 v[68:71], v[148:151], v[214:217], v[68:71]
	v_mfma_f32_16x16x32_bf16 v[64:67], v[156:159], v[214:217], v[64:67]
	s_barrier
	s_add_i32 s46, s65, s17
	s_mov_b32 m0, s46
	s_add_u32 s98, s50, 0x80
	s_addc_u32 s99, s51, 0
	ds_read_b128 v[160:163], v207 offset:49152
	ds_read_b128 v[164:167], v207 offset:50176
	ds_read_b128 v[184:187], v207 offset:51200
	ds_read_b128 v[188:191], v207 offset:52224
	ds_read_b128 v[192:195], v207 offset:53248
	ds_read_b128 v[196:199], v207 offset:54272
	ds_read_b128 v[210:213], v207 offset:55296
	ds_read_b128 v[214:217], v207 offset:56320
	global_load_lds_dwordx4 v170, s[98:99]
	s_add_i32 m0, s46, 0x2000
	s_add_u32 s46, s50, 0x2b4080
	s_addc_u32 s47, s51, 0
	s_add_i32 s50, s66, s17
	global_load_lds_dwordx4 v174, s[98:99]
	s_mov_b32 m0, s50
	s_nop 0
	global_load_lds_dwordx4 v170, s[46:47]
	s_add_i32 m0, s50, 0x2000
	s_nop 0
	global_load_lds_dwordx4 v174, s[46:47]
	s_waitcnt vmcnt(4)
	s_waitcnt lgkmcnt(0)
	s_barrier
	v_mfma_f32_16x16x32_bf16 v[60:63], v[128:131], v[160:163], v[60:63]
	v_mfma_f32_16x16x32_bf16 v[56:59], v[136:139], v[160:163], v[56:59]
	v_mfma_f32_16x16x32_bf16 v[44:47], v[128:131], v[184:187], v[44:47]
	v_mfma_f32_16x16x32_bf16 v[40:43], v[136:139], v[184:187], v[40:43]
	v_mfma_f32_16x16x32_bf16 v[28:31], v[128:131], v[192:195], v[28:31]
	v_mfma_f32_16x16x32_bf16 v[24:27], v[136:139], v[192:195], v[24:27]
	v_mfma_f32_16x16x32_bf16 v[12:15], v[128:131], v[210:213], v[12:15]
	v_mfma_f32_16x16x32_bf16 v[8:11], v[136:139], v[210:213], v[8:11]
	v_mfma_f32_16x16x32_bf16 v[60:63], v[132:135], v[164:167], v[60:63]
	v_mfma_f32_16x16x32_bf16 v[56:59], v[140:143], v[164:167], v[56:59]
	v_mfma_f32_16x16x32_bf16 v[44:47], v[132:135], v[188:191], v[44:47]
	v_mfma_f32_16x16x32_bf16 v[40:43], v[140:143], v[188:191], v[40:43]
	v_mfma_f32_16x16x32_bf16 v[28:31], v[132:135], v[196:199], v[28:31]
	v_mfma_f32_16x16x32_bf16 v[24:27], v[140:143], v[196:199], v[24:27]
	v_mfma_f32_16x16x32_bf16 v[12:15], v[132:135], v[214:217], v[12:15]
	v_mfma_f32_16x16x32_bf16 v[8:11], v[140:143], v[214:217], v[8:11]
	v_mfma_f32_16x16x32_bf16 v[52:55], v[144:147], v[160:163], v[52:55]
	v_mfma_f32_16x16x32_bf16 v[48:51], v[152:155], v[160:163], v[48:51]
	v_mfma_f32_16x16x32_bf16 v[36:39], v[144:147], v[184:187], v[36:39]
	v_mfma_f32_16x16x32_bf16 v[32:35], v[152:155], v[184:187], v[32:35]
	v_mfma_f32_16x16x32_bf16 v[20:23], v[144:147], v[192:195], v[20:23]
	v_mfma_f32_16x16x32_bf16 v[16:19], v[152:155], v[192:195], v[16:19]
	v_mfma_f32_16x16x32_bf16 v[4:7], v[144:147], v[210:213], v[4:7]
	v_mfma_f32_16x16x32_bf16 v[0:3], v[152:155], v[210:213], v[0:3]
	v_mfma_f32_16x16x32_bf16 v[52:55], v[148:151], v[164:167], v[52:55]
	v_mfma_f32_16x16x32_bf16 v[48:51], v[156:159], v[164:167], v[48:51]
	v_mfma_f32_16x16x32_bf16 v[36:39], v[148:151], v[188:191], v[36:39]
	v_mfma_f32_16x16x32_bf16 v[32:35], v[156:159], v[188:191], v[32:35]
	v_mfma_f32_16x16x32_bf16 v[20:23], v[148:151], v[196:199], v[20:23]
	v_mfma_f32_16x16x32_bf16 v[16:19], v[156:159], v[196:199], v[16:19]
	v_mfma_f32_16x16x32_bf16 v[4:7], v[148:151], v[214:217], v[4:7]
	v_mfma_f32_16x16x32_bf16 v[0:3], v[156:159], v[214:217], v[0:3]
	s_barrier
	s_add_i32 s64, s64, 2
	s_add_u32 s62, s62, 0x100
	s_addc_u32 s63, s63, 0
	s_cmpk_gt_u32 s64, 0xa9
	s_mov_b64 s[46:47], s[48:49]
	s_cbranch_scc0 .LBB0_317
	s_and_b64 vcc, exec, s[42:43]
	s_cbranch_vccz .LBB0_320
	s_barrier

; #define PG8_STAGE(bufoff, gbase, voff) do { _Pragma("unroll") for (int _i = 0; _i < 2; ++_i) \
;         __builtin_amdgcn_global_load_lds((const unsigned*)((const char*)(gbase) + (voff)[_i]), (PG8_LAS unsigned*)(lds + (bufoff) + ldsw + _i * 8192), 16, 0, 0); } while (0)
; #define PG8_STAGE_NT(bufoff, gbase, voff) do { _Pragma("unroll") for (int _i = 0; _i < 2; ++_i) \
;         __builtin_amdgcn_global_load_lds((const unsigned*)((const char*)(gbase) + (voff)[_i]), (PG8_LAS unsigned*)(lds + (bufoff) + ldsw + _i * 8192), 16, 0, PG8_B_AUX); } while (0)
; #define PG8_LDA(dst, b, h) do { _Pragma("unroll") for (int m = 0; m < 4; ++m) _Pragma("unroll") for (int k = 0; k < 2; ++k) dst[m][k] = *(const PG8_LAS bf16x8*)(lds + PG8_SA(b, h) + aoff + m * 2048 + k * 1024); } while (0)
; #define PG8_LDB(dst, b, h) do { _Pragma("unroll") for (int n = 0; n < 2; ++n) _Pragma("unroll") for (int k = 0; k < 2; ++k) dst[n][k] = *(const PG8_LAS bf16x8*)(lds + PG8_SB(b, h) + boff + n * 2048 + k * 1024); } while (0)
; #define PG8_WAIT_V(n) asm volatile("s_waitcnt vmcnt(" #n ")" ::: "memory")
; #define PG8_WAIT_L(n) asm volatile("s_waitcnt lgkmcnt(" #n ")" ::: "memory")
; #define PG8_BAR __builtin_amdgcn_s_barrier()
; #define PG8_SCHED __builtin_amdgcn_sched_barrier(0)
; template <class Epi, class Sched, bool ALIGN_EPI = false, bool SP2 = false>
; __device__ __forceinline__ void gemm_phase(PG8_LAS unsigned char* lds, const Gemm g, const Sched& S, const Epi& E, int wid) {
;     ...
;             const bool last = (t == nt - 2);
;             const char* a1 = cA + (size_t)(t + 1) * kstep;
;             const char* a2 = last ? nA : cA + (size_t)(t + 2) * kstep; const char* b2 = last ? nB : cB + (size_t)(t + 2) * kstep;
;             const char* a3 = a2 + kstep; const char* b3 = b2 + kstep;
;             if (last && has_next) S.a_ready(nxt);
;             if constexpr (SP2) {
;             PG8_LDB(B0, 0, 0); PG8_LDB(B1, 0, 1); PG8_SCHED; PG8_LDA(At, 0, 0); PG8_STAGE(PG8_SA(1, 1), a1 + hstepA, voffA);
;             PG8_WAIT_V(8); PG8_WAIT_L(0); PG8_BAR; PG8_MMA(0, 0, At, B0); PG8_MMA(0, 1, At, B1); PG8_BAR; PG8_SCHED;
;             PG8_LDA(At, 0, 1); PG8_STAGE_NT(PG8_SB(0, 0), b2, voffB); PG8_STAGE_NT(PG8_SB(0, 1), b2 + hstepB, voffB); PG8_STAGE(PG8_SA(0, 0), a2, voffA);
;             PG8_WAIT_V(8); PG8_WAIT_L(0); PG8_BAR; PG8_MMA(1, 0, At, B0); PG8_MMA(1, 1, At, B1); PG8_BAR; PG8_SCHED;
.LBB0_426:
	ds_read_b128 v[144:147], v161
	ds_read_b128 v[148:151], v161 offset:1024
	ds_read_b128 v[152:155], v161 offset:2048
	ds_read_b128 v[166:169], v161 offset:3072
	ds_read_b128 v[170:173], v162
	ds_read_b128 v[174:177], v162 offset:1024
	ds_read_b128 v[178:181], v162 offset:2048
	ds_read_b128 v[182:185], v162 offset:3072
	s_add_u32 s4, s46, 0x100
	s_addc_u32 s5, s47, 0
	s_add_u32 s98, s46, 0x80
	s_addc_u32 s99, s47, 0
	s_add_u32 s100, s46, 0x104080
	s_addc_u32 s101, s47, 0
	s_cmp_eq_u32 s64, 60
	s_cselect_b32 s51, s43, s5
	s_cselect_b32 s50, s42, s4
	s_cselect_b32 s49, s45, s63
	s_cselect_b32 s48, s44, s62
	s_add_i32 m0, s23, 0xc000
	ds_read_b128 v[186:189], v163
	ds_read_b128 v[190:193], v163 offset:1024
	ds_read_b128 v[194:197], v163 offset:2048
	ds_read_b128 v[198:201], v163 offset:3072
	ds_read_b128 v[202:205], v163 offset:4096
	ds_read_b128 v[206:209], v163 offset:5120
	ds_read_b128 v[210:213], v163 offset:6144
	ds_read_b128 v[214:217], v163 offset:7168
	global_load_lds_dwordx4 v134, s[100:101]
	s_add_i32 m0, s23, 0xe000
	s_nop 0
	global_load_lds_dwordx4 v130, s[100:101]
	s_mov_b32 m0, s53
	s_nop 0
	global_load_lds_dwordx4 v134, s[98:99]
	s_mov_b32 m0, s54
	s_nop 0
	global_load_lds_dwordx4 v130, s[98:99]
	s_nop 0
	s_waitcnt vmcnt(8)
	s_waitcnt lgkmcnt(0)
	s_barrier
	v_mfma_f32_16x16x32_bf16 v[124:127], v[144:147], v[186:189], v[124:127]
	v_mfma_f32_16x16x32_bf16 v[120:123], v[152:155], v[186:189], v[120:123]
	v_mfma_f32_16x16x32_bf16 v[116:119], v[144:147], v[194:197], v[116:119]
	v_mfma_f32_16x16x32_bf16 v[112:115], v[152:155], v[194:197], v[112:115]
	v_mfma_f32_16x16x32_bf16 v[92:95], v[144:147], v[202:205], v[92:95]
	v_mfma_f32_16x16x32_bf16 v[88:91], v[152:155], v[202:205], v[88:91]
	v_mfma_f32_16x16x32_bf16 v[76:79], v[144:147], v[210:213], v[76:79]
	v_mfma_f32_16x16x32_bf16 v[72:75], v[152:155], v[210:213], v[72:75]
	v_mfma_f32_16x16x32_bf16 v[124:127], v[148:151], v[190:193], v[124:127]
	v_mfma_f32_16x16x32_bf16 v[120:123], v[166:169], v[190:193], v[120:123]
	v_mfma_f32_16x16x32_bf16 v[116:119], v[148:151], v[198:201], v[116:119]
	v_mfma_f32_16x16x32_bf16 v[112:115], v[166:169], v[198:201], v[112:115]
	v_mfma_f32_16x16x32_bf16 v[92:95], v[148:151], v[206:209], v[92:95]
	v_mfma_f32_16x16x32_bf16 v[88:91], v[166:169], v[206:209], v[88:91]
	v_mfma_f32_16x16x32_bf16 v[76:79], v[148:151], v[214:217], v[76:79]
	v_mfma_f32_16x16x32_bf16 v[72:75], v[166:169], v[214:217], v[72:75]
	v_mfma_f32_16x16x32_bf16 v[108:111], v[170:173], v[186:189], v[108:111]
	v_mfma_f32_16x16x32_bf16 v[104:107], v[178:181], v[186:189], v[104:107]
	v_mfma_f32_16x16x32_bf16 v[100:103], v[170:173], v[194:197], v[100:103]
	v_mfma_f32_16x16x32_bf16 v[96:99], v[178:181], v[194:197], v[96:99]
	v_mfma_f32_16x16x32_bf16 v[84:87], v[170:173], v[202:205], v[84:87]
	v_mfma_f32_16x16x32_bf16 v[80:83], v[178:181], v[202:205], v[80:83]
	v_mfma_f32_16x16x32_bf16 v[68:71], v[170:173], v[210:213], v[68:71]
	v_mfma_f32_16x16x32_bf16 v[64:67], v[178:181], v[210:213], v[64:67]
	v_mfma_f32_16x16x32_bf16 v[108:111], v[174:177], v[190:193], v[108:111]
	v_mfma_f32_16x16x32_bf16 v[104:107], v[182:185], v[190:193], v[104:107]
	v_mfma_f32_16x16x32_bf16 v[100:103], v[174:177], v[198:201], v[100:103]
	v_mfma_f32_16x16x32_bf16 v[96:99], v[182:185], v[198:201], v[96:99]
	v_mfma_f32_16x16x32_bf16 v[84:87], v[174:177], v[206:209], v[84:87]
	v_mfma_f32_16x16x32_bf16 v[80:83], v[182:185], v[206:209], v[80:83]
	v_mfma_f32_16x16x32_bf16 v[68:71], v[174:177], v[214:217], v[68:71]
	v_mfma_f32_16x16x32_bf16 v[64:67], v[182:185], v[214:217], v[64:67]
	s_barrier
	s_add_i32 s46, s56, s17
	s_mov_b32 m0, s46
	ds_read_b128 v[186:189], v163 offset:16384
	ds_read_b128 v[190:193], v163 offset:17408
	ds_read_b128 v[194:197], v163 offset:18432
	ds_read_b128 v[198:201], v163 offset:19456
	ds_read_b128 v[202:205], v163 offset:20480
	ds_read_b128 v[206:209], v163 offset:21504
	ds_read_b128 v[210:213], v163 offset:22528
	ds_read_b128 v[214:217], v163 offset:23552
	global_load_lds_dwordx4 v132, s[48:49]
	s_add_i32 m0, s46, 0x2000
	s_add_u32 s46, s48, 0x104000
	s_addc_u32 s47, s49, 0
	s_add_i32 s65, s57, s17
	global_load_lds_dwordx4 v128, s[48:49]
	s_mov_b32 m0, s65
	s_nop 0
	global_load_lds_dwordx4 v132, s[46:47]
	s_add_i32 m0, s65, 0x2000
	s_nop 0
	global_load_lds_dwordx4 v128, s[46:47]
	s_nop 0
	s_waitcnt vmcnt(4)
	s_waitcnt lgkmcnt(0)
	s_barrier
	v_mfma_f32_16x16x32_bf16 v[60:63], v[144:147], v[186:189], v[60:63]
	v_mfma_f32_16x16x32_bf16 v[56:59], v[152:155], v[186:189], v[56:59]
	v_mfma_f32_16x16x32_bf16 v[44:47], v[144:147], v[194:197], v[44:47]
	v_mfma_f32_16x16x32_bf16 v[40:43], v[152:155], v[194:197], v[40:43]
	v_mfma_f32_16x16x32_bf16 v[28:31], v[144:147], v[202:205], v[28:31]
	v_mfma_f32_16x16x32_bf16 v[24:27], v[152:155], v[202:205], v[24:27]
	v_mfma_f32_16x16x32_bf16 v[12:15], v[144:147], v[210:213], v[12:15]
	v_mfma_f32_16x16x32_bf16 v[8:11], v[152:155], v[210:213], v[8:11]
	v_mfma_f32_16x16x32_bf16 v[60:63], v[148:151], v[190:193], v[60:63]
	v_mfma_f32_16x16x32_bf16 v[56:59], v[166:169], v[190:193], v[56:59]
	v_mfma_f32_16x16x32_bf16 v[44:47], v[148:151], v[198:201], v[44:47]
	v_mfma_f32_16x16x32_bf16 v[40:43], v[166:169], v[198:201], v[40:43]
	v_mfma_f32_16x16x32_bf16 v[28:31], v[148:151], v[206:209], v[28:31]
	v_mfma_f32_16x16x32_bf16 v[24:27], v[166:169], v[206:209], v[24:27]
	v_mfma_f32_16x16x32_bf16 v[12:15], v[148:151], v[214:217], v[12:15]
	v_mfma_f32_16x16x32_bf16 v[8:11], v[166:169], v[214:217], v[8:11]
	v_mfma_f32_16x16x32_bf16 v[52:55], v[170:173], v[186:189], v[52:55]
	v_mfma_f32_16x16x32_bf16 v[48:51], v[178:181], v[186:189], v[48:51]
	v_mfma_f32_16x16x32_bf16 v[36:39], v[170:173], v[194:197], v[36:39]
	v_mfma_f32_16x16x32_bf16 v[32:35], v[178:181], v[194:197], v[32:35]
	v_mfma_f32_16x16x32_bf16 v[20:23], v[170:173], v[202:205], v[20:23]
	v_mfma_f32_16x16x32_bf16 v[16:19], v[178:181], v[202:205], v[16:19]
	v_mfma_f32_16x16x32_bf16 v[4:7], v[170:173], v[210:213], v[4:7]
	v_mfma_f32_16x16x32_bf16 v[0:3], v[178:181], v[210:213], v[0:3]
	v_mfma_f32_16x16x32_bf16 v[52:55], v[174:177], v[190:193], v[52:55]
	v_mfma_f32_16x16x32_bf16 v[48:51], v[182:185], v[190:193], v[48:51]
	v_mfma_f32_16x16x32_bf16 v[36:39], v[174:177], v[198:201], v[36:39]
	v_mfma_f32_16x16x32_bf16 v[32:35], v[182:185], v[198:201], v[32:35]
	v_mfma_f32_16x16x32_bf16 v[20:23], v[174:177], v[206:209], v[20:23]
	v_mfma_f32_16x16x32_bf16 v[16:19], v[182:185], v[206:209], v[16:19]
	v_mfma_f32_16x16x32_bf16 v[4:7], v[174:177], v[214:217], v[4:7]
	v_mfma_f32_16x16x32_bf16 v[0:3], v[182:185], v[214:217], v[0:3]
	s_barrier
; #define PG8_STAGE(bufoff, gbase, voff) do { _Pragma("unroll") for (int _i = 0; _i < 2; ++_i) \
;         __builtin_amdgcn_global_load_lds((const unsigned*)((const char*)(gbase) + (voff)[_i]), (PG8_LAS unsigned*)(lds + (bufoff) + ldsw + _i * 8192), 16, 0, 0); } while (0)
; #define PG8_STAGE_NT(bufoff, gbase, voff) do { _Pragma("unroll") for (int _i = 0; _i < 2; ++_i) \
;         __builtin_amdgcn_global_load_lds((const unsigned*)((const char*)(gbase) + (voff)[_i]), (PG8_LAS unsigned*)(lds + (bufoff) + ldsw + _i * 8192), 16, 0, PG8_B_AUX); } while (0)
; #define PG8_LDA(dst, b, h) do { _Pragma("unroll") for (int m = 0; m < 4; ++m) _Pragma("unroll") for (int k = 0; k < 2; ++k) dst[m][k] = *(const PG8_LAS bf16x8*)(lds + PG8_SA(b, h) + aoff + m * 2048 + k * 1024); } while (0)
; #define PG8_LDB(dst, b, h) do { _Pragma("unroll") for (int n = 0; n < 2; ++n) _Pragma("unroll") for (int k = 0; k < 2; ++k) dst[n][k] = *(const PG8_LAS bf16x8*)(lds + PG8_SB(b, h) + boff + n * 2048 + k * 1024); } while (0)
; #define PG8_MMA(ai, bj, At, Bt) do { __builtin_amdgcn_s_setprio(1); _Pragma("unroll") for (int m = 0; m < 4; ++m) _Pragma("unroll") for (int n = 0; n < 2; ++n) _Pragma("unroll") for (int k = 0; k < 2; ++k) \
;         acc[ai][bj][m][n] = __builtin_amdgcn_mfma_f32_16x16x32_bf16(Bt[n][k], At[m][k], acc[ai][bj][m][n], 0, 0, 0); __builtin_amdgcn_s_setprio(0); } while (0)
; #define PG8_WAIT_V(n) asm volatile("s_waitcnt vmcnt(" #n ")" ::: "memory")
; #define PG8_WAIT_L(n) asm volatile("s_waitcnt lgkmcnt(" #n ")" ::: "memory")
; #define PG8_BAR __builtin_amdgcn_s_barrier()
; template <class Epi, class Sched, bool ALIGN_EPI = false, bool SP2 = false>
; __device__ __forceinline__ void gemm_phase(PG8_LAS unsigned char* lds, const Gemm g, const Sched& S, const Epi& E, int wid) {
;     ...
;             PG8_LDB(B0, 1, 0); PG8_LDB(B1, 1, 1); PG8_SCHED; PG8_LDA(At, 1, 0); PG8_STAGE(PG8_SA(0, 1), a2 + hstepA, voffA);
;             PG8_WAIT_V(8); PG8_WAIT_L(0); PG8_BAR; PG8_MMA(0, 0, At, B0); PG8_MMA(0, 1, At, B1); PG8_BAR; PG8_SCHED;
;             PG8_LDA(At, 1, 1); PG8_STAGE_NT(PG8_SB(1, 0), b3, voffB); PG8_STAGE_NT(PG8_SB(1, 1), b3 + hstepB, voffB); PG8_STAGE(PG8_SA(1, 0), a3, voffA);
;             PG8_WAIT_V(8); PG8_WAIT_L(0); PG8_BAR; PG8_MMA(1, 0, At, B0); PG8_MMA(1, 1, At, B1); PG8_BAR; PG8_SCHED;
;     ...
;         if constexpr (ALIGN_EPI) { if (wr == 0) PG8_BAR; }
	s_add_i32 s65, 0, 0x18000
	v_add_u32_e32 v165, s65, v159
	s_add_i32 s66, 0, 0x1c000
	ds_read_b128 v[144:147], v165
	ds_read_b128 v[148:151], v165 offset:1024
	ds_read_b128 v[152:155], v165 offset:2048
	ds_read_b128 v[166:169], v165 offset:3072
	v_add_u32_e32 v165, s66, v159
	ds_read_b128 v[170:173], v165
	ds_read_b128 v[174:177], v165 offset:1024
	ds_read_b128 v[178:181], v165 offset:2048
	ds_read_b128 v[182:185], v165 offset:3072
	s_add_u32 s46, s50, 0x104000
	s_addc_u32 s47, s51, 0
	s_mov_b32 m0, s25
	ds_read_b128 v[186:189], v163 offset:32768
	ds_read_b128 v[190:193], v163 offset:33792
	ds_read_b128 v[194:197], v163 offset:34816
	ds_read_b128 v[198:201], v163 offset:35840
	ds_read_b128 v[202:205], v163 offset:36864
	ds_read_b128 v[206:209], v163 offset:37888
	ds_read_b128 v[210:213], v163 offset:38912
	ds_read_b128 v[214:217], v163 offset:39936
	global_load_lds_dwordx4 v134, s[46:47]
	s_mov_b32 m0, s29
	s_nop 0
	global_load_lds_dwordx4 v130, s[46:47]
	s_mov_b32 m0, s23
	s_nop 0
	global_load_lds_dwordx4 v134, s[50:51]
	s_mov_b32 m0, s24
	s_nop 0
	global_load_lds_dwordx4 v130, s[50:51]
	s_waitcnt vmcnt(8)
	s_waitcnt lgkmcnt(0)
	s_barrier
	v_mfma_f32_16x16x32_bf16 v[124:127], v[144:147], v[186:189], v[124:127]
	v_mfma_f32_16x16x32_bf16 v[120:123], v[152:155], v[186:189], v[120:123]
	v_mfma_f32_16x16x32_bf16 v[116:119], v[144:147], v[194:197], v[116:119]
	v_mfma_f32_16x16x32_bf16 v[112:115], v[152:155], v[194:197], v[112:115]
	v_mfma_f32_16x16x32_bf16 v[92:95], v[144:147], v[202:205], v[92:95]
	v_mfma_f32_16x16x32_bf16 v[88:91], v[152:155], v[202:205], v[88:91]
	v_mfma_f32_16x16x32_bf16 v[76:79], v[144:147], v[210:213], v[76:79]
	v_mfma_f32_16x16x32_bf16 v[72:75], v[152:155], v[210:213], v[72:75]
	v_mfma_f32_16x16x32_bf16 v[124:127], v[148:151], v[190:193], v[124:127]
	v_mfma_f32_16x16x32_bf16 v[120:123], v[166:169], v[190:193], v[120:123]
	v_mfma_f32_16x16x32_bf16 v[116:119], v[148:151], v[198:201], v[116:119]
	v_mfma_f32_16x16x32_bf16 v[112:115], v[166:169], v[198:201], v[112:115]
	v_mfma_f32_16x16x32_bf16 v[92:95], v[148:151], v[206:209], v[92:95]
	v_mfma_f32_16x16x32_bf16 v[88:91], v[166:169], v[206:209], v[88:91]
	v_mfma_f32_16x16x32_bf16 v[76:79], v[148:151], v[214:217], v[76:79]
	v_mfma_f32_16x16x32_bf16 v[72:75], v[166:169], v[214:217], v[72:75]
	v_mfma_f32_16x16x32_bf16 v[108:111], v[170:173], v[186:189], v[108:111]
	v_mfma_f32_16x16x32_bf16 v[104:107], v[178:181], v[186:189], v[104:107]
	v_mfma_f32_16x16x32_bf16 v[100:103], v[170:173], v[194:197], v[100:103]
	v_mfma_f32_16x16x32_bf16 v[96:99], v[178:181], v[194:197], v[96:99]
	v_mfma_f32_16x16x32_bf16 v[84:87], v[170:173], v[202:205], v[84:87]
	v_mfma_f32_16x16x32_bf16 v[80:83], v[178:181], v[202:205], v[80:83]
	v_mfma_f32_16x16x32_bf16 v[68:71], v[170:173], v[210:213], v[68:71]
	v_mfma_f32_16x16x32_bf16 v[64:67], v[178:181], v[210:213], v[64:67]
	v_mfma_f32_16x16x32_bf16 v[108:111], v[174:177], v[190:193], v[108:111]
	v_mfma_f32_16x16x32_bf16 v[104:107], v[182:185], v[190:193], v[104:107]
	v_mfma_f32_16x16x32_bf16 v[100:103], v[174:177], v[198:201], v[100:103]
	v_mfma_f32_16x16x32_bf16 v[96:99], v[182:185], v[198:201], v[96:99]
	v_mfma_f32_16x16x32_bf16 v[84:87], v[174:177], v[206:209], v[84:87]
	v_mfma_f32_16x16x32_bf16 v[80:83], v[182:185], v[206:209], v[80:83]
	v_mfma_f32_16x16x32_bf16 v[68:71], v[174:177], v[214:217], v[68:71]
	v_mfma_f32_16x16x32_bf16 v[64:67], v[182:185], v[214:217], v[64:67]
	s_barrier
	s_add_i32 s46, s65, s17
	s_mov_b32 m0, s46
	s_add_u32 s98, s48, 0x80
	s_addc_u32 s99, s49, 0
	ds_read_b128 v[186:189], v163 offset:49152
	ds_read_b128 v[190:193], v163 offset:50176
	ds_read_b128 v[194:197], v163 offset:51200
	ds_read_b128 v[198:201], v163 offset:52224
	ds_read_b128 v[202:205], v163 offset:53248
	ds_read_b128 v[206:209], v163 offset:54272
	ds_read_b128 v[210:213], v163 offset:55296
	ds_read_b128 v[214:217], v163 offset:56320
	global_load_lds_dwordx4 v132, s[98:99]
	s_add_i32 m0, s46, 0x2000
	s_add_u32 s46, s48, 0x104080
	s_addc_u32 s47, s49, 0
	s_add_i32 s48, s66, s17
	global_load_lds_dwordx4 v128, s[98:99]
	s_mov_b32 m0, s48
	s_nop 0
	global_load_lds_dwordx4 v132, s[46:47]
	s_add_i32 m0, s48, 0x2000
	s_nop 0
	global_load_lds_dwordx4 v128, s[46:47]
	s_waitcnt vmcnt(4)
	s_waitcnt lgkmcnt(0)
	s_barrier
	v_mfma_f32_16x16x32_bf16 v[60:63], v[144:147], v[186:189], v[60:63]
	v_mfma_f32_16x16x32_bf16 v[56:59], v[152:155], v[186:189], v[56:59]
	v_mfma_f32_16x16x32_bf16 v[44:47], v[144:147], v[194:197], v[44:47]
	v_mfma_f32_16x16x32_bf16 v[40:43], v[152:155], v[194:197], v[40:43]
	v_mfma_f32_16x16x32_bf16 v[28:31], v[144:147], v[202:205], v[28:31]
	v_mfma_f32_16x16x32_bf16 v[24:27], v[152:155], v[202:205], v[24:27]
	v_mfma_f32_16x16x32_bf16 v[12:15], v[144:147], v[210:213], v[12:15]
	v_mfma_f32_16x16x32_bf16 v[8:11], v[152:155], v[210:213], v[8:11]
	v_mfma_f32_16x16x32_bf16 v[60:63], v[148:151], v[190:193], v[60:63]
	v_mfma_f32_16x16x32_bf16 v[56:59], v[166:169], v[190:193], v[56:59]
	v_mfma_f32_16x16x32_bf16 v[44:47], v[148:151], v[198:201], v[44:47]
	v_mfma_f32_16x16x32_bf16 v[40:43], v[166:169], v[198:201], v[40:43]
	v_mfma_f32_16x16x32_bf16 v[28:31], v[148:151], v[206:209], v[28:31]
	v_mfma_f32_16x16x32_bf16 v[24:27], v[166:169], v[206:209], v[24:27]
	v_mfma_f32_16x16x32_bf16 v[12:15], v[148:151], v[214:217], v[12:15]
	v_mfma_f32_16x16x32_bf16 v[8:11], v[166:169], v[214:217], v[8:11]
	v_mfma_f32_16x16x32_bf16 v[52:55], v[170:173], v[186:189], v[52:55]
	v_mfma_f32_16x16x32_bf16 v[48:51], v[178:181], v[186:189], v[48:51]
	v_mfma_f32_16x16x32_bf16 v[36:39], v[170:173], v[194:197], v[36:39]
	v_mfma_f32_16x16x32_bf16 v[32:35], v[178:181], v[194:197], v[32:35]
	v_mfma_f32_16x16x32_bf16 v[20:23], v[170:173], v[202:205], v[20:23]
	v_mfma_f32_16x16x32_bf16 v[16:19], v[178:181], v[202:205], v[16:19]
	v_mfma_f32_16x16x32_bf16 v[4:7], v[170:173], v[210:213], v[4:7]
	v_mfma_f32_16x16x32_bf16 v[0:3], v[178:181], v[210:213], v[0:3]
	v_mfma_f32_16x16x32_bf16 v[52:55], v[174:177], v[190:193], v[52:55]
	v_mfma_f32_16x16x32_bf16 v[48:51], v[182:185], v[190:193], v[48:51]
	v_mfma_f32_16x16x32_bf16 v[36:39], v[174:177], v[198:201], v[36:39]
	v_mfma_f32_16x16x32_bf16 v[32:35], v[182:185], v[198:201], v[32:35]
	v_mfma_f32_16x16x32_bf16 v[20:23], v[174:177], v[206:209], v[20:23]
	v_mfma_f32_16x16x32_bf16 v[16:19], v[182:185], v[206:209], v[16:19]
	v_mfma_f32_16x16x32_bf16 v[4:7], v[174:177], v[214:217], v[4:7]
	v_mfma_f32_16x16x32_bf16 v[0:3], v[182:185], v[214:217], v[0:3]
	s_barrier
	s_add_i32 s64, s64, 2
	s_add_u32 s62, s62, 0x100
	s_addc_u32 s63, s63, 0
	s_cmp_gt_u32 s64, 61
	s_mov_b64 s[46:47], s[4:5]
	s_cbranch_scc0 .LBB0_426
	s_and_b64 vcc, exec, s[40:41]
	s_cbranch_vccz .LBB0_429
	s_barrier

; #define PG8_STAGE(bufoff, gbase, voff) do { _Pragma("unroll") for (int _i = 0; _i < 2; ++_i) \
;         __builtin_amdgcn_global_load_lds((const unsigned*)((const char*)(gbase) + (voff)[_i]), (PG8_LAS unsigned*)(lds + (bufoff) + ldsw + _i * 8192), 16, 0, 0); } while (0)
; #define PG8_STAGE_NT(bufoff, gbase, voff) do { _Pragma("unroll") for (int _i = 0; _i < 2; ++_i) \
;         __builtin_amdgcn_global_load_lds((const unsigned*)((const char*)(gbase) + (voff)[_i]), (PG8_LAS unsigned*)(lds + (bufoff) + ldsw + _i * 8192), 16, 0, PG8_B_AUX); } while (0)
; #define PG8_LDA(dst, b, h) do { _Pragma("unroll") for (int m = 0; m < 4; ++m) _Pragma("unroll") for (int k = 0; k < 2; ++k) dst[m][k] = *(const PG8_LAS bf16x8*)(lds + PG8_SA(b, h) + aoff + m * 2048 + k * 1024); } while (0)
; #define PG8_LDB(dst, b, h) do { _Pragma("unroll") for (int n = 0; n < 2; ++n) _Pragma("unroll") for (int k = 0; k < 2; ++k) dst[n][k] = *(const PG8_LAS bf16x8*)(lds + PG8_SB(b, h) + boff + n * 2048 + k * 1024); } while (0)
; #define PG8_WAIT_V(n) asm volatile("s_waitcnt vmcnt(" #n ")" ::: "memory")
; #define PG8_WAIT_L(n) asm volatile("s_waitcnt lgkmcnt(" #n ")" ::: "memory")
; #define PG8_BAR __builtin_amdgcn_s_barrier()
; #define PG8_SCHED __builtin_amdgcn_sched_barrier(0)
; template <class Epi, class Sched, bool ALIGN_EPI = false, bool SP2 = false>
; __device__ __forceinline__ void gemm_phase(PG8_LAS unsigned char* lds, const Gemm g, const Sched& S, const Epi& E, int wid) {
;     ...
;             const bool last = (t == nt - 2);
;             const char* a1 = cA + (size_t)(t + 1) * kstep;
;             const char* a2 = last ? nA : cA + (size_t)(t + 2) * kstep; const char* b2 = last ? nB : cB + (size_t)(t + 2) * kstep;
;             const char* a3 = a2 + kstep; const char* b3 = b2 + kstep;
;             if (last && has_next) S.a_ready(nxt);
;             if constexpr (SP2) {
;             PG8_LDB(B0, 0, 0); PG8_LDB(B1, 0, 1); PG8_SCHED; PG8_LDA(At, 0, 0); PG8_STAGE(PG8_SA(1, 1), a1 + hstepA, voffA);
;             PG8_WAIT_V(8); PG8_WAIT_L(0); PG8_BAR; PG8_MMA(0, 0, At, B0); PG8_MMA(0, 1, At, B1); PG8_BAR; PG8_SCHED;
;             PG8_LDA(At, 0, 1); PG8_STAGE_NT(PG8_SB(0, 0), b2, voffB); PG8_STAGE_NT(PG8_SB(0, 1), b2 + hstepB, voffB); PG8_STAGE(PG8_SA(0, 0), a2, voffA);
;             PG8_WAIT_V(8); PG8_WAIT_L(0); PG8_BAR; PG8_MMA(1, 0, At, B0); PG8_MMA(1, 1, At, B1); PG8_BAR; PG8_SCHED;
.LBB0_1037:
	ds_read_b128 v[104:107], v221
	ds_read_b128 v[116:119], v221 offset:1024
	ds_read_b128 v[128:131], v221 offset:2048
	ds_read_b128 v[140:143], v221 offset:3072
	ds_read_b128 v[144:147], v222
	ds_read_b128 v[148:151], v222 offset:1024
	ds_read_b128 v[152:155], v222 offset:2048
	ds_read_b128 v[156:159], v222 offset:3072
	s_add_u32 s52, s50, 0x100
	s_addc_u32 s53, s51, 0
	s_add_u32 s98, s50, 0x80
	s_addc_u32 s99, s51, 0
	s_add_u32 s100, s50, 0x104080
	s_addc_u32 s101, s51, 0
	s_cmp_eq_u32 s67, 60
	s_cselect_b32 s57, s7, s53
	s_cselect_b32 s56, s6, s52
	s_cselect_b32 s55, s49, s66
	s_cselect_b32 s54, s48, s65
	s_add_i32 m0, s17, 0xc000
	ds_read_b128 v[160:163], v223
	ds_read_b128 v[164:167], v223 offset:1024
	ds_read_b128 v[168:171], v223 offset:2048
	ds_read_b128 v[172:175], v223 offset:3072
	ds_read_b128 v[176:179], v223 offset:4096
	ds_read_b128 v[180:183], v223 offset:5120
	ds_read_b128 v[200:203], v223 offset:6144
	ds_read_b128 v[204:207], v223 offset:7168
	global_load_lds_dwordx4 v184, s[100:101]
	s_add_i32 m0, s17, 0xe000
	s_nop 0
	global_load_lds_dwordx4 v188, s[100:101]
	s_mov_b32 m0, s25
	s_nop 0
	global_load_lds_dwordx4 v184, s[98:99]
	s_mov_b32 m0, s29
	s_nop 0
	global_load_lds_dwordx4 v188, s[98:99]
	s_nop 0
	s_waitcnt vmcnt(8)
	s_waitcnt lgkmcnt(0)
	s_barrier
	v_mfma_f32_16x16x32_bf16 v[136:139], v[104:107], v[160:163], v[136:139]
	v_mfma_f32_16x16x32_bf16 v[132:135], v[128:131], v[160:163], v[132:135]
	v_mfma_f32_16x16x32_bf16 v[112:115], v[104:107], v[168:171], v[112:115]
	v_mfma_f32_16x16x32_bf16 v[108:111], v[128:131], v[168:171], v[108:111]
	v_mfma_f32_16x16x32_bf16 v[92:95], v[104:107], v[176:179], v[92:95]
	v_mfma_f32_16x16x32_bf16 v[88:91], v[128:131], v[176:179], v[88:91]
	v_mfma_f32_16x16x32_bf16 v[76:79], v[104:107], v[200:203], v[76:79]
	v_mfma_f32_16x16x32_bf16 v[72:75], v[128:131], v[200:203], v[72:75]
	v_mfma_f32_16x16x32_bf16 v[136:139], v[116:119], v[164:167], v[136:139]
	v_mfma_f32_16x16x32_bf16 v[132:135], v[140:143], v[164:167], v[132:135]
	v_mfma_f32_16x16x32_bf16 v[112:115], v[116:119], v[172:175], v[112:115]
	v_mfma_f32_16x16x32_bf16 v[108:111], v[140:143], v[172:175], v[108:111]
	v_mfma_f32_16x16x32_bf16 v[92:95], v[116:119], v[180:183], v[92:95]
	v_mfma_f32_16x16x32_bf16 v[88:91], v[140:143], v[180:183], v[88:91]
	v_mfma_f32_16x16x32_bf16 v[76:79], v[116:119], v[204:207], v[76:79]
	v_mfma_f32_16x16x32_bf16 v[72:75], v[140:143], v[204:207], v[72:75]
	v_mfma_f32_16x16x32_bf16 v[124:127], v[144:147], v[160:163], v[124:127]
	v_mfma_f32_16x16x32_bf16 v[120:123], v[152:155], v[160:163], v[120:123]
	v_mfma_f32_16x16x32_bf16 v[100:103], v[144:147], v[168:171], v[100:103]
	v_mfma_f32_16x16x32_bf16 v[96:99], v[152:155], v[168:171], v[96:99]
	v_mfma_f32_16x16x32_bf16 v[84:87], v[144:147], v[176:179], v[84:87]
	v_mfma_f32_16x16x32_bf16 v[80:83], v[152:155], v[176:179], v[80:83]
	v_mfma_f32_16x16x32_bf16 v[68:71], v[144:147], v[200:203], v[68:71]
	v_mfma_f32_16x16x32_bf16 v[64:67], v[152:155], v[200:203], v[64:67]
	v_mfma_f32_16x16x32_bf16 v[124:127], v[148:151], v[164:167], v[124:127]
	v_mfma_f32_16x16x32_bf16 v[120:123], v[156:159], v[164:167], v[120:123]
	v_mfma_f32_16x16x32_bf16 v[100:103], v[148:151], v[172:175], v[100:103]
	v_mfma_f32_16x16x32_bf16 v[96:99], v[156:159], v[172:175], v[96:99]
	v_mfma_f32_16x16x32_bf16 v[84:87], v[148:151], v[180:183], v[84:87]
	v_mfma_f32_16x16x32_bf16 v[80:83], v[156:159], v[180:183], v[80:83]
	v_mfma_f32_16x16x32_bf16 v[68:71], v[148:151], v[204:207], v[68:71]
	v_mfma_f32_16x16x32_bf16 v[64:67], v[156:159], v[204:207], v[64:67]
	s_barrier
	s_add_i32 s50, s60, s9
	s_mov_b32 m0, s50
	ds_read_b128 v[160:163], v223 offset:16384
	ds_read_b128 v[164:167], v223 offset:17408
	ds_read_b128 v[168:171], v223 offset:18432
	ds_read_b128 v[172:175], v223 offset:19456
	ds_read_b128 v[176:179], v223 offset:20480
	ds_read_b128 v[180:183], v223 offset:21504
	ds_read_b128 v[200:203], v223 offset:22528
	ds_read_b128 v[204:207], v223 offset:23552
	global_load_lds_dwordx4 v186, s[54:55]
	s_add_i32 m0, s50, 0x2000
	s_add_u32 s50, s54, 0x104000
	s_addc_u32 s51, s55, 0
	s_add_i32 s68, s61, s9
	global_load_lds_dwordx4 v190, s[54:55]
	s_mov_b32 m0, s68
	s_nop 0
	global_load_lds_dwordx4 v186, s[50:51]
	s_add_i32 m0, s68, 0x2000
	s_nop 0
	global_load_lds_dwordx4 v190, s[50:51]
	s_nop 0
	s_waitcnt vmcnt(4)
	s_waitcnt lgkmcnt(0)
	s_barrier
	v_mfma_f32_16x16x32_bf16 v[60:63], v[104:107], v[160:163], v[60:63]
	v_mfma_f32_16x16x32_bf16 v[56:59], v[128:131], v[160:163], v[56:59]
	v_mfma_f32_16x16x32_bf16 v[44:47], v[104:107], v[168:171], v[44:47]
	v_mfma_f32_16x16x32_bf16 v[40:43], v[128:131], v[168:171], v[40:43]
	v_mfma_f32_16x16x32_bf16 v[28:31], v[104:107], v[176:179], v[28:31]
	v_mfma_f32_16x16x32_bf16 v[24:27], v[128:131], v[176:179], v[24:27]
	v_mfma_f32_16x16x32_bf16 v[12:15], v[104:107], v[200:203], v[12:15]
	v_mfma_f32_16x16x32_bf16 v[8:11], v[128:131], v[200:203], v[8:11]
	v_mfma_f32_16x16x32_bf16 v[60:63], v[116:119], v[164:167], v[60:63]
	v_mfma_f32_16x16x32_bf16 v[56:59], v[140:143], v[164:167], v[56:59]
	v_mfma_f32_16x16x32_bf16 v[44:47], v[116:119], v[172:175], v[44:47]
	v_mfma_f32_16x16x32_bf16 v[40:43], v[140:143], v[172:175], v[40:43]
	v_mfma_f32_16x16x32_bf16 v[28:31], v[116:119], v[180:183], v[28:31]
	v_mfma_f32_16x16x32_bf16 v[24:27], v[140:143], v[180:183], v[24:27]
	v_mfma_f32_16x16x32_bf16 v[12:15], v[116:119], v[204:207], v[12:15]
	v_mfma_f32_16x16x32_bf16 v[8:11], v[140:143], v[204:207], v[8:11]
	v_mfma_f32_16x16x32_bf16 v[52:55], v[144:147], v[160:163], v[52:55]
	v_mfma_f32_16x16x32_bf16 v[48:51], v[152:155], v[160:163], v[48:51]
	v_mfma_f32_16x16x32_bf16 v[36:39], v[144:147], v[168:171], v[36:39]
	v_mfma_f32_16x16x32_bf16 v[32:35], v[152:155], v[168:171], v[32:35]
	v_mfma_f32_16x16x32_bf16 v[20:23], v[144:147], v[176:179], v[20:23]
	v_mfma_f32_16x16x32_bf16 v[16:19], v[152:155], v[176:179], v[16:19]
	v_mfma_f32_16x16x32_bf16 v[4:7], v[144:147], v[200:203], v[4:7]
	v_mfma_f32_16x16x32_bf16 v[0:3], v[152:155], v[200:203], v[0:3]
	v_mfma_f32_16x16x32_bf16 v[52:55], v[148:151], v[164:167], v[52:55]
	v_mfma_f32_16x16x32_bf16 v[48:51], v[156:159], v[164:167], v[48:51]
	v_mfma_f32_16x16x32_bf16 v[36:39], v[148:151], v[172:175], v[36:39]
	v_mfma_f32_16x16x32_bf16 v[32:35], v[156:159], v[172:175], v[32:35]
	v_mfma_f32_16x16x32_bf16 v[20:23], v[148:151], v[180:183], v[20:23]
	v_mfma_f32_16x16x32_bf16 v[16:19], v[156:159], v[180:183], v[16:19]
	v_mfma_f32_16x16x32_bf16 v[4:7], v[148:151], v[204:207], v[4:7]
	v_mfma_f32_16x16x32_bf16 v[0:3], v[156:159], v[204:207], v[0:3]
	s_barrier
; #define PG8_STAGE(bufoff, gbase, voff) do { _Pragma("unroll") for (int _i = 0; _i < 2; ++_i) \
;         __builtin_amdgcn_global_load_lds((const unsigned*)((const char*)(gbase) + (voff)[_i]), (PG8_LAS unsigned*)(lds + (bufoff) + ldsw + _i * 8192), 16, 0, 0); } while (0)
; #define PG8_STAGE_NT(bufoff, gbase, voff) do { _Pragma("unroll") for (int _i = 0; _i < 2; ++_i) \
;         __builtin_amdgcn_global_load_lds((const unsigned*)((const char*)(gbase) + (voff)[_i]), (PG8_LAS unsigned*)(lds + (bufoff) + ldsw + _i * 8192), 16, 0, PG8_B_AUX); } while (0)
; #define PG8_LDA(dst, b, h) do { _Pragma("unroll") for (int m = 0; m < 4; ++m) _Pragma("unroll") for (int k = 0; k < 2; ++k) dst[m][k] = *(const PG8_LAS bf16x8*)(lds + PG8_SA(b, h) + aoff + m * 2048 + k * 1024); } while (0)
; #define PG8_LDB(dst, b, h) do { _Pragma("unroll") for (int n = 0; n < 2; ++n) _Pragma("unroll") for (int k = 0; k < 2; ++k) dst[n][k] = *(const PG8_LAS bf16x8*)(lds + PG8_SB(b, h) + boff + n * 2048 + k * 1024); } while (0)
; #define PG8_MMA(ai, bj, At, Bt) do { __builtin_amdgcn_s_setprio(1); _Pragma("unroll") for (int m = 0; m < 4; ++m) _Pragma("unroll") for (int n = 0; n < 2; ++n) _Pragma("unroll") for (int k = 0; k < 2; ++k) \
;         acc[ai][bj][m][n] = __builtin_amdgcn_mfma_f32_16x16x32_bf16(Bt[n][k], At[m][k], acc[ai][bj][m][n], 0, 0, 0); __builtin_amdgcn_s_setprio(0); } while (0)
; #define PG8_WAIT_V(n) asm volatile("s_waitcnt vmcnt(" #n ")" ::: "memory")
; #define PG8_WAIT_L(n) asm volatile("s_waitcnt lgkmcnt(" #n ")" ::: "memory")
; #define PG8_BAR __builtin_amdgcn_s_barrier()
; template <class Epi, class Sched, bool ALIGN_EPI = false, bool SP2 = false>
; __device__ __forceinline__ void gemm_phase(PG8_LAS unsigned char* lds, const Gemm g, const Sched& S, const Epi& E, int wid) {
;     ...
;             PG8_LDB(B0, 1, 0); PG8_LDB(B1, 1, 1); PG8_SCHED; PG8_LDA(At, 1, 0); PG8_STAGE(PG8_SA(0, 1), a2 + hstepA, voffA);
;             PG8_WAIT_V(8); PG8_WAIT_L(0); PG8_BAR; PG8_MMA(0, 0, At, B0); PG8_MMA(0, 1, At, B1); PG8_BAR; PG8_SCHED;
;             PG8_LDA(At, 1, 1); PG8_STAGE_NT(PG8_SB(1, 0), b3, voffB); PG8_STAGE_NT(PG8_SB(1, 1), b3 + hstepB, voffB); PG8_STAGE(PG8_SA(1, 0), a3, voffA);
;             PG8_WAIT_V(8); PG8_WAIT_L(0); PG8_BAR; PG8_MMA(1, 0, At, B0); PG8_MMA(1, 1, At, B1); PG8_BAR; PG8_SCHED;
;     ...
;         if constexpr (ALIGN_EPI) { if (wr == 0) PG8_BAR; }
	s_add_i32 s68, 0, 0x18000
	v_add_u32_e32 v140, s68, v219
	s_add_i32 s69, 0, 0x1c000
	ds_read_b128 v[104:107], v140
	ds_read_b128 v[116:119], v140 offset:1024
	ds_read_b128 v[128:131], v140 offset:2048
	ds_read_b128 v[140:143], v140 offset:3072
	v_add_u32_e32 v156, s69, v219
	ds_read_b128 v[144:147], v156
	ds_read_b128 v[148:151], v156 offset:1024
	ds_read_b128 v[152:155], v156 offset:2048
	ds_read_b128 v[156:159], v156 offset:3072
	s_add_u32 s50, s56, 0x104000
	s_addc_u32 s51, s57, 0
	s_mov_b32 m0, s22
	ds_read_b128 v[160:163], v223 offset:32768
	ds_read_b128 v[164:167], v223 offset:33792
	ds_read_b128 v[168:171], v223 offset:34816
	ds_read_b128 v[172:175], v223 offset:35840
	ds_read_b128 v[176:179], v223 offset:36864
	ds_read_b128 v[180:183], v223 offset:37888
	ds_read_b128 v[200:203], v223 offset:38912
	ds_read_b128 v[204:207], v223 offset:39936
	global_load_lds_dwordx4 v184, s[50:51]
	s_mov_b32 m0, s23
	s_nop 0
	global_load_lds_dwordx4 v188, s[50:51]
	s_mov_b32 m0, s17
	s_nop 0
	global_load_lds_dwordx4 v184, s[56:57]
	s_mov_b32 m0, s19
	s_nop 0
	global_load_lds_dwordx4 v188, s[56:57]
	s_waitcnt vmcnt(8)
	s_waitcnt lgkmcnt(0)
	s_barrier
	v_mfma_f32_16x16x32_bf16 v[136:139], v[104:107], v[160:163], v[136:139]
	v_mfma_f32_16x16x32_bf16 v[132:135], v[128:131], v[160:163], v[132:135]
	v_mfma_f32_16x16x32_bf16 v[112:115], v[104:107], v[168:171], v[112:115]
	v_mfma_f32_16x16x32_bf16 v[108:111], v[128:131], v[168:171], v[108:111]
	v_mfma_f32_16x16x32_bf16 v[92:95], v[104:107], v[176:179], v[92:95]
	v_mfma_f32_16x16x32_bf16 v[88:91], v[128:131], v[176:179], v[88:91]
	v_mfma_f32_16x16x32_bf16 v[76:79], v[104:107], v[200:203], v[76:79]
	v_mfma_f32_16x16x32_bf16 v[72:75], v[128:131], v[200:203], v[72:75]
	v_mfma_f32_16x16x32_bf16 v[136:139], v[116:119], v[164:167], v[136:139]
	v_mfma_f32_16x16x32_bf16 v[132:135], v[140:143], v[164:167], v[132:135]
	v_mfma_f32_16x16x32_bf16 v[112:115], v[116:119], v[172:175], v[112:115]
	v_mfma_f32_16x16x32_bf16 v[108:111], v[140:143], v[172:175], v[108:111]
	v_mfma_f32_16x16x32_bf16 v[92:95], v[116:119], v[180:183], v[92:95]
	v_mfma_f32_16x16x32_bf16 v[88:91], v[140:143], v[180:183], v[88:91]
	v_mfma_f32_16x16x32_bf16 v[76:79], v[116:119], v[204:207], v[76:79]
	v_mfma_f32_16x16x32_bf16 v[72:75], v[140:143], v[204:207], v[72:75]
	v_mfma_f32_16x16x32_bf16 v[124:127], v[144:147], v[160:163], v[124:127]
	v_mfma_f32_16x16x32_bf16 v[120:123], v[152:155], v[160:163], v[120:123]
	v_mfma_f32_16x16x32_bf16 v[100:103], v[144:147], v[168:171], v[100:103]
	v_mfma_f32_16x16x32_bf16 v[96:99], v[152:155], v[168:171], v[96:99]
	v_mfma_f32_16x16x32_bf16 v[84:87], v[144:147], v[176:179], v[84:87]
	v_mfma_f32_16x16x32_bf16 v[80:83], v[152:155], v[176:179], v[80:83]
	v_mfma_f32_16x16x32_bf16 v[68:71], v[144:147], v[200:203], v[68:71]
	v_mfma_f32_16x16x32_bf16 v[64:67], v[152:155], v[200:203], v[64:67]
	v_mfma_f32_16x16x32_bf16 v[124:127], v[148:151], v[164:167], v[124:127]
	v_mfma_f32_16x16x32_bf16 v[120:123], v[156:159], v[164:167], v[120:123]
	v_mfma_f32_16x16x32_bf16 v[100:103], v[148:151], v[172:175], v[100:103]
	v_mfma_f32_16x16x32_bf16 v[96:99], v[156:159], v[172:175], v[96:99]
	v_mfma_f32_16x16x32_bf16 v[84:87], v[148:151], v[180:183], v[84:87]
	v_mfma_f32_16x16x32_bf16 v[80:83], v[156:159], v[180:183], v[80:83]
	v_mfma_f32_16x16x32_bf16 v[68:71], v[148:151], v[204:207], v[68:71]
	v_mfma_f32_16x16x32_bf16 v[64:67], v[156:159], v[204:207], v[64:67]
	s_barrier
	s_add_i32 s50, s68, s9
	s_mov_b32 m0, s50
	s_add_u32 s98, s54, 0x80
	s_addc_u32 s99, s55, 0
	ds_read_b128 v[160:163], v223 offset:49152
	ds_read_b128 v[164:167], v223 offset:50176
	ds_read_b128 v[168:171], v223 offset:51200
	ds_read_b128 v[172:175], v223 offset:52224
	ds_read_b128 v[176:179], v223 offset:53248
	ds_read_b128 v[180:183], v223 offset:54272
	ds_read_b128 v[200:203], v223 offset:55296
	ds_read_b128 v[204:207], v223 offset:56320
	global_load_lds_dwordx4 v186, s[98:99]
	s_add_i32 m0, s50, 0x2000
	s_add_u32 s50, s54, 0x104080
	s_addc_u32 s51, s55, 0
	s_add_i32 s54, s69, s9
	global_load_lds_dwordx4 v190, s[98:99]
	s_mov_b32 m0, s54
	s_nop 0
	global_load_lds_dwordx4 v186, s[50:51]
	s_add_i32 m0, s54, 0x2000
	s_nop 0
	global_load_lds_dwordx4 v190, s[50:51]
	s_waitcnt vmcnt(4)
	s_waitcnt lgkmcnt(0)
	s_barrier
	v_mfma_f32_16x16x32_bf16 v[60:63], v[104:107], v[160:163], v[60:63]
	v_mfma_f32_16x16x32_bf16 v[56:59], v[128:131], v[160:163], v[56:59]
	v_mfma_f32_16x16x32_bf16 v[44:47], v[104:107], v[168:171], v[44:47]
	v_mfma_f32_16x16x32_bf16 v[40:43], v[128:131], v[168:171], v[40:43]
	v_mfma_f32_16x16x32_bf16 v[28:31], v[104:107], v[176:179], v[28:31]
	v_mfma_f32_16x16x32_bf16 v[24:27], v[128:131], v[176:179], v[24:27]
	v_mfma_f32_16x16x32_bf16 v[12:15], v[104:107], v[200:203], v[12:15]
	v_mfma_f32_16x16x32_bf16 v[8:11], v[128:131], v[200:203], v[8:11]
	v_mfma_f32_16x16x32_bf16 v[60:63], v[116:119], v[164:167], v[60:63]
	v_mfma_f32_16x16x32_bf16 v[56:59], v[140:143], v[164:167], v[56:59]
	v_mfma_f32_16x16x32_bf16 v[44:47], v[116:119], v[172:175], v[44:47]
	v_mfma_f32_16x16x32_bf16 v[40:43], v[140:143], v[172:175], v[40:43]
	v_mfma_f32_16x16x32_bf16 v[28:31], v[116:119], v[180:183], v[28:31]
	v_mfma_f32_16x16x32_bf16 v[24:27], v[140:143], v[180:183], v[24:27]
	v_mfma_f32_16x16x32_bf16 v[12:15], v[116:119], v[204:207], v[12:15]
	v_mfma_f32_16x16x32_bf16 v[8:11], v[140:143], v[204:207], v[8:11]
	v_mfma_f32_16x16x32_bf16 v[52:55], v[144:147], v[160:163], v[52:55]
	v_mfma_f32_16x16x32_bf16 v[48:51], v[152:155], v[160:163], v[48:51]
	v_mfma_f32_16x16x32_bf16 v[36:39], v[144:147], v[168:171], v[36:39]
	v_mfma_f32_16x16x32_bf16 v[32:35], v[152:155], v[168:171], v[32:35]
	v_mfma_f32_16x16x32_bf16 v[20:23], v[144:147], v[176:179], v[20:23]
	v_mfma_f32_16x16x32_bf16 v[16:19], v[152:155], v[176:179], v[16:19]
	v_mfma_f32_16x16x32_bf16 v[4:7], v[144:147], v[200:203], v[4:7]
	v_mfma_f32_16x16x32_bf16 v[0:3], v[152:155], v[200:203], v[0:3]
	v_mfma_f32_16x16x32_bf16 v[52:55], v[148:151], v[164:167], v[52:55]
	v_mfma_f32_16x16x32_bf16 v[48:51], v[156:159], v[164:167], v[48:51]
	v_mfma_f32_16x16x32_bf16 v[36:39], v[148:151], v[172:175], v[36:39]
	v_mfma_f32_16x16x32_bf16 v[32:35], v[156:159], v[172:175], v[32:35]
	v_mfma_f32_16x16x32_bf16 v[20:23], v[148:151], v[180:183], v[20:23]
	v_mfma_f32_16x16x32_bf16 v[16:19], v[156:159], v[180:183], v[16:19]
	v_mfma_f32_16x16x32_bf16 v[4:7], v[148:151], v[204:207], v[4:7]
	v_mfma_f32_16x16x32_bf16 v[0:3], v[156:159], v[204:207], v[0:3]
	s_barrier
	s_add_i32 s67, s67, 2
	s_add_u32 s65, s65, 0x100
	s_addc_u32 s66, s66, 0
	s_cmp_gt_u32 s67, 61
	s_mov_b64 s[50:51], s[52:53]
	s_cbranch_scc0 .LBB0_1037
	s_and_b64 vcc, exec, s[46:47]
	s_cbranch_vccz .LBB0_1040
	s_barrier

; #define PG8_STAGE(bufoff, gbase, voff) do { _Pragma("unroll") for (int _i = 0; _i < 2; ++_i) \
;         __builtin_amdgcn_global_load_lds((const unsigned*)((const char*)(gbase) + (voff)[_i]), (PG8_LAS unsigned*)(lds + (bufoff) + ldsw + _i * 8192), 16, 0, 0); } while (0)
; #define PG8_STAGE_NT(bufoff, gbase, voff) do { _Pragma("unroll") for (int _i = 0; _i < 2; ++_i) \
;         __builtin_amdgcn_global_load_lds((const unsigned*)((const char*)(gbase) + (voff)[_i]), (PG8_LAS unsigned*)(lds + (bufoff) + ldsw + _i * 8192), 16, 0, PG8_B_AUX); } while (0)
; #define PG8_LDA(dst, b, h) do { _Pragma("unroll") for (int m = 0; m < 4; ++m) _Pragma("unroll") for (int k = 0; k < 2; ++k) dst[m][k] = *(const PG8_LAS bf16x8*)(lds + PG8_SA(b, h) + aoff + m * 2048 + k * 1024); } while (0)
; #define PG8_LDB(dst, b, h) do { _Pragma("unroll") for (int n = 0; n < 2; ++n) _Pragma("unroll") for (int k = 0; k < 2; ++k) dst[n][k] = *(const PG8_LAS bf16x8*)(lds + PG8_SB(b, h) + boff + n * 2048 + k * 1024); } while (0)
; #define PG8_WAIT_V(n) asm volatile("s_waitcnt vmcnt(" #n ")" ::: "memory")
; #define PG8_WAIT_L(n) asm volatile("s_waitcnt lgkmcnt(" #n ")" ::: "memory")
; #define PG8_BAR __builtin_amdgcn_s_barrier()
; #define PG8_SCHED __builtin_amdgcn_sched_barrier(0)
; template <class Epi, class Sched, bool ALIGN_EPI = false, bool SP2 = false>
; __device__ __forceinline__ void gemm_phase(PG8_LAS unsigned char* lds, const Gemm g, const Sched& S, const Epi& E, int wid) {
;     ...
;             const bool last = (t == nt - 2);
;             const char* a1 = cA + (size_t)(t + 1) * kstep;
;             const char* a2 = last ? nA : cA + (size_t)(t + 2) * kstep; const char* b2 = last ? nB : cB + (size_t)(t + 2) * kstep;
;             const char* a3 = a2 + kstep; const char* b3 = b2 + kstep;
;             if (last && has_next) S.a_ready(nxt);
;             if constexpr (SP2) {
;             PG8_LDB(B0, 0, 0); PG8_LDB(B1, 0, 1); PG8_SCHED; PG8_LDA(At, 0, 0); PG8_STAGE(PG8_SA(1, 1), a1 + hstepA, voffA);
;             PG8_WAIT_V(8); PG8_WAIT_L(0); PG8_BAR; PG8_MMA(0, 0, At, B0); PG8_MMA(0, 1, At, B1); PG8_BAR; PG8_SCHED;
;             PG8_LDA(At, 0, 1); PG8_STAGE_NT(PG8_SB(0, 0), b2, voffB); PG8_STAGE_NT(PG8_SB(0, 1), b2 + hstepB, voffB); PG8_STAGE(PG8_SA(0, 0), a2, voffA);
;             PG8_WAIT_V(8); PG8_WAIT_L(0); PG8_BAR; PG8_MMA(1, 0, At, B0); PG8_MMA(1, 1, At, B1); PG8_BAR; PG8_SCHED;
.LBB0_1133:
	ds_read_b128 v[144:147], v155
	ds_read_b128 v[148:151], v155 offset:1024
	ds_read_b128 v[160:163], v155 offset:2048
	ds_read_b128 v[164:167], v155 offset:3072
	ds_read_b128 v[168:171], v156
	ds_read_b128 v[172:175], v156 offset:1024
	ds_read_b128 v[176:179], v156 offset:2048
	ds_read_b128 v[180:183], v156 offset:3072
	s_add_u32 s4, s46, 0x100
	s_addc_u32 s5, s47, 0
	s_add_u32 s98, s46, 0x80
	s_addc_u32 s99, s47, 0
	s_add_u32 s100, s46, 0x104080
	s_addc_u32 s101, s47, 0
	s_cmp_eq_u32 s63, 60
	s_cselect_b32 s51, s43, s5
	s_cselect_b32 s50, s42, s4
	s_cselect_b32 s49, s45, s62
	s_cselect_b32 s48, s44, s61
	s_add_i32 m0, s22, 0xc000
	ds_read_b128 v[184:187], v157
	ds_read_b128 v[188:191], v157 offset:1024
	ds_read_b128 v[192:195], v157 offset:2048
	ds_read_b128 v[196:199], v157 offset:3072
	ds_read_b128 v[200:203], v157 offset:4096
	ds_read_b128 v[204:207], v157 offset:5120
	ds_read_b128 v[208:211], v157 offset:6144
	ds_read_b128 v[212:215], v157 offset:7168
	global_load_lds_dwordx4 v134, s[100:101]
	s_add_i32 m0, s22, 0xe000
	s_nop 0
	global_load_lds_dwordx4 v130, s[100:101]
	s_mov_b32 m0, s52
	s_nop 0
	global_load_lds_dwordx4 v134, s[98:99]
	s_mov_b32 m0, s53
	s_nop 0
	global_load_lds_dwordx4 v130, s[98:99]
	s_nop 0
	s_waitcnt vmcnt(8)
	s_waitcnt lgkmcnt(0)
	s_barrier
	v_mfma_f32_16x16x32_bf16 v[112:115], v[144:147], v[184:187], v[112:115]
	v_mfma_f32_16x16x32_bf16 v[108:111], v[160:163], v[184:187], v[108:111]
	v_mfma_f32_16x16x32_bf16 v[104:107], v[144:147], v[192:195], v[104:107]
	v_mfma_f32_16x16x32_bf16 v[100:103], v[160:163], v[192:195], v[100:103]
	v_mfma_f32_16x16x32_bf16 v[92:95], v[144:147], v[200:203], v[92:95]
	v_mfma_f32_16x16x32_bf16 v[84:87], v[160:163], v[200:203], v[84:87]
	v_mfma_f32_16x16x32_bf16 v[76:79], v[144:147], v[208:211], v[76:79]
	v_mfma_f32_16x16x32_bf16 v[68:71], v[160:163], v[208:211], v[68:71]
	v_mfma_f32_16x16x32_bf16 v[112:115], v[148:151], v[188:191], v[112:115]
	v_mfma_f32_16x16x32_bf16 v[108:111], v[164:167], v[188:191], v[108:111]
	v_mfma_f32_16x16x32_bf16 v[104:107], v[148:151], v[196:199], v[104:107]
	v_mfma_f32_16x16x32_bf16 v[100:103], v[164:167], v[196:199], v[100:103]
	v_mfma_f32_16x16x32_bf16 v[92:95], v[148:151], v[204:207], v[92:95]
	v_mfma_f32_16x16x32_bf16 v[84:87], v[164:167], v[204:207], v[84:87]
	v_mfma_f32_16x16x32_bf16 v[76:79], v[148:151], v[212:215], v[76:79]
	v_mfma_f32_16x16x32_bf16 v[68:71], v[164:167], v[212:215], v[68:71]
	v_mfma_f32_16x16x32_bf16 v[124:127], v[168:171], v[184:187], v[124:127]
	v_mfma_f32_16x16x32_bf16 v[120:123], v[176:179], v[184:187], v[120:123]
	v_mfma_f32_16x16x32_bf16 v[116:119], v[168:171], v[192:195], v[116:119]
	v_mfma_f32_16x16x32_bf16 v[96:99], v[176:179], v[192:195], v[96:99]
	v_mfma_f32_16x16x32_bf16 v[88:91], v[168:171], v[200:203], v[88:91]
	v_mfma_f32_16x16x32_bf16 v[80:83], v[176:179], v[200:203], v[80:83]
	v_mfma_f32_16x16x32_bf16 v[72:75], v[168:171], v[208:211], v[72:75]
	v_mfma_f32_16x16x32_bf16 v[64:67], v[176:179], v[208:211], v[64:67]
	v_mfma_f32_16x16x32_bf16 v[124:127], v[172:175], v[188:191], v[124:127]
	v_mfma_f32_16x16x32_bf16 v[120:123], v[180:183], v[188:191], v[120:123]
	v_mfma_f32_16x16x32_bf16 v[116:119], v[172:175], v[196:199], v[116:119]
	v_mfma_f32_16x16x32_bf16 v[96:99], v[180:183], v[196:199], v[96:99]
	v_mfma_f32_16x16x32_bf16 v[88:91], v[172:175], v[204:207], v[88:91]
	v_mfma_f32_16x16x32_bf16 v[80:83], v[180:183], v[204:207], v[80:83]
	v_mfma_f32_16x16x32_bf16 v[72:75], v[172:175], v[212:215], v[72:75]
	v_mfma_f32_16x16x32_bf16 v[64:67], v[180:183], v[212:215], v[64:67]
	s_barrier
	s_add_i32 s46, s55, s9
	s_mov_b32 m0, s46
	ds_read_b128 v[184:187], v157 offset:16384
	ds_read_b128 v[188:191], v157 offset:17408
	ds_read_b128 v[192:195], v157 offset:18432
	ds_read_b128 v[196:199], v157 offset:19456
	ds_read_b128 v[200:203], v157 offset:20480
	ds_read_b128 v[204:207], v157 offset:21504
	ds_read_b128 v[208:211], v157 offset:22528
	ds_read_b128 v[212:215], v157 offset:23552
	global_load_lds_dwordx4 v132, s[48:49]
	s_add_i32 m0, s46, 0x2000
	s_add_u32 s46, s48, 0x104000
	s_addc_u32 s47, s49, 0
	s_add_i32 s64, s56, s9
	global_load_lds_dwordx4 v128, s[48:49]
	s_mov_b32 m0, s64
	s_nop 0
	global_load_lds_dwordx4 v132, s[46:47]
	s_add_i32 m0, s64, 0x2000
	s_nop 0
	global_load_lds_dwordx4 v128, s[46:47]
	s_nop 0
	s_waitcnt vmcnt(4)
	s_waitcnt lgkmcnt(0)
	s_barrier
	v_mfma_f32_16x16x32_bf16 v[60:63], v[144:147], v[184:187], v[60:63]
	v_mfma_f32_16x16x32_bf16 v[52:55], v[160:163], v[184:187], v[52:55]
	v_mfma_f32_16x16x32_bf16 v[44:47], v[144:147], v[192:195], v[44:47]
	v_mfma_f32_16x16x32_bf16 v[36:39], v[160:163], v[192:195], v[36:39]
	v_mfma_f32_16x16x32_bf16 v[28:31], v[144:147], v[200:203], v[28:31]
	v_mfma_f32_16x16x32_bf16 v[20:23], v[160:163], v[200:203], v[20:23]
	v_mfma_f32_16x16x32_bf16 v[12:15], v[144:147], v[208:211], v[12:15]
	v_mfma_f32_16x16x32_bf16 v[4:7], v[160:163], v[208:211], v[4:7]
	v_mfma_f32_16x16x32_bf16 v[60:63], v[148:151], v[188:191], v[60:63]
	v_mfma_f32_16x16x32_bf16 v[52:55], v[164:167], v[188:191], v[52:55]
	v_mfma_f32_16x16x32_bf16 v[44:47], v[148:151], v[196:199], v[44:47]
	v_mfma_f32_16x16x32_bf16 v[36:39], v[164:167], v[196:199], v[36:39]
	v_mfma_f32_16x16x32_bf16 v[28:31], v[148:151], v[204:207], v[28:31]
	v_mfma_f32_16x16x32_bf16 v[20:23], v[164:167], v[204:207], v[20:23]
	v_mfma_f32_16x16x32_bf16 v[12:15], v[148:151], v[212:215], v[12:15]
	v_mfma_f32_16x16x32_bf16 v[4:7], v[164:167], v[212:215], v[4:7]
	v_mfma_f32_16x16x32_bf16 v[56:59], v[168:171], v[184:187], v[56:59]
	v_mfma_f32_16x16x32_bf16 v[48:51], v[176:179], v[184:187], v[48:51]
	v_mfma_f32_16x16x32_bf16 v[40:43], v[168:171], v[192:195], v[40:43]
	v_mfma_f32_16x16x32_bf16 v[32:35], v[176:179], v[192:195], v[32:35]
	v_mfma_f32_16x16x32_bf16 v[24:27], v[168:171], v[200:203], v[24:27]
	v_mfma_f32_16x16x32_bf16 v[16:19], v[176:179], v[200:203], v[16:19]
	v_mfma_f32_16x16x32_bf16 v[8:11], v[168:171], v[208:211], v[8:11]
	v_mfma_f32_16x16x32_bf16 v[0:3], v[176:179], v[208:211], v[0:3]
	v_mfma_f32_16x16x32_bf16 v[56:59], v[172:175], v[188:191], v[56:59]
	v_mfma_f32_16x16x32_bf16 v[48:51], v[180:183], v[188:191], v[48:51]
	v_mfma_f32_16x16x32_bf16 v[40:43], v[172:175], v[196:199], v[40:43]
	v_mfma_f32_16x16x32_bf16 v[32:35], v[180:183], v[196:199], v[32:35]
	v_mfma_f32_16x16x32_bf16 v[24:27], v[172:175], v[204:207], v[24:27]
	v_mfma_f32_16x16x32_bf16 v[16:19], v[180:183], v[204:207], v[16:19]
	v_mfma_f32_16x16x32_bf16 v[8:11], v[172:175], v[212:215], v[8:11]
	v_mfma_f32_16x16x32_bf16 v[0:3], v[180:183], v[212:215], v[0:3]
	s_barrier
; #define PG8_STAGE(bufoff, gbase, voff) do { _Pragma("unroll") for (int _i = 0; _i < 2; ++_i) \
;         __builtin_amdgcn_global_load_lds((const unsigned*)((const char*)(gbase) + (voff)[_i]), (PG8_LAS unsigned*)(lds + (bufoff) + ldsw + _i * 8192), 16, 0, 0); } while (0)
; #define PG8_STAGE_NT(bufoff, gbase, voff) do { _Pragma("unroll") for (int _i = 0; _i < 2; ++_i) \
;         __builtin_amdgcn_global_load_lds((const unsigned*)((const char*)(gbase) + (voff)[_i]), (PG8_LAS unsigned*)(lds + (bufoff) + ldsw + _i * 8192), 16, 0, PG8_B_AUX); } while (0)
; #define PG8_LDA(dst, b, h) do { _Pragma("unroll") for (int m = 0; m < 4; ++m) _Pragma("unroll") for (int k = 0; k < 2; ++k) dst[m][k] = *(const PG8_LAS bf16x8*)(lds + PG8_SA(b, h) + aoff + m * 2048 + k * 1024); } while (0)
; #define PG8_LDB(dst, b, h) do { _Pragma("unroll") for (int n = 0; n < 2; ++n) _Pragma("unroll") for (int k = 0; k < 2; ++k) dst[n][k] = *(const PG8_LAS bf16x8*)(lds + PG8_SB(b, h) + boff + n * 2048 + k * 1024); } while (0)
; #define PG8_MMA(ai, bj, At, Bt) do { __builtin_amdgcn_s_setprio(1); _Pragma("unroll") for (int m = 0; m < 4; ++m) _Pragma("unroll") for (int n = 0; n < 2; ++n) _Pragma("unroll") for (int k = 0; k < 2; ++k) \
;         acc[ai][bj][m][n] = __builtin_amdgcn_mfma_f32_16x16x32_bf16(Bt[n][k], At[m][k], acc[ai][bj][m][n], 0, 0, 0); __builtin_amdgcn_s_setprio(0); } while (0)
; #define PG8_WAIT_V(n) asm volatile("s_waitcnt vmcnt(" #n ")" ::: "memory")
; #define PG8_WAIT_L(n) asm volatile("s_waitcnt lgkmcnt(" #n ")" ::: "memory")
; #define PG8_BAR __builtin_amdgcn_s_barrier()
; #define PG8_SCHED __builtin_amdgcn_sched_barrier(0)
; template <class Epi, class Sched, bool ALIGN_EPI = false, bool SP2 = false>
; __device__ __forceinline__ void gemm_phase(PG8_LAS unsigned char* lds, const Gemm g, const Sched& S, const Epi& E, int wid) {
;     ...
;             PG8_LDB(B0, 1, 0); PG8_LDB(B1, 1, 1); PG8_SCHED; PG8_LDA(At, 1, 0); PG8_STAGE(PG8_SA(0, 1), a2 + hstepA, voffA);
;             PG8_WAIT_V(8); PG8_WAIT_L(0); PG8_BAR; PG8_MMA(0, 0, At, B0); PG8_MMA(0, 1, At, B1); PG8_BAR; PG8_SCHED;
;             PG8_LDA(At, 1, 1); PG8_STAGE_NT(PG8_SB(1, 0), b3, voffB); PG8_STAGE_NT(PG8_SB(1, 1), b3 + hstepB, voffB); PG8_STAGE(PG8_SA(1, 0), a3, voffA);
;             PG8_WAIT_V(8); PG8_WAIT_L(0); PG8_BAR; PG8_MMA(1, 0, At, B0); PG8_MMA(1, 1, At, B1); PG8_BAR; PG8_SCHED;
	s_add_i32 s64, 0, 0x18000
	v_add_u32_e32 v159, s64, v153
	s_add_i32 s65, 0, 0x1c000
	ds_read_b128 v[144:147], v159
	ds_read_b128 v[148:151], v159 offset:1024
	ds_read_b128 v[160:163], v159 offset:2048
	ds_read_b128 v[164:167], v159 offset:3072
	v_add_u32_e32 v159, s65, v153
	ds_read_b128 v[168:171], v159
	ds_read_b128 v[172:175], v159 offset:1024
	ds_read_b128 v[176:179], v159 offset:2048
	ds_read_b128 v[180:183], v159 offset:3072
	s_add_u32 s46, s50, 0x104000
	s_addc_u32 s47, s51, 0
	s_mov_b32 m0, s24
	ds_read_b128 v[184:187], v157 offset:32768
	ds_read_b128 v[188:191], v157 offset:33792
	ds_read_b128 v[192:195], v157 offset:34816
	ds_read_b128 v[196:199], v157 offset:35840
	ds_read_b128 v[200:203], v157 offset:36864
	ds_read_b128 v[204:207], v157 offset:37888
	ds_read_b128 v[208:211], v157 offset:38912
	ds_read_b128 v[212:215], v157 offset:39936
	global_load_lds_dwordx4 v134, s[46:47]
	s_mov_b32 m0, s25
	s_nop 0
	global_load_lds_dwordx4 v130, s[46:47]
	s_mov_b32 m0, s22
	s_nop 0
	global_load_lds_dwordx4 v134, s[50:51]
	s_mov_b32 m0, s23
	s_nop 0
	global_load_lds_dwordx4 v130, s[50:51]
	s_waitcnt vmcnt(8)
	s_waitcnt lgkmcnt(0)
	s_barrier
	v_mfma_f32_16x16x32_bf16 v[112:115], v[144:147], v[184:187], v[112:115]
	v_mfma_f32_16x16x32_bf16 v[108:111], v[160:163], v[184:187], v[108:111]
	v_mfma_f32_16x16x32_bf16 v[104:107], v[144:147], v[192:195], v[104:107]
	v_mfma_f32_16x16x32_bf16 v[100:103], v[160:163], v[192:195], v[100:103]
	v_mfma_f32_16x16x32_bf16 v[92:95], v[144:147], v[200:203], v[92:95]
	v_mfma_f32_16x16x32_bf16 v[84:87], v[160:163], v[200:203], v[84:87]
	v_mfma_f32_16x16x32_bf16 v[76:79], v[144:147], v[208:211], v[76:79]
	v_mfma_f32_16x16x32_bf16 v[68:71], v[160:163], v[208:211], v[68:71]
	v_mfma_f32_16x16x32_bf16 v[112:115], v[148:151], v[188:191], v[112:115]
	v_mfma_f32_16x16x32_bf16 v[108:111], v[164:167], v[188:191], v[108:111]
	v_mfma_f32_16x16x32_bf16 v[104:107], v[148:151], v[196:199], v[104:107]
	v_mfma_f32_16x16x32_bf16 v[100:103], v[164:167], v[196:199], v[100:103]
	v_mfma_f32_16x16x32_bf16 v[92:95], v[148:151], v[204:207], v[92:95]
	v_mfma_f32_16x16x32_bf16 v[84:87], v[164:167], v[204:207], v[84:87]
	v_mfma_f32_16x16x32_bf16 v[76:79], v[148:151], v[212:215], v[76:79]
	v_mfma_f32_16x16x32_bf16 v[68:71], v[164:167], v[212:215], v[68:71]
	v_mfma_f32_16x16x32_bf16 v[124:127], v[168:171], v[184:187], v[124:127]
	v_mfma_f32_16x16x32_bf16 v[120:123], v[176:179], v[184:187], v[120:123]
	v_mfma_f32_16x16x32_bf16 v[116:119], v[168:171], v[192:195], v[116:119]
	v_mfma_f32_16x16x32_bf16 v[96:99], v[176:179], v[192:195], v[96:99]
	v_mfma_f32_16x16x32_bf16 v[88:91], v[168:171], v[200:203], v[88:91]
	v_mfma_f32_16x16x32_bf16 v[80:83], v[176:179], v[200:203], v[80:83]
	v_mfma_f32_16x16x32_bf16 v[72:75], v[168:171], v[208:211], v[72:75]
	v_mfma_f32_16x16x32_bf16 v[64:67], v[176:179], v[208:211], v[64:67]
	v_mfma_f32_16x16x32_bf16 v[124:127], v[172:175], v[188:191], v[124:127]
	v_mfma_f32_16x16x32_bf16 v[120:123], v[180:183], v[188:191], v[120:123]
	v_mfma_f32_16x16x32_bf16 v[116:119], v[172:175], v[196:199], v[116:119]
	v_mfma_f32_16x16x32_bf16 v[96:99], v[180:183], v[196:199], v[96:99]
	v_mfma_f32_16x16x32_bf16 v[88:91], v[172:175], v[204:207], v[88:91]
	v_mfma_f32_16x16x32_bf16 v[80:83], v[180:183], v[204:207], v[80:83]
	v_mfma_f32_16x16x32_bf16 v[72:75], v[172:175], v[212:215], v[72:75]
	v_mfma_f32_16x16x32_bf16 v[64:67], v[180:183], v[212:215], v[64:67]
	s_barrier
	s_add_i32 s46, s64, s9
	s_mov_b32 m0, s46
	s_add_u32 s98, s48, 0x80
	s_addc_u32 s99, s49, 0
	ds_read_b128 v[184:187], v157 offset:49152
	ds_read_b128 v[188:191], v157 offset:50176
	ds_read_b128 v[192:195], v157 offset:51200
	ds_read_b128 v[196:199], v157 offset:52224
	ds_read_b128 v[200:203], v157 offset:53248
	ds_read_b128 v[204:207], v157 offset:54272
	ds_read_b128 v[208:211], v157 offset:55296
	ds_read_b128 v[212:215], v157 offset:56320
	global_load_lds_dwordx4 v132, s[98:99]
	s_add_i32 m0, s46, 0x2000
	s_add_u32 s46, s48, 0x104080
	s_addc_u32 s47, s49, 0
	s_add_i32 s48, s65, s9
	global_load_lds_dwordx4 v128, s[98:99]
	s_mov_b32 m0, s48
	s_nop 0
	global_load_lds_dwordx4 v132, s[46:47]
	s_add_i32 m0, s48, 0x2000
	s_nop 0
	global_load_lds_dwordx4 v128, s[46:47]
	s_waitcnt vmcnt(4)
	s_waitcnt lgkmcnt(0)
	s_barrier
	v_mfma_f32_16x16x32_bf16 v[60:63], v[144:147], v[184:187], v[60:63]
	v_mfma_f32_16x16x32_bf16 v[52:55], v[160:163], v[184:187], v[52:55]
	v_mfma_f32_16x16x32_bf16 v[44:47], v[144:147], v[192:195], v[44:47]
	v_mfma_f32_16x16x32_bf16 v[36:39], v[160:163], v[192:195], v[36:39]
	v_mfma_f32_16x16x32_bf16 v[28:31], v[144:147], v[200:203], v[28:31]
	v_mfma_f32_16x16x32_bf16 v[20:23], v[160:163], v[200:203], v[20:23]
	v_mfma_f32_16x16x32_bf16 v[12:15], v[144:147], v[208:211], v[12:15]
	v_mfma_f32_16x16x32_bf16 v[4:7], v[160:163], v[208:211], v[4:7]
	v_mfma_f32_16x16x32_bf16 v[60:63], v[148:151], v[188:191], v[60:63]
	v_mfma_f32_16x16x32_bf16 v[52:55], v[164:167], v[188:191], v[52:55]
	v_mfma_f32_16x16x32_bf16 v[44:47], v[148:151], v[196:199], v[44:47]
	v_mfma_f32_16x16x32_bf16 v[36:39], v[164:167], v[196:199], v[36:39]
	v_mfma_f32_16x16x32_bf16 v[28:31], v[148:151], v[204:207], v[28:31]
	v_mfma_f32_16x16x32_bf16 v[20:23], v[164:167], v[204:207], v[20:23]
	v_mfma_f32_16x16x32_bf16 v[12:15], v[148:151], v[212:215], v[12:15]
	v_mfma_f32_16x16x32_bf16 v[4:7], v[164:167], v[212:215], v[4:7]
	v_mfma_f32_16x16x32_bf16 v[56:59], v[168:171], v[184:187], v[56:59]
	v_mfma_f32_16x16x32_bf16 v[48:51], v[176:179], v[184:187], v[48:51]
	v_mfma_f32_16x16x32_bf16 v[40:43], v[168:171], v[192:195], v[40:43]
	v_mfma_f32_16x16x32_bf16 v[32:35], v[176:179], v[192:195], v[32:35]
	v_mfma_f32_16x16x32_bf16 v[24:27], v[168:171], v[200:203], v[24:27]
	v_mfma_f32_16x16x32_bf16 v[16:19], v[176:179], v[200:203], v[16:19]
	v_mfma_f32_16x16x32_bf16 v[8:11], v[168:171], v[208:211], v[8:11]
	v_mfma_f32_16x16x32_bf16 v[0:3], v[176:179], v[208:211], v[0:3]
	v_mfma_f32_16x16x32_bf16 v[56:59], v[172:175], v[188:191], v[56:59]
	v_mfma_f32_16x16x32_bf16 v[48:51], v[180:183], v[188:191], v[48:51]
	v_mfma_f32_16x16x32_bf16 v[40:43], v[172:175], v[196:199], v[40:43]
	v_mfma_f32_16x16x32_bf16 v[32:35], v[180:183], v[196:199], v[32:35]
	v_mfma_f32_16x16x32_bf16 v[24:27], v[172:175], v[204:207], v[24:27]
	v_mfma_f32_16x16x32_bf16 v[16:19], v[180:183], v[204:207], v[16:19]
	v_mfma_f32_16x16x32_bf16 v[8:11], v[172:175], v[212:215], v[8:11]
	v_mfma_f32_16x16x32_bf16 v[0:3], v[180:183], v[212:215], v[0:3]
	s_barrier
	s_add_i32 s63, s63, 2
	s_add_u32 s61, s61, 0x100
	s_addc_u32 s62, s62, 0
	s_cmp_gt_u32 s63, 61
	s_mov_b64 s[46:47], s[4:5]
	s_cbranch_scc0 .LBB0_1133
	s_and_b64 vcc, exec, s[40:41]
	s_cbranch_vccz .LBB0_1136
	s_barrier

; #define PG8_STAGE(bufoff, gbase, voff) do { _Pragma("unroll") for (int _i = 0; _i < 2; ++_i) \
;         __builtin_amdgcn_global_load_lds((const unsigned*)((const char*)(gbase) + (voff)[_i]), (PG8_LAS unsigned*)(lds + (bufoff) + ldsw + _i * 8192), 16, 0, 0); } while (0)
; #define PG8_STAGE_NT(bufoff, gbase, voff) do { _Pragma("unroll") for (int _i = 0; _i < 2; ++_i) \
;         __builtin_amdgcn_global_load_lds((const unsigned*)((const char*)(gbase) + (voff)[_i]), (PG8_LAS unsigned*)(lds + (bufoff) + ldsw + _i * 8192), 16, 0, PG8_B_AUX); } while (0)
; #define PG8_LDA(dst, b, h) do { _Pragma("unroll") for (int m = 0; m < 4; ++m) _Pragma("unroll") for (int k = 0; k < 2; ++k) dst[m][k] = *(const PG8_LAS bf16x8*)(lds + PG8_SA(b, h) + aoff + m * 2048 + k * 1024); } while (0)
; #define PG8_LDB(dst, b, h) do { _Pragma("unroll") for (int n = 0; n < 2; ++n) _Pragma("unroll") for (int k = 0; k < 2; ++k) dst[n][k] = *(const PG8_LAS bf16x8*)(lds + PG8_SB(b, h) + boff + n * 2048 + k * 1024); } while (0)
; #define PG8_WAIT_V(n) asm volatile("s_waitcnt vmcnt(" #n ")" ::: "memory")
; #define PG8_WAIT_L(n) asm volatile("s_waitcnt lgkmcnt(" #n ")" ::: "memory")
; #define PG8_BAR __builtin_amdgcn_s_barrier()
; #define PG8_SCHED __builtin_amdgcn_sched_barrier(0)
; template <class Epi, class Sched, bool ALIGN_EPI = false, bool SP2 = false>
; __device__ __forceinline__ void gemm_phase(PG8_LAS unsigned char* lds, const Gemm g, const Sched& S, const Epi& E, int wid) {
;     ...
;             const bool last = (t == nt - 2);
;             const char* a1 = cA + (size_t)(t + 1) * kstep;
;             const char* a2 = last ? nA : cA + (size_t)(t + 2) * kstep; const char* b2 = last ? nB : cB + (size_t)(t + 2) * kstep;
;             const char* a3 = a2 + kstep; const char* b3 = b2 + kstep;
;             if (last && has_next) S.a_ready(nxt);
;             if constexpr (SP2) {
;             PG8_LDB(B0, 0, 0); PG8_LDB(B1, 0, 1); PG8_SCHED; PG8_LDA(At, 0, 0); PG8_STAGE(PG8_SA(1, 1), a1 + hstepA, voffA);
;             PG8_WAIT_V(8); PG8_WAIT_L(0); PG8_BAR; PG8_MMA(0, 0, At, B0); PG8_MMA(0, 1, At, B1); PG8_BAR; PG8_SCHED;
;             PG8_LDA(At, 0, 1); PG8_STAGE_NT(PG8_SB(0, 0), b2, voffB); PG8_STAGE_NT(PG8_SB(0, 1), b2 + hstepB, voffB); PG8_STAGE(PG8_SA(0, 0), a2, voffA);
;             PG8_WAIT_V(8); PG8_WAIT_L(0); PG8_BAR; PG8_MMA(1, 0, At, B0); PG8_MMA(1, 1, At, B1); PG8_BAR; PG8_SCHED;
.LBB0_1221:
	ds_read_b128 v[128:131], v205
	ds_read_b128 v[132:135], v205 offset:1024
	ds_read_b128 v[136:139], v205 offset:2048
	ds_read_b128 v[140:143], v205 offset:3072
	ds_read_b128 v[144:147], v206
	ds_read_b128 v[148:151], v206 offset:1024
	ds_read_b128 v[152:155], v206 offset:2048
	ds_read_b128 v[156:159], v206 offset:3072
	s_add_u32 s48, s46, 0x100
	s_addc_u32 s49, s47, 0
	s_cmpk_eq_i32 s63, 0xa8
	s_cselect_b32 s53, s7, s49
	s_cselect_b32 s52, s6, s48
	s_cselect_b32 s51, s45, s62
	s_cselect_b32 s50, s44, s61
	v_lshl_add_u64 v[200:201], s[46:47], 0, v[176:177]
	s_add_i32 m0, s17, 0xc000
	ds_read_b128 v[160:163], v207
	ds_read_b128 v[164:167], v207 offset:1024
	ds_read_b128 v[184:187], v207 offset:2048
	ds_read_b128 v[188:191], v207 offset:3072
	ds_read_b128 v[192:195], v207 offset:4096
	ds_read_b128 v[196:199], v207 offset:5120
	ds_read_b128 v[210:213], v207 offset:6144
	ds_read_b128 v[214:217], v207 offset:7168
	global_load_lds_dwordx4 v[200:201], off
	v_lshl_add_u64 v[200:201], s[46:47], 0, v[178:179]
	s_add_i32 m0, s17, 0xe000
	s_nop 0
	global_load_lds_dwordx4 v[200:201], off
	s_waitcnt vmcnt(8)
	s_waitcnt lgkmcnt(0)
	s_barrier
	v_mfma_f32_16x16x32_bf16 v[124:127], v[128:131], v[160:163], v[124:127]
	v_mfma_f32_16x16x32_bf16 v[120:123], v[136:139], v[160:163], v[120:123]
	v_mfma_f32_16x16x32_bf16 v[116:119], v[128:131], v[184:187], v[116:119]
	v_mfma_f32_16x16x32_bf16 v[112:115], v[136:139], v[184:187], v[112:115]
	v_mfma_f32_16x16x32_bf16 v[92:95], v[128:131], v[192:195], v[92:95]
	v_mfma_f32_16x16x32_bf16 v[88:91], v[136:139], v[192:195], v[88:91]
	v_mfma_f32_16x16x32_bf16 v[76:79], v[128:131], v[210:213], v[76:79]
	v_mfma_f32_16x16x32_bf16 v[72:75], v[136:139], v[210:213], v[72:75]
	v_mfma_f32_16x16x32_bf16 v[124:127], v[132:135], v[164:167], v[124:127]
	v_mfma_f32_16x16x32_bf16 v[120:123], v[140:143], v[164:167], v[120:123]
	v_mfma_f32_16x16x32_bf16 v[116:119], v[132:135], v[188:191], v[116:119]
	v_mfma_f32_16x16x32_bf16 v[112:115], v[140:143], v[188:191], v[112:115]
	v_mfma_f32_16x16x32_bf16 v[92:95], v[132:135], v[196:199], v[92:95]
	v_mfma_f32_16x16x32_bf16 v[88:91], v[140:143], v[196:199], v[88:91]
	v_mfma_f32_16x16x32_bf16 v[76:79], v[132:135], v[214:217], v[76:79]
	v_mfma_f32_16x16x32_bf16 v[72:75], v[140:143], v[214:217], v[72:75]
	v_mfma_f32_16x16x32_bf16 v[108:111], v[144:147], v[160:163], v[108:111]
	v_mfma_f32_16x16x32_bf16 v[104:107], v[152:155], v[160:163], v[104:107]
	v_mfma_f32_16x16x32_bf16 v[100:103], v[144:147], v[184:187], v[100:103]
	v_mfma_f32_16x16x32_bf16 v[96:99], v[152:155], v[184:187], v[96:99]
	v_mfma_f32_16x16x32_bf16 v[84:87], v[144:147], v[192:195], v[84:87]
	v_mfma_f32_16x16x32_bf16 v[80:83], v[152:155], v[192:195], v[80:83]
	v_mfma_f32_16x16x32_bf16 v[68:71], v[144:147], v[210:213], v[68:71]
	v_mfma_f32_16x16x32_bf16 v[64:67], v[152:155], v[210:213], v[64:67]
	v_mfma_f32_16x16x32_bf16 v[108:111], v[148:151], v[164:167], v[108:111]
	v_mfma_f32_16x16x32_bf16 v[104:107], v[156:159], v[164:167], v[104:107]
	v_mfma_f32_16x16x32_bf16 v[100:103], v[148:151], v[188:191], v[100:103]
	v_mfma_f32_16x16x32_bf16 v[96:99], v[156:159], v[188:191], v[96:99]
	v_mfma_f32_16x16x32_bf16 v[84:87], v[148:151], v[196:199], v[84:87]
	v_mfma_f32_16x16x32_bf16 v[80:83], v[156:159], v[196:199], v[80:83]
	v_mfma_f32_16x16x32_bf16 v[68:71], v[148:151], v[214:217], v[68:71]
	v_mfma_f32_16x16x32_bf16 v[64:67], v[156:159], v[214:217], v[64:67]
	s_barrier
	s_add_i32 s46, s56, s9
	v_lshl_add_u64 v[200:201], s[50:51], 0, v[170:171]
	s_mov_b32 m0, s46
	ds_read_b128 v[160:163], v207 offset:16384
	ds_read_b128 v[164:167], v207 offset:17408
	ds_read_b128 v[184:187], v207 offset:18432
	ds_read_b128 v[188:191], v207 offset:19456
	ds_read_b128 v[192:195], v207 offset:20480
	ds_read_b128 v[196:199], v207 offset:21504
	ds_read_b128 v[210:213], v207 offset:22528
	ds_read_b128 v[214:217], v207 offset:23552
	global_load_lds_dwordx4 v[200:201], off
	s_add_i32 m0, s46, 0x2000
	s_add_u32 s46, s50, 0x2b4000
	v_lshl_add_u64 v[218:219], s[50:51], 0, v[174:175]
	s_addc_u32 s47, s51, 0
	s_add_i32 s64, s57, s9
	global_load_lds_dwordx4 v[218:219], off
	v_lshl_add_u64 v[220:221], s[46:47], 0, v[170:171]
	s_mov_b32 m0, s64
	v_lshl_add_u64 v[222:223], s[52:53], 0, v[172:173]
	global_load_lds_dwordx4 v[220:221], off
	v_lshl_add_u64 v[220:221], s[46:47], 0, v[174:175]
	s_add_i32 m0, s64, 0x2000
	s_nop 0
	global_load_lds_dwordx4 v[220:221], off
	v_lshl_add_u64 v[220:221], s[52:53], 0, v[168:169]
	s_mov_b32 m0, s17
	s_nop 0
	global_load_lds_dwordx4 v[220:221], off
	s_mov_b32 m0, s19
	s_nop 0
	global_load_lds_dwordx4 v[222:223], off
	s_waitcnt vmcnt(8)
	s_waitcnt lgkmcnt(0)
	s_barrier
; #define PG8_STAGE(bufoff, gbase, voff) do { _Pragma("unroll") for (int _i = 0; _i < 2; ++_i) \
;         __builtin_amdgcn_global_load_lds((const unsigned*)((const char*)(gbase) + (voff)[_i]), (PG8_LAS unsigned*)(lds + (bufoff) + ldsw + _i * 8192), 16, 0, 0); } while (0)
; #define PG8_LDA(dst, b, h) do { _Pragma("unroll") for (int m = 0; m < 4; ++m) _Pragma("unroll") for (int k = 0; k < 2; ++k) dst[m][k] = *(const PG8_LAS bf16x8*)(lds + PG8_SA(b, h) + aoff + m * 2048 + k * 1024); } while (0)
; #define PG8_LDB(dst, b, h) do { _Pragma("unroll") for (int n = 0; n < 2; ++n) _Pragma("unroll") for (int k = 0; k < 2; ++k) dst[n][k] = *(const PG8_LAS bf16x8*)(lds + PG8_SB(b, h) + boff + n * 2048 + k * 1024); } while (0)
; #define PG8_MMA(ai, bj, At, Bt) do { __builtin_amdgcn_s_setprio(1); _Pragma("unroll") for (int m = 0; m < 4; ++m) _Pragma("unroll") for (int n = 0; n < 2; ++n) _Pragma("unroll") for (int k = 0; k < 2; ++k) \
;         acc[ai][bj][m][n] = __builtin_amdgcn_mfma_f32_16x16x32_bf16(Bt[n][k], At[m][k], acc[ai][bj][m][n], 0, 0, 0); __builtin_amdgcn_s_setprio(0); } while (0)
; #define PG8_WAIT_V(n) asm volatile("s_waitcnt vmcnt(" #n ")" ::: "memory")
; #define PG8_WAIT_L(n) asm volatile("s_waitcnt lgkmcnt(" #n ")" ::: "memory")
; #define PG8_BAR __builtin_amdgcn_s_barrier()
; #define PG8_SCHED __builtin_amdgcn_sched_barrier(0)
; template <class Epi, class Sched, bool ALIGN_EPI = false, bool SP2 = false>
; __device__ __forceinline__ void gemm_phase(PG8_LAS unsigned char* lds, const Gemm g, const Sched& S, const Epi& E, int wid) {
;     ...
;             PG8_WAIT_V(8); PG8_WAIT_L(0); PG8_BAR; PG8_MMA(1, 0, At, B0); PG8_MMA(1, 1, At, B1); PG8_BAR; PG8_SCHED;
;             PG8_LDB(B0, 1, 0); PG8_LDB(B1, 1, 1); PG8_SCHED; PG8_LDA(At, 1, 0); PG8_STAGE(PG8_SA(0, 1), a2 + hstepA, voffA);
;             PG8_WAIT_V(8); PG8_WAIT_L(0); PG8_BAR; PG8_MMA(0, 0, At, B0); PG8_MMA(0, 1, At, B1); PG8_BAR; PG8_SCHED;
	v_mfma_f32_16x16x32_bf16 v[60:63], v[128:131], v[160:163], v[60:63]
	v_mfma_f32_16x16x32_bf16 v[56:59], v[136:139], v[160:163], v[56:59]
	v_mfma_f32_16x16x32_bf16 v[44:47], v[128:131], v[184:187], v[44:47]
	v_mfma_f32_16x16x32_bf16 v[40:43], v[136:139], v[184:187], v[40:43]
	v_mfma_f32_16x16x32_bf16 v[28:31], v[128:131], v[192:195], v[28:31]
	v_mfma_f32_16x16x32_bf16 v[24:27], v[136:139], v[192:195], v[24:27]
	v_mfma_f32_16x16x32_bf16 v[12:15], v[128:131], v[210:213], v[12:15]
	v_mfma_f32_16x16x32_bf16 v[8:11], v[136:139], v[210:213], v[8:11]
	v_mfma_f32_16x16x32_bf16 v[60:63], v[132:135], v[164:167], v[60:63]
	v_mfma_f32_16x16x32_bf16 v[56:59], v[140:143], v[164:167], v[56:59]
	v_mfma_f32_16x16x32_bf16 v[44:47], v[132:135], v[188:191], v[44:47]
	v_mfma_f32_16x16x32_bf16 v[40:43], v[140:143], v[188:191], v[40:43]
	v_mfma_f32_16x16x32_bf16 v[28:31], v[132:135], v[196:199], v[28:31]
	v_mfma_f32_16x16x32_bf16 v[24:27], v[140:143], v[196:199], v[24:27]
	v_mfma_f32_16x16x32_bf16 v[12:15], v[132:135], v[214:217], v[12:15]
	v_mfma_f32_16x16x32_bf16 v[8:11], v[140:143], v[214:217], v[8:11]
	v_mfma_f32_16x16x32_bf16 v[52:55], v[144:147], v[160:163], v[52:55]
	v_mfma_f32_16x16x32_bf16 v[48:51], v[152:155], v[160:163], v[48:51]
	v_mfma_f32_16x16x32_bf16 v[36:39], v[144:147], v[184:187], v[36:39]
	v_mfma_f32_16x16x32_bf16 v[32:35], v[152:155], v[184:187], v[32:35]
	v_mfma_f32_16x16x32_bf16 v[20:23], v[144:147], v[192:195], v[20:23]
	v_mfma_f32_16x16x32_bf16 v[16:19], v[152:155], v[192:195], v[16:19]
	v_mfma_f32_16x16x32_bf16 v[4:7], v[144:147], v[210:213], v[4:7]
	v_mfma_f32_16x16x32_bf16 v[0:3], v[152:155], v[210:213], v[0:3]
	v_mfma_f32_16x16x32_bf16 v[52:55], v[148:151], v[164:167], v[52:55]
	v_mfma_f32_16x16x32_bf16 v[48:51], v[156:159], v[164:167], v[48:51]
	v_mfma_f32_16x16x32_bf16 v[36:39], v[148:151], v[188:191], v[36:39]
	v_mfma_f32_16x16x32_bf16 v[32:35], v[156:159], v[188:191], v[32:35]
	v_mfma_f32_16x16x32_bf16 v[20:23], v[148:151], v[196:199], v[20:23]
	v_mfma_f32_16x16x32_bf16 v[16:19], v[156:159], v[196:199], v[16:19]
	v_mfma_f32_16x16x32_bf16 v[4:7], v[148:151], v[214:217], v[4:7]
	v_mfma_f32_16x16x32_bf16 v[0:3], v[156:159], v[214:217], v[0:3]
	s_barrier
	s_add_i32 s64, 0, 0x18000
	s_add_i32 s65, 0, 0x1c000
	v_add_u32_e32 v140, s64, v203
	v_add_u32_e32 v156, s65, v203
	ds_read_b128 v[128:131], v140
	ds_read_b128 v[132:135], v140 offset:1024
	ds_read_b128 v[136:139], v140 offset:2048
	ds_read_b128 v[140:143], v140 offset:3072
	ds_read_b128 v[144:147], v156
	ds_read_b128 v[148:151], v156 offset:1024
	ds_read_b128 v[152:155], v156 offset:2048
	ds_read_b128 v[156:159], v156 offset:3072
	s_add_u32 s46, s52, 0x2b4000
	s_addc_u32 s47, s53, 0
	s_mov_b32 m0, s22
	v_lshl_add_u64 v[224:225], s[46:47], 0, v[168:169]
	ds_read_b128 v[160:163], v207 offset:32768
	ds_read_b128 v[164:167], v207 offset:33792
	ds_read_b128 v[184:187], v207 offset:34816
	ds_read_b128 v[188:191], v207 offset:35840
	ds_read_b128 v[192:195], v207 offset:36864
	ds_read_b128 v[196:199], v207 offset:37888
	ds_read_b128 v[210:213], v207 offset:38912
	ds_read_b128 v[214:217], v207 offset:39936
	global_load_lds_dwordx4 v[224:225], off
	v_lshl_add_u64 v[224:225], s[46:47], 0, v[172:173]
	s_mov_b32 m0, s23
	s_nop 0
	global_load_lds_dwordx4 v[224:225], off
	s_waitcnt vmcnt(8)
	s_waitcnt lgkmcnt(0)
	s_barrier
	v_mfma_f32_16x16x32_bf16 v[124:127], v[128:131], v[160:163], v[124:127]
	v_mfma_f32_16x16x32_bf16 v[120:123], v[136:139], v[160:163], v[120:123]
	v_mfma_f32_16x16x32_bf16 v[116:119], v[128:131], v[184:187], v[116:119]
	v_mfma_f32_16x16x32_bf16 v[112:115], v[136:139], v[184:187], v[112:115]
	v_mfma_f32_16x16x32_bf16 v[92:95], v[128:131], v[192:195], v[92:95]
	v_mfma_f32_16x16x32_bf16 v[88:91], v[136:139], v[192:195], v[88:91]
	v_mfma_f32_16x16x32_bf16 v[76:79], v[128:131], v[210:213], v[76:79]
	v_mfma_f32_16x16x32_bf16 v[72:75], v[136:139], v[210:213], v[72:75]
	v_mfma_f32_16x16x32_bf16 v[124:127], v[132:135], v[164:167], v[124:127]
	v_mfma_f32_16x16x32_bf16 v[120:123], v[140:143], v[164:167], v[120:123]
	v_mfma_f32_16x16x32_bf16 v[116:119], v[132:135], v[188:191], v[116:119]
	v_mfma_f32_16x16x32_bf16 v[112:115], v[140:143], v[188:191], v[112:115]
	v_mfma_f32_16x16x32_bf16 v[92:95], v[132:135], v[196:199], v[92:95]
	v_mfma_f32_16x16x32_bf16 v[88:91], v[140:143], v[196:199], v[88:91]
	v_mfma_f32_16x16x32_bf16 v[76:79], v[132:135], v[214:217], v[76:79]
	v_mfma_f32_16x16x32_bf16 v[72:75], v[140:143], v[214:217], v[72:75]
	v_mfma_f32_16x16x32_bf16 v[108:111], v[144:147], v[160:163], v[108:111]
	v_mfma_f32_16x16x32_bf16 v[104:107], v[152:155], v[160:163], v[104:107]
	v_mfma_f32_16x16x32_bf16 v[100:103], v[144:147], v[184:187], v[100:103]
	v_mfma_f32_16x16x32_bf16 v[96:99], v[152:155], v[184:187], v[96:99]
	v_mfma_f32_16x16x32_bf16 v[84:87], v[144:147], v[192:195], v[84:87]
	v_mfma_f32_16x16x32_bf16 v[80:83], v[152:155], v[192:195], v[80:83]
	v_mfma_f32_16x16x32_bf16 v[68:71], v[144:147], v[210:213], v[68:71]
	v_mfma_f32_16x16x32_bf16 v[64:67], v[152:155], v[210:213], v[64:67]
	v_mfma_f32_16x16x32_bf16 v[108:111], v[148:151], v[164:167], v[108:111]
	v_mfma_f32_16x16x32_bf16 v[104:107], v[156:159], v[164:167], v[104:107]
	v_mfma_f32_16x16x32_bf16 v[100:103], v[148:151], v[188:191], v[100:103]
	v_mfma_f32_16x16x32_bf16 v[96:99], v[156:159], v[188:191], v[96:99]
	v_mfma_f32_16x16x32_bf16 v[84:87], v[148:151], v[196:199], v[84:87]
	v_mfma_f32_16x16x32_bf16 v[80:83], v[156:159], v[196:199], v[80:83]
	v_mfma_f32_16x16x32_bf16 v[68:71], v[148:151], v[214:217], v[68:71]
	v_mfma_f32_16x16x32_bf16 v[64:67], v[156:159], v[214:217], v[64:67]
	s_barrier
; #define PG8_STAGE(bufoff, gbase, voff) do { _Pragma("unroll") for (int _i = 0; _i < 2; ++_i) \
;         __builtin_amdgcn_global_load_lds((const unsigned*)((const char*)(gbase) + (voff)[_i]), (PG8_LAS unsigned*)(lds + (bufoff) + ldsw + _i * 8192), 16, 0, 0); } while (0)
; #define PG8_STAGE_NT(bufoff, gbase, voff) do { _Pragma("unroll") for (int _i = 0; _i < 2; ++_i) \
;         __builtin_amdgcn_global_load_lds((const unsigned*)((const char*)(gbase) + (voff)[_i]), (PG8_LAS unsigned*)(lds + (bufoff) + ldsw + _i * 8192), 16, 0, PG8_B_AUX); } while (0)
; #define PG8_LDA(dst, b, h) do { _Pragma("unroll") for (int m = 0; m < 4; ++m) _Pragma("unroll") for (int k = 0; k < 2; ++k) dst[m][k] = *(const PG8_LAS bf16x8*)(lds + PG8_SA(b, h) + aoff + m * 2048 + k * 1024); } while (0)
; #define PG8_MMA(ai, bj, At, Bt) do { __builtin_amdgcn_s_setprio(1); _Pragma("unroll") for (int m = 0; m < 4; ++m) _Pragma("unroll") for (int n = 0; n < 2; ++n) _Pragma("unroll") for (int k = 0; k < 2; ++k) \
;         acc[ai][bj][m][n] = __builtin_amdgcn_mfma_f32_16x16x32_bf16(Bt[n][k], At[m][k], acc[ai][bj][m][n], 0, 0, 0); __builtin_amdgcn_s_setprio(0); } while (0)
; #define PG8_WAIT_V(n) asm volatile("s_waitcnt vmcnt(" #n ")" ::: "memory")
; #define PG8_WAIT_L(n) asm volatile("s_waitcnt lgkmcnt(" #n ")" ::: "memory")
; #define PG8_BAR __builtin_amdgcn_s_barrier()
; #define PG8_SCHED __builtin_amdgcn_sched_barrier(0)
; template <class Epi, class Sched, bool ALIGN_EPI = false, bool SP2 = false>
; __device__ __forceinline__ void gemm_phase(PG8_LAS unsigned char* lds, const Gemm g, const Sched& S, const Epi& E, int wid) {
;     ...
;             PG8_LDA(At, 1, 1); PG8_STAGE_NT(PG8_SB(1, 0), b3, voffB); PG8_STAGE_NT(PG8_SB(1, 1), b3 + hstepB, voffB); PG8_STAGE(PG8_SA(1, 0), a3, voffA);
;             PG8_WAIT_V(8); PG8_WAIT_L(0); PG8_BAR; PG8_MMA(1, 0, At, B0); PG8_MMA(1, 1, At, B1); PG8_BAR; PG8_SCHED;
	s_add_i32 s46, s64, s9
	v_lshl_add_u64 v[200:201], v[200:201], 0, s[40:41]
	s_mov_b32 m0, s46
	ds_read_b128 v[160:163], v207 offset:49152
	ds_read_b128 v[164:167], v207 offset:50176
	ds_read_b128 v[184:187], v207 offset:51200
	ds_read_b128 v[188:191], v207 offset:52224
	ds_read_b128 v[192:195], v207 offset:53248
	ds_read_b128 v[196:199], v207 offset:54272
	ds_read_b128 v[210:213], v207 offset:55296
	ds_read_b128 v[214:217], v207 offset:56320
	global_load_lds_dwordx4 v[200:201], off
	s_add_i32 m0, s46, 0x2000
	s_add_u32 s46, s50, 0x2b4080
	v_lshl_add_u64 v[200:201], v[218:219], 0, s[40:41]
	s_addc_u32 s47, s51, 0
	s_add_i32 s50, s65, s9
	global_load_lds_dwordx4 v[200:201], off
	v_lshl_add_u64 v[200:201], s[46:47], 0, v[170:171]
	s_mov_b32 m0, s50
	s_nop 0
	global_load_lds_dwordx4 v[200:201], off
	v_lshl_add_u64 v[200:201], s[46:47], 0, v[174:175]
	s_add_i32 m0, s50, 0x2000
	s_nop 0
	global_load_lds_dwordx4 v[200:201], off
	v_lshl_add_u64 v[200:201], v[220:221], 0, s[40:41]
	s_mov_b32 m0, s25
	s_nop 0
	global_load_lds_dwordx4 v[200:201], off
	v_lshl_add_u64 v[200:201], v[222:223], 0, s[40:41]
	s_mov_b32 m0, s29
	s_nop 0
	global_load_lds_dwordx4 v[200:201], off
	s_nop 0
	s_waitcnt vmcnt(8)
	s_waitcnt lgkmcnt(0)
	s_barrier
	v_mfma_f32_16x16x32_bf16 v[60:63], v[128:131], v[160:163], v[60:63]
	v_mfma_f32_16x16x32_bf16 v[56:59], v[136:139], v[160:163], v[56:59]
	v_mfma_f32_16x16x32_bf16 v[44:47], v[128:131], v[184:187], v[44:47]
	v_mfma_f32_16x16x32_bf16 v[40:43], v[136:139], v[184:187], v[40:43]
	v_mfma_f32_16x16x32_bf16 v[28:31], v[128:131], v[192:195], v[28:31]
	v_mfma_f32_16x16x32_bf16 v[24:27], v[136:139], v[192:195], v[24:27]
	v_mfma_f32_16x16x32_bf16 v[12:15], v[128:131], v[210:213], v[12:15]
	v_mfma_f32_16x16x32_bf16 v[8:11], v[136:139], v[210:213], v[8:11]
	v_mfma_f32_16x16x32_bf16 v[60:63], v[132:135], v[164:167], v[60:63]
	v_mfma_f32_16x16x32_bf16 v[56:59], v[140:143], v[164:167], v[56:59]
	v_mfma_f32_16x16x32_bf16 v[44:47], v[132:135], v[188:191], v[44:47]
	v_mfma_f32_16x16x32_bf16 v[40:43], v[140:143], v[188:191], v[40:43]
	v_mfma_f32_16x16x32_bf16 v[28:31], v[132:135], v[196:199], v[28:31]
	v_mfma_f32_16x16x32_bf16 v[24:27], v[140:143], v[196:199], v[24:27]
	v_mfma_f32_16x16x32_bf16 v[12:15], v[132:135], v[214:217], v[12:15]
	v_mfma_f32_16x16x32_bf16 v[8:11], v[140:143], v[214:217], v[8:11]
	v_mfma_f32_16x16x32_bf16 v[52:55], v[144:147], v[160:163], v[52:55]
	v_mfma_f32_16x16x32_bf16 v[48:51], v[152:155], v[160:163], v[48:51]
	v_mfma_f32_16x16x32_bf16 v[36:39], v[144:147], v[184:187], v[36:39]
	v_mfma_f32_16x16x32_bf16 v[32:35], v[152:155], v[184:187], v[32:35]
	v_mfma_f32_16x16x32_bf16 v[20:23], v[144:147], v[192:195], v[20:23]
	v_mfma_f32_16x16x32_bf16 v[16:19], v[152:155], v[192:195], v[16:19]
	v_mfma_f32_16x16x32_bf16 v[4:7], v[144:147], v[210:213], v[4:7]
	v_mfma_f32_16x16x32_bf16 v[0:3], v[152:155], v[210:213], v[0:3]
	v_mfma_f32_16x16x32_bf16 v[52:55], v[148:151], v[164:167], v[52:55]
	v_mfma_f32_16x16x32_bf16 v[48:51], v[156:159], v[164:167], v[48:51]
	v_mfma_f32_16x16x32_bf16 v[36:39], v[148:151], v[188:191], v[36:39]
	v_mfma_f32_16x16x32_bf16 v[32:35], v[156:159], v[188:191], v[32:35]
	v_mfma_f32_16x16x32_bf16 v[20:23], v[148:151], v[196:199], v[20:23]
	v_mfma_f32_16x16x32_bf16 v[16:19], v[156:159], v[196:199], v[16:19]
	v_mfma_f32_16x16x32_bf16 v[4:7], v[148:151], v[214:217], v[4:7]
	v_mfma_f32_16x16x32_bf16 v[0:3], v[156:159], v[214:217], v[0:3]
	s_barrier
	s_add_i32 s63, s63, 2
	s_add_u32 s61, s61, 0x100
	s_addc_u32 s62, s62, 0
	s_cmpk_gt_u32 s63, 0xa9
	s_mov_b64 s[46:47], s[48:49]
	s_cbranch_scc0 .LBB0_1221
	s_and_b64 vcc, exec, s[42:43]
	s_cbranch_vccz .LBB0_1224
	s_barrier

; #define PG8_STAGE(bufoff, gbase, voff) do { _Pragma("unroll") for (int _i = 0; _i < 2; ++_i) \
;         __builtin_amdgcn_global_load_lds((const unsigned*)((const char*)(gbase) + (voff)[_i]), (PG8_LAS unsigned*)(lds + (bufoff) + ldsw + _i * 8192), 16, 0, 0); } while (0)
; #define PG8_STAGE_NT(bufoff, gbase, voff) do { _Pragma("unroll") for (int _i = 0; _i < 2; ++_i) \
;         __builtin_amdgcn_global_load_lds((const unsigned*)((const char*)(gbase) + (voff)[_i]), (PG8_LAS unsigned*)(lds + (bufoff) + ldsw + _i * 8192), 16, 0, PG8_B_AUX); } while (0)
; #define PG8_LDA(dst, b, h) do { _Pragma("unroll") for (int m = 0; m < 4; ++m) _Pragma("unroll") for (int k = 0; k < 2; ++k) dst[m][k] = *(const PG8_LAS bf16x8*)(lds + PG8_SA(b, h) + aoff + m * 2048 + k * 1024); } while (0)
; #define PG8_LDB(dst, b, h) do { _Pragma("unroll") for (int n = 0; n < 2; ++n) _Pragma("unroll") for (int k = 0; k < 2; ++k) dst[n][k] = *(const PG8_LAS bf16x8*)(lds + PG8_SB(b, h) + boff + n * 2048 + k * 1024); } while (0)
; #define PG8_WAIT_V(n) asm volatile("s_waitcnt vmcnt(" #n ")" ::: "memory")
; #define PG8_WAIT_L(n) asm volatile("s_waitcnt lgkmcnt(" #n ")" ::: "memory")
; #define PG8_BAR __builtin_amdgcn_s_barrier()
; #define PG8_SCHED __builtin_amdgcn_sched_barrier(0)
; template <class Epi, class Sched, bool ALIGN_EPI = false, bool SP2 = false>
; __device__ __forceinline__ void gemm_phase(PG8_LAS unsigned char* lds, const Gemm g, const Sched& S, const Epi& E, int wid) {
;     ...
;             const bool last = (t == nt - 2);
;             const char* a1 = cA + (size_t)(t + 1) * kstep;
;             const char* a2 = last ? nA : cA + (size_t)(t + 2) * kstep; const char* b2 = last ? nB : cB + (size_t)(t + 2) * kstep;
;             const char* a3 = a2 + kstep; const char* b3 = b2 + kstep;
;             if (last && has_next) S.a_ready(nxt);
;             if constexpr (SP2) {
;             PG8_LDB(B0, 0, 0); PG8_LDB(B1, 0, 1); PG8_SCHED; PG8_LDA(At, 0, 0); PG8_STAGE(PG8_SA(1, 1), a1 + hstepA, voffA);
;             PG8_WAIT_V(8); PG8_WAIT_L(0); PG8_BAR; PG8_MMA(0, 0, At, B0); PG8_MMA(0, 1, At, B1); PG8_BAR; PG8_SCHED;
;             PG8_LDA(At, 0, 1); PG8_STAGE_NT(PG8_SB(0, 0), b2, voffB); PG8_STAGE_NT(PG8_SB(0, 1), b2 + hstepB, voffB); PG8_STAGE(PG8_SA(0, 0), a2, voffA);
;             PG8_WAIT_V(8); PG8_WAIT_L(0); PG8_BAR; PG8_MMA(1, 0, At, B0); PG8_MMA(1, 1, At, B1); PG8_BAR; PG8_SCHED;
.LBB0_1249:
	ds_read_b128 v[146:149], v141
	ds_read_b128 v[150:153], v141 offset:1024
	ds_read_b128 v[154:157], v141 offset:2048
	ds_read_b128 v[158:161], v141 offset:3072
	ds_read_b128 v[162:165], v142
	ds_read_b128 v[166:169], v142 offset:1024
	ds_read_b128 v[170:173], v142 offset:2048
	ds_read_b128 v[174:177], v142 offset:3072
	s_add_u32 s46, s14, s50
	s_addc_u32 s47, s15, s51
	s_add_u32 s53, s14, s44
	s_addc_u32 s54, s15, s45
	s_cmpk_eq_i32 s52, 0xa8
	s_cselect_b32 s49, s3, s47
	s_cselect_b32 s48, s2, s46
	s_cselect_b32 s47, s11, s54
	s_cselect_b32 s46, s10, s53
	s_mov_b32 m0, s57
	v_lshl_add_u64 v[212:213], s[14:15], 0, v[136:137]
	ds_read_b128 v[178:181], v143
	ds_read_b128 v[182:185], v143 offset:1024
	ds_read_b128 v[186:189], v143 offset:2048
	ds_read_b128 v[190:193], v143 offset:3072
	ds_read_b128 v[194:197], v143 offset:4096
	ds_read_b128 v[198:201], v143 offset:5120
	ds_read_b128 v[202:205], v143 offset:6144
	ds_read_b128 v[208:211], v143 offset:7168
	global_load_lds_dwordx4 v[212:213], off
	v_lshl_add_u64 v[212:213], s[14:15], 0, v[138:139]
	s_mov_b32 m0, s58
	s_nop 0
	global_load_lds_dwordx4 v[212:213], off
	s_nop 0
	s_waitcnt vmcnt(8)
	s_waitcnt lgkmcnt(0)
	s_barrier
	v_mfma_f32_16x16x32_bf16 v[124:127], v[146:149], v[178:181], v[124:127]
	v_mfma_f32_16x16x32_bf16 v[120:123], v[154:157], v[178:181], v[120:123]
	v_mfma_f32_16x16x32_bf16 v[108:111], v[146:149], v[186:189], v[108:111]
	v_mfma_f32_16x16x32_bf16 v[104:107], v[154:157], v[186:189], v[104:107]
	v_mfma_f32_16x16x32_bf16 v[92:95], v[146:149], v[194:197], v[92:95]
	v_mfma_f32_16x16x32_bf16 v[88:91], v[154:157], v[194:197], v[88:91]
	v_mfma_f32_16x16x32_bf16 v[76:79], v[146:149], v[202:205], v[76:79]
	v_mfma_f32_16x16x32_bf16 v[72:75], v[154:157], v[202:205], v[72:75]
	v_mfma_f32_16x16x32_bf16 v[124:127], v[150:153], v[182:185], v[124:127]
	v_mfma_f32_16x16x32_bf16 v[120:123], v[158:161], v[182:185], v[120:123]
	v_mfma_f32_16x16x32_bf16 v[108:111], v[150:153], v[190:193], v[108:111]
	v_mfma_f32_16x16x32_bf16 v[104:107], v[158:161], v[190:193], v[104:107]
	v_mfma_f32_16x16x32_bf16 v[92:95], v[150:153], v[198:201], v[92:95]
	v_mfma_f32_16x16x32_bf16 v[88:91], v[158:161], v[198:201], v[88:91]
	v_mfma_f32_16x16x32_bf16 v[76:79], v[150:153], v[208:211], v[76:79]
	v_mfma_f32_16x16x32_bf16 v[72:75], v[158:161], v[208:211], v[72:75]
	v_mfma_f32_16x16x32_bf16 v[116:119], v[162:165], v[178:181], v[116:119]
	v_mfma_f32_16x16x32_bf16 v[112:115], v[170:173], v[178:181], v[112:115]
	v_mfma_f32_16x16x32_bf16 v[100:103], v[162:165], v[186:189], v[100:103]
	v_mfma_f32_16x16x32_bf16 v[96:99], v[170:173], v[186:189], v[96:99]
	v_mfma_f32_16x16x32_bf16 v[84:87], v[162:165], v[194:197], v[84:87]
	v_mfma_f32_16x16x32_bf16 v[80:83], v[170:173], v[194:197], v[80:83]
	v_mfma_f32_16x16x32_bf16 v[68:71], v[162:165], v[202:205], v[68:71]
	v_mfma_f32_16x16x32_bf16 v[64:67], v[170:173], v[202:205], v[64:67]
	v_mfma_f32_16x16x32_bf16 v[116:119], v[166:169], v[182:185], v[116:119]
	v_mfma_f32_16x16x32_bf16 v[112:115], v[174:177], v[182:185], v[112:115]
	v_mfma_f32_16x16x32_bf16 v[100:103], v[166:169], v[190:193], v[100:103]
	v_mfma_f32_16x16x32_bf16 v[96:99], v[174:177], v[190:193], v[96:99]
	v_mfma_f32_16x16x32_bf16 v[84:87], v[166:169], v[198:201], v[84:87]
	v_mfma_f32_16x16x32_bf16 v[80:83], v[174:177], v[198:201], v[80:83]
	v_mfma_f32_16x16x32_bf16 v[68:71], v[166:169], v[208:211], v[68:71]
	v_mfma_f32_16x16x32_bf16 v[64:67], v[174:177], v[208:211], v[64:67]
	s_barrier
	s_mov_b32 m0, s59
	v_lshl_add_u64 v[212:213], s[46:47], 0, v[130:131]
	s_add_u32 s54, s46, 0x2b4000
	ds_read_b128 v[178:181], v143 offset:16384
	ds_read_b128 v[182:185], v143 offset:17408
	ds_read_b128 v[186:189], v143 offset:18432
	ds_read_b128 v[190:193], v143 offset:19456
	ds_read_b128 v[194:197], v143 offset:20480
	ds_read_b128 v[198:201], v143 offset:21504
	ds_read_b128 v[202:205], v143 offset:22528
	ds_read_b128 v[208:211], v143 offset:23552
	global_load_lds_dwordx4 v[212:213], off
	v_lshl_add_u64 v[214:215], s[46:47], 0, v[134:135]
	s_mov_b32 m0, s60
	s_addc_u32 s55, s47, 0
	global_load_lds_dwordx4 v[214:215], off
	v_lshl_add_u64 v[216:217], s[54:55], 0, v[130:131]
	s_mov_b32 m0, s61
	v_lshl_add_u64 v[218:219], s[48:49], 0, v[132:133]
	global_load_lds_dwordx4 v[216:217], off
	v_lshl_add_u64 v[216:217], s[54:55], 0, v[134:135]
	s_mov_b32 m0, s62
	s_nop 0
	global_load_lds_dwordx4 v[216:217], off
	v_lshl_add_u64 v[216:217], s[48:49], 0, v[128:129]
	s_mov_b32 m0, s17
	s_nop 0
	global_load_lds_dwordx4 v[216:217], off
	s_mov_b32 m0, s19
	s_nop 0
	global_load_lds_dwordx4 v[218:219], off
	s_waitcnt vmcnt(8)
	s_waitcnt lgkmcnt(0)
	s_barrier
; #define PG8_STAGE(bufoff, gbase, voff) do { _Pragma("unroll") for (int _i = 0; _i < 2; ++_i) \
;         __builtin_amdgcn_global_load_lds((const unsigned*)((const char*)(gbase) + (voff)[_i]), (PG8_LAS unsigned*)(lds + (bufoff) + ldsw + _i * 8192), 16, 0, 0); } while (0)
; #define PG8_LDA(dst, b, h) do { _Pragma("unroll") for (int m = 0; m < 4; ++m) _Pragma("unroll") for (int k = 0; k < 2; ++k) dst[m][k] = *(const PG8_LAS bf16x8*)(lds + PG8_SA(b, h) + aoff + m * 2048 + k * 1024); } while (0)
; #define PG8_LDB(dst, b, h) do { _Pragma("unroll") for (int n = 0; n < 2; ++n) _Pragma("unroll") for (int k = 0; k < 2; ++k) dst[n][k] = *(const PG8_LAS bf16x8*)(lds + PG8_SB(b, h) + boff + n * 2048 + k * 1024); } while (0)
; #define PG8_MMA(ai, bj, At, Bt) do { __builtin_amdgcn_s_setprio(1); _Pragma("unroll") for (int m = 0; m < 4; ++m) _Pragma("unroll") for (int n = 0; n < 2; ++n) _Pragma("unroll") for (int k = 0; k < 2; ++k) \
;         acc[ai][bj][m][n] = __builtin_amdgcn_mfma_f32_16x16x32_bf16(Bt[n][k], At[m][k], acc[ai][bj][m][n], 0, 0, 0); __builtin_amdgcn_s_setprio(0); } while (0)
; #define PG8_WAIT_V(n) asm volatile("s_waitcnt vmcnt(" #n ")" ::: "memory")
; #define PG8_WAIT_L(n) asm volatile("s_waitcnt lgkmcnt(" #n ")" ::: "memory")
; #define PG8_BAR __builtin_amdgcn_s_barrier()
; #define PG8_SCHED __builtin_amdgcn_sched_barrier(0)
; template <class Epi, class Sched, bool ALIGN_EPI = false, bool SP2 = false>
; __device__ __forceinline__ void gemm_phase(PG8_LAS unsigned char* lds, const Gemm g, const Sched& S, const Epi& E, int wid) {
;     ...
;             PG8_WAIT_V(8); PG8_WAIT_L(0); PG8_BAR; PG8_MMA(1, 0, At, B0); PG8_MMA(1, 1, At, B1); PG8_BAR; PG8_SCHED;
;             PG8_LDB(B0, 1, 0); PG8_LDB(B1, 1, 1); PG8_SCHED; PG8_LDA(At, 1, 0); PG8_STAGE(PG8_SA(0, 1), a2 + hstepA, voffA);
;             PG8_WAIT_V(8); PG8_WAIT_L(0); PG8_BAR; PG8_MMA(0, 0, At, B0); PG8_MMA(0, 1, At, B1); PG8_BAR; PG8_SCHED;
	v_mfma_f32_16x16x32_bf16 v[60:63], v[146:149], v[178:181], v[60:63]
	v_mfma_f32_16x16x32_bf16 v[56:59], v[154:157], v[178:181], v[56:59]
	v_mfma_f32_16x16x32_bf16 v[44:47], v[146:149], v[186:189], v[44:47]
	v_mfma_f32_16x16x32_bf16 v[40:43], v[154:157], v[186:189], v[40:43]
	v_mfma_f32_16x16x32_bf16 v[28:31], v[146:149], v[194:197], v[28:31]
	v_mfma_f32_16x16x32_bf16 v[24:27], v[154:157], v[194:197], v[24:27]
	v_mfma_f32_16x16x32_bf16 v[12:15], v[146:149], v[202:205], v[12:15]
	v_mfma_f32_16x16x32_bf16 v[8:11], v[154:157], v[202:205], v[8:11]
	v_mfma_f32_16x16x32_bf16 v[60:63], v[150:153], v[182:185], v[60:63]
	v_mfma_f32_16x16x32_bf16 v[56:59], v[158:161], v[182:185], v[56:59]
	v_mfma_f32_16x16x32_bf16 v[44:47], v[150:153], v[190:193], v[44:47]
	v_mfma_f32_16x16x32_bf16 v[40:43], v[158:161], v[190:193], v[40:43]
	v_mfma_f32_16x16x32_bf16 v[28:31], v[150:153], v[198:201], v[28:31]
	v_mfma_f32_16x16x32_bf16 v[24:27], v[158:161], v[198:201], v[24:27]
	v_mfma_f32_16x16x32_bf16 v[12:15], v[150:153], v[208:211], v[12:15]
	v_mfma_f32_16x16x32_bf16 v[8:11], v[158:161], v[208:211], v[8:11]
	v_mfma_f32_16x16x32_bf16 v[52:55], v[162:165], v[178:181], v[52:55]
	v_mfma_f32_16x16x32_bf16 v[48:51], v[170:173], v[178:181], v[48:51]
	v_mfma_f32_16x16x32_bf16 v[36:39], v[162:165], v[186:189], v[36:39]
	v_mfma_f32_16x16x32_bf16 v[32:35], v[170:173], v[186:189], v[32:35]
	v_mfma_f32_16x16x32_bf16 v[20:23], v[162:165], v[194:197], v[20:23]
	v_mfma_f32_16x16x32_bf16 v[16:19], v[170:173], v[194:197], v[16:19]
	v_mfma_f32_16x16x32_bf16 v[4:7], v[162:165], v[202:205], v[4:7]
	v_mfma_f32_16x16x32_bf16 v[0:3], v[170:173], v[202:205], v[0:3]
	v_mfma_f32_16x16x32_bf16 v[52:55], v[166:169], v[182:185], v[52:55]
	v_mfma_f32_16x16x32_bf16 v[48:51], v[174:177], v[182:185], v[48:51]
	v_mfma_f32_16x16x32_bf16 v[36:39], v[166:169], v[190:193], v[36:39]
	v_mfma_f32_16x16x32_bf16 v[32:35], v[174:177], v[190:193], v[32:35]
	v_mfma_f32_16x16x32_bf16 v[20:23], v[166:169], v[198:201], v[20:23]
	v_mfma_f32_16x16x32_bf16 v[16:19], v[174:177], v[198:201], v[16:19]
	v_mfma_f32_16x16x32_bf16 v[4:7], v[166:169], v[208:211], v[4:7]
	v_mfma_f32_16x16x32_bf16 v[0:3], v[174:177], v[208:211], v[0:3]
	s_barrier
	ds_read_b128 v[146:149], v144
	ds_read_b128 v[150:153], v144 offset:1024
	ds_read_b128 v[154:157], v144 offset:2048
	ds_read_b128 v[158:161], v144 offset:3072
	ds_read_b128 v[162:165], v145
	ds_read_b128 v[166:169], v145 offset:1024
	ds_read_b128 v[170:173], v145 offset:2048
	ds_read_b128 v[174:177], v145 offset:3072
	s_add_u32 s48, s48, 0x2b4000
	s_addc_u32 s49, s49, 0
	s_mov_b32 m0, s22
	v_lshl_add_u64 v[220:221], s[48:49], 0, v[128:129]
	ds_read_b128 v[178:181], v143 offset:32768
	ds_read_b128 v[182:185], v143 offset:33792
	ds_read_b128 v[186:189], v143 offset:34816
	ds_read_b128 v[190:193], v143 offset:35840
	ds_read_b128 v[194:197], v143 offset:36864
	ds_read_b128 v[198:201], v143 offset:37888
	ds_read_b128 v[202:205], v143 offset:38912
	ds_read_b128 v[208:211], v143 offset:39936
	global_load_lds_dwordx4 v[220:221], off
	v_lshl_add_u64 v[220:221], s[48:49], 0, v[132:133]
	s_mov_b32 m0, s23
	s_nop 0
	global_load_lds_dwordx4 v[220:221], off
	s_waitcnt vmcnt(8)
	s_waitcnt lgkmcnt(0)
	s_barrier
	v_mfma_f32_16x16x32_bf16 v[124:127], v[146:149], v[178:181], v[124:127]
	v_mfma_f32_16x16x32_bf16 v[120:123], v[154:157], v[178:181], v[120:123]
	v_mfma_f32_16x16x32_bf16 v[108:111], v[146:149], v[186:189], v[108:111]
	v_mfma_f32_16x16x32_bf16 v[104:107], v[154:157], v[186:189], v[104:107]
	v_mfma_f32_16x16x32_bf16 v[92:95], v[146:149], v[194:197], v[92:95]
	v_mfma_f32_16x16x32_bf16 v[88:91], v[154:157], v[194:197], v[88:91]
	v_mfma_f32_16x16x32_bf16 v[76:79], v[146:149], v[202:205], v[76:79]
	v_mfma_f32_16x16x32_bf16 v[72:75], v[154:157], v[202:205], v[72:75]
	v_mfma_f32_16x16x32_bf16 v[124:127], v[150:153], v[182:185], v[124:127]
	v_mfma_f32_16x16x32_bf16 v[120:123], v[158:161], v[182:185], v[120:123]
	v_mfma_f32_16x16x32_bf16 v[108:111], v[150:153], v[190:193], v[108:111]
	v_mfma_f32_16x16x32_bf16 v[104:107], v[158:161], v[190:193], v[104:107]
	v_mfma_f32_16x16x32_bf16 v[92:95], v[150:153], v[198:201], v[92:95]
	v_mfma_f32_16x16x32_bf16 v[88:91], v[158:161], v[198:201], v[88:91]
	v_mfma_f32_16x16x32_bf16 v[76:79], v[150:153], v[208:211], v[76:79]
	v_mfma_f32_16x16x32_bf16 v[72:75], v[158:161], v[208:211], v[72:75]
	v_mfma_f32_16x16x32_bf16 v[116:119], v[162:165], v[178:181], v[116:119]
	v_mfma_f32_16x16x32_bf16 v[112:115], v[170:173], v[178:181], v[112:115]
	v_mfma_f32_16x16x32_bf16 v[100:103], v[162:165], v[186:189], v[100:103]
	v_mfma_f32_16x16x32_bf16 v[96:99], v[170:173], v[186:189], v[96:99]
	v_mfma_f32_16x16x32_bf16 v[84:87], v[162:165], v[194:197], v[84:87]
	v_mfma_f32_16x16x32_bf16 v[80:83], v[170:173], v[194:197], v[80:83]
	v_mfma_f32_16x16x32_bf16 v[68:71], v[162:165], v[202:205], v[68:71]
	v_mfma_f32_16x16x32_bf16 v[64:67], v[170:173], v[202:205], v[64:67]
	v_mfma_f32_16x16x32_bf16 v[116:119], v[166:169], v[182:185], v[116:119]
	v_mfma_f32_16x16x32_bf16 v[112:115], v[174:177], v[182:185], v[112:115]
	v_mfma_f32_16x16x32_bf16 v[100:103], v[166:169], v[190:193], v[100:103]
	v_mfma_f32_16x16x32_bf16 v[96:99], v[174:177], v[190:193], v[96:99]
	v_mfma_f32_16x16x32_bf16 v[84:87], v[166:169], v[198:201], v[84:87]
	v_mfma_f32_16x16x32_bf16 v[80:83], v[174:177], v[198:201], v[80:83]
	v_mfma_f32_16x16x32_bf16 v[68:71], v[166:169], v[208:211], v[68:71]
	v_mfma_f32_16x16x32_bf16 v[64:67], v[174:177], v[208:211], v[64:67]
	s_barrier
; #define PG8_STAGE(bufoff, gbase, voff) do { _Pragma("unroll") for (int _i = 0; _i < 2; ++_i) \
;         __builtin_amdgcn_global_load_lds((const unsigned*)((const char*)(gbase) + (voff)[_i]), (PG8_LAS unsigned*)(lds + (bufoff) + ldsw + _i * 8192), 16, 0, 0); } while (0)
; #define PG8_STAGE_NT(bufoff, gbase, voff) do { _Pragma("unroll") for (int _i = 0; _i < 2; ++_i) \
;         __builtin_amdgcn_global_load_lds((const unsigned*)((const char*)(gbase) + (voff)[_i]), (PG8_LAS unsigned*)(lds + (bufoff) + ldsw + _i * 8192), 16, 0, PG8_B_AUX); } while (0)
; #define PG8_LDA(dst, b, h) do { _Pragma("unroll") for (int m = 0; m < 4; ++m) _Pragma("unroll") for (int k = 0; k < 2; ++k) dst[m][k] = *(const PG8_LAS bf16x8*)(lds + PG8_SA(b, h) + aoff + m * 2048 + k * 1024); } while (0)
; #define PG8_MMA(ai, bj, At, Bt) do { __builtin_amdgcn_s_setprio(1); _Pragma("unroll") for (int m = 0; m < 4; ++m) _Pragma("unroll") for (int n = 0; n < 2; ++n) _Pragma("unroll") for (int k = 0; k < 2; ++k) \
;         acc[ai][bj][m][n] = __builtin_amdgcn_mfma_f32_16x16x32_bf16(Bt[n][k], At[m][k], acc[ai][bj][m][n], 0, 0, 0); __builtin_amdgcn_s_setprio(0); } while (0)
; #define PG8_WAIT_V(n) asm volatile("s_waitcnt vmcnt(" #n ")" ::: "memory")
; #define PG8_WAIT_L(n) asm volatile("s_waitcnt lgkmcnt(" #n ")" ::: "memory")
; #define PG8_BAR __builtin_amdgcn_s_barrier()
; #define PG8_SCHED __builtin_amdgcn_sched_barrier(0)
; template <class Epi, class Sched, bool ALIGN_EPI = false, bool SP2 = false>
; __device__ __forceinline__ void gemm_phase(PG8_LAS unsigned char* lds, const Gemm g, const Sched& S, const Epi& E, int wid) {
;     ...
;             PG8_LDA(At, 1, 1); PG8_STAGE_NT(PG8_SB(1, 0), b3, voffB); PG8_STAGE_NT(PG8_SB(1, 1), b3 + hstepB, voffB); PG8_STAGE(PG8_SA(1, 0), a3, voffA);
;             PG8_WAIT_V(8); PG8_WAIT_L(0); PG8_BAR; PG8_MMA(1, 0, At, B0); PG8_MMA(1, 1, At, B1); PG8_BAR; PG8_SCHED;
;     ...
;     PG8_WAIT_V(0);
;     if constexpr (!ALIGN_EPI) { if (wr == 0) PG8_BAR; }
	s_mov_b32 m0, s63
	v_lshl_add_u64 v[212:213], v[212:213], 0, s[4:5]
	s_add_u32 s46, s46, 0x2b4080
	ds_read_b128 v[178:181], v143 offset:49152
	ds_read_b128 v[182:185], v143 offset:50176
	ds_read_b128 v[186:189], v143 offset:51200
	ds_read_b128 v[190:193], v143 offset:52224
	ds_read_b128 v[194:197], v143 offset:53248
	ds_read_b128 v[198:201], v143 offset:54272
	ds_read_b128 v[202:205], v143 offset:55296
	ds_read_b128 v[208:211], v143 offset:56320
	global_load_lds_dwordx4 v[212:213], off
	v_lshl_add_u64 v[212:213], v[214:215], 0, s[4:5]
	s_mov_b32 m0, s64
	s_addc_u32 s47, s47, 0
	global_load_lds_dwordx4 v[212:213], off
	v_lshl_add_u64 v[212:213], s[46:47], 0, v[130:131]
	s_mov_b32 m0, s65
	s_nop 0
	global_load_lds_dwordx4 v[212:213], off
	v_lshl_add_u64 v[212:213], s[46:47], 0, v[134:135]
	s_mov_b32 m0, s66
	s_nop 0
	global_load_lds_dwordx4 v[212:213], off
	v_lshl_add_u64 v[212:213], v[216:217], 0, s[4:5]
	s_mov_b32 m0, s25
	s_nop 0
	global_load_lds_dwordx4 v[212:213], off
	v_lshl_add_u64 v[212:213], v[218:219], 0, s[4:5]
	s_mov_b32 m0, s56
	s_nop 0
	global_load_lds_dwordx4 v[212:213], off
	s_nop 0
	s_waitcnt vmcnt(8)
	s_waitcnt lgkmcnt(0)
	s_barrier
	v_mfma_f32_16x16x32_bf16 v[60:63], v[146:149], v[178:181], v[60:63]
	v_mfma_f32_16x16x32_bf16 v[56:59], v[154:157], v[178:181], v[56:59]
	v_mfma_f32_16x16x32_bf16 v[44:47], v[146:149], v[186:189], v[44:47]
	v_mfma_f32_16x16x32_bf16 v[40:43], v[154:157], v[186:189], v[40:43]
	v_mfma_f32_16x16x32_bf16 v[28:31], v[146:149], v[194:197], v[28:31]
	v_mfma_f32_16x16x32_bf16 v[24:27], v[154:157], v[194:197], v[24:27]
	v_mfma_f32_16x16x32_bf16 v[12:15], v[146:149], v[202:205], v[12:15]
	v_mfma_f32_16x16x32_bf16 v[8:11], v[154:157], v[202:205], v[8:11]
	v_mfma_f32_16x16x32_bf16 v[60:63], v[150:153], v[182:185], v[60:63]
	v_mfma_f32_16x16x32_bf16 v[56:59], v[158:161], v[182:185], v[56:59]
	v_mfma_f32_16x16x32_bf16 v[44:47], v[150:153], v[190:193], v[44:47]
	v_mfma_f32_16x16x32_bf16 v[40:43], v[158:161], v[190:193], v[40:43]
	v_mfma_f32_16x16x32_bf16 v[28:31], v[150:153], v[198:201], v[28:31]
	v_mfma_f32_16x16x32_bf16 v[24:27], v[158:161], v[198:201], v[24:27]
	v_mfma_f32_16x16x32_bf16 v[12:15], v[150:153], v[208:211], v[12:15]
	v_mfma_f32_16x16x32_bf16 v[8:11], v[158:161], v[208:211], v[8:11]
	v_mfma_f32_16x16x32_bf16 v[52:55], v[162:165], v[178:181], v[52:55]
	v_mfma_f32_16x16x32_bf16 v[48:51], v[170:173], v[178:181], v[48:51]
	v_mfma_f32_16x16x32_bf16 v[36:39], v[162:165], v[186:189], v[36:39]
	v_mfma_f32_16x16x32_bf16 v[32:35], v[170:173], v[186:189], v[32:35]
	v_mfma_f32_16x16x32_bf16 v[20:23], v[162:165], v[194:197], v[20:23]
	v_mfma_f32_16x16x32_bf16 v[16:19], v[170:173], v[194:197], v[16:19]
	v_mfma_f32_16x16x32_bf16 v[4:7], v[162:165], v[202:205], v[4:7]
	v_mfma_f32_16x16x32_bf16 v[0:3], v[170:173], v[202:205], v[0:3]
	v_mfma_f32_16x16x32_bf16 v[52:55], v[166:169], v[182:185], v[52:55]
	v_mfma_f32_16x16x32_bf16 v[48:51], v[174:177], v[182:185], v[48:51]
	v_mfma_f32_16x16x32_bf16 v[36:39], v[166:169], v[190:193], v[36:39]
	v_mfma_f32_16x16x32_bf16 v[32:35], v[174:177], v[190:193], v[32:35]
	v_mfma_f32_16x16x32_bf16 v[20:23], v[166:169], v[198:201], v[20:23]
	v_mfma_f32_16x16x32_bf16 v[16:19], v[174:177], v[198:201], v[16:19]
	v_mfma_f32_16x16x32_bf16 v[4:7], v[166:169], v[208:211], v[4:7]
	v_mfma_f32_16x16x32_bf16 v[0:3], v[174:177], v[208:211], v[0:3]
	s_barrier
	s_add_i32 s52, s52, 2
	s_add_u32 s50, s50, 0x100
	s_addc_u32 s51, s51, 0
	s_add_u32 s44, s44, 0x100
	s_addc_u32 s45, s45, 0
	v_lshl_add_u64 v[136:137], v[136:137], 0, s[42:43]
	s_cmpk_lt_u32 s52, 0xaa
	v_lshl_add_u64 v[138:139], v[138:139], 0, s[42:43]
	s_cbranch_scc1 .LBB0_1249
	s_waitcnt vmcnt(0)
	s_cmpk_lt_u32 s95, 0x100
	s_cselect_b64 s[44:45], -1, 0
	s_cmpk_gt_u32 s95, 0xff
	s_cbranch_scc1 .LBB0_1252
	s_barrier

; #define PG8_STAGE(bufoff, gbase, voff) do { _Pragma("unroll") for (int _i = 0; _i < 2; ++_i) \
;         __builtin_amdgcn_global_load_lds((const unsigned*)((const char*)(gbase) + (voff)[_i]), (PG8_LAS unsigned*)(lds + (bufoff) + ldsw + _i * 8192), 16, 0, 0); } while (0)
; #define PG8_STAGE_NT(bufoff, gbase, voff) do { _Pragma("unroll") for (int _i = 0; _i < 2; ++_i) \
;         __builtin_amdgcn_global_load_lds((const unsigned*)((const char*)(gbase) + (voff)[_i]), (PG8_LAS unsigned*)(lds + (bufoff) + ldsw + _i * 8192), 16, 0, PG8_B_AUX); } while (0)
; #define PG8_LDA(dst, b, h) do { _Pragma("unroll") for (int m = 0; m < 4; ++m) _Pragma("unroll") for (int k = 0; k < 2; ++k) dst[m][k] = *(const PG8_LAS bf16x8*)(lds + PG8_SA(b, h) + aoff + m * 2048 + k * 1024); } while (0)
; #define PG8_LDB(dst, b, h) do { _Pragma("unroll") for (int n = 0; n < 2; ++n) _Pragma("unroll") for (int k = 0; k < 2; ++k) dst[n][k] = *(const PG8_LAS bf16x8*)(lds + PG8_SB(b, h) + boff + n * 2048 + k * 1024); } while (0)
; #define PG8_WAIT_V(n) asm volatile("s_waitcnt vmcnt(" #n ")" ::: "memory")
; #define PG8_WAIT_L(n) asm volatile("s_waitcnt lgkmcnt(" #n ")" ::: "memory")
; #define PG8_BAR __builtin_amdgcn_s_barrier()
; #define PG8_SCHED __builtin_amdgcn_sched_barrier(0)
; template <class Epi, class Sched, bool ALIGN_EPI = false, bool SP2 = false>
; __device__ __forceinline__ void gemm_phase(PG8_LAS unsigned char* lds, const Gemm g, const Sched& S, const Epi& E, int wid) {
;     ...
;             const bool last = (t == nt - 2);
;             const char* a1 = cA + (size_t)(t + 1) * kstep;
;             const char* a2 = last ? nA : cA + (size_t)(t + 2) * kstep; const char* b2 = last ? nB : cB + (size_t)(t + 2) * kstep;
;             const char* a3 = a2 + kstep; const char* b3 = b2 + kstep;
;             if (last && has_next) S.a_ready(nxt);
;             if constexpr (SP2) {
;             PG8_LDB(B0, 0, 0); PG8_LDB(B1, 0, 1); PG8_SCHED; PG8_LDA(At, 0, 0); PG8_STAGE(PG8_SA(1, 1), a1 + hstepA, voffA);
;             PG8_WAIT_V(8); PG8_WAIT_L(0); PG8_BAR; PG8_MMA(0, 0, At, B0); PG8_MMA(0, 1, At, B1); PG8_BAR; PG8_SCHED;
;             PG8_LDA(At, 0, 1); PG8_STAGE_NT(PG8_SB(0, 0), b2, voffB); PG8_STAGE_NT(PG8_SB(0, 1), b2 + hstepB, voffB); PG8_STAGE(PG8_SA(0, 0), a2, voffA);
;             PG8_WAIT_V(8); PG8_WAIT_L(0); PG8_BAR; PG8_MMA(1, 0, At, B0); PG8_MMA(1, 1, At, B1); PG8_BAR; PG8_SCHED;
.LBB0_1307:
	ds_read_b128 v[146:149], v141
	ds_read_b128 v[150:153], v141 offset:1024
	ds_read_b128 v[154:157], v141 offset:2048
	ds_read_b128 v[158:161], v141 offset:3072
	ds_read_b128 v[162:165], v142
	ds_read_b128 v[166:169], v142 offset:1024
	ds_read_b128 v[170:173], v142 offset:2048
	ds_read_b128 v[174:177], v142 offset:3072
	s_add_u32 s30, s14, s21
	s_addc_u32 s31, s15, s40
	s_add_u32 s48, s14, s8
	s_addc_u32 s49, s15, s9
	s_cmpk_eq_i32 s41, 0xa8
	s_cselect_b32 s39, s3, s31
	s_cselect_b32 s38, s2, s30
	s_cselect_b32 s31, s11, s49
	s_cselect_b32 s30, s10, s48
	s_mov_b32 m0, s57
	v_lshl_add_u64 v[202:203], s[14:15], 0, v[136:137]
	ds_read_b128 v[178:181], v143
	ds_read_b128 v[182:185], v143 offset:1024
	ds_read_b128 v[186:189], v143 offset:2048
	ds_read_b128 v[190:193], v143 offset:3072
	ds_read_b128 v[194:197], v143 offset:4096
	ds_read_b128 v[198:201], v143 offset:5120
	ds_read_b128 v[208:211], v143 offset:6144
	ds_read_b128 v[212:215], v143 offset:7168
	global_load_lds_dwordx4 v[202:203], off
	v_lshl_add_u64 v[202:203], s[14:15], 0, v[138:139]
	s_mov_b32 m0, s58
	s_nop 0
	global_load_lds_dwordx4 v[202:203], off
	s_nop 0
	s_waitcnt vmcnt(8)
	s_waitcnt lgkmcnt(0)
	s_barrier
	v_mfma_f32_16x16x32_bf16 v[124:127], v[146:149], v[178:181], v[124:127]
	v_mfma_f32_16x16x32_bf16 v[120:123], v[154:157], v[178:181], v[120:123]
	v_mfma_f32_16x16x32_bf16 v[108:111], v[146:149], v[186:189], v[108:111]
	v_mfma_f32_16x16x32_bf16 v[104:107], v[154:157], v[186:189], v[104:107]
	v_mfma_f32_16x16x32_bf16 v[92:95], v[146:149], v[194:197], v[92:95]
	v_mfma_f32_16x16x32_bf16 v[88:91], v[154:157], v[194:197], v[88:91]
	v_mfma_f32_16x16x32_bf16 v[76:79], v[146:149], v[208:211], v[76:79]
	v_mfma_f32_16x16x32_bf16 v[72:75], v[154:157], v[208:211], v[72:75]
	v_mfma_f32_16x16x32_bf16 v[124:127], v[150:153], v[182:185], v[124:127]
	v_mfma_f32_16x16x32_bf16 v[120:123], v[158:161], v[182:185], v[120:123]
	v_mfma_f32_16x16x32_bf16 v[108:111], v[150:153], v[190:193], v[108:111]
	v_mfma_f32_16x16x32_bf16 v[104:107], v[158:161], v[190:193], v[104:107]
	v_mfma_f32_16x16x32_bf16 v[92:95], v[150:153], v[198:201], v[92:95]
	v_mfma_f32_16x16x32_bf16 v[88:91], v[158:161], v[198:201], v[88:91]
	v_mfma_f32_16x16x32_bf16 v[76:79], v[150:153], v[212:215], v[76:79]
	v_mfma_f32_16x16x32_bf16 v[72:75], v[158:161], v[212:215], v[72:75]
	v_mfma_f32_16x16x32_bf16 v[116:119], v[162:165], v[178:181], v[116:119]
	v_mfma_f32_16x16x32_bf16 v[112:115], v[170:173], v[178:181], v[112:115]
	v_mfma_f32_16x16x32_bf16 v[100:103], v[162:165], v[186:189], v[100:103]
	v_mfma_f32_16x16x32_bf16 v[96:99], v[170:173], v[186:189], v[96:99]
	v_mfma_f32_16x16x32_bf16 v[84:87], v[162:165], v[194:197], v[84:87]
	v_mfma_f32_16x16x32_bf16 v[80:83], v[170:173], v[194:197], v[80:83]
	v_mfma_f32_16x16x32_bf16 v[68:71], v[162:165], v[208:211], v[68:71]
	v_mfma_f32_16x16x32_bf16 v[64:67], v[170:173], v[208:211], v[64:67]
	v_mfma_f32_16x16x32_bf16 v[116:119], v[166:169], v[182:185], v[116:119]
	v_mfma_f32_16x16x32_bf16 v[112:115], v[174:177], v[182:185], v[112:115]
	v_mfma_f32_16x16x32_bf16 v[100:103], v[166:169], v[190:193], v[100:103]
	v_mfma_f32_16x16x32_bf16 v[96:99], v[174:177], v[190:193], v[96:99]
	v_mfma_f32_16x16x32_bf16 v[84:87], v[166:169], v[198:201], v[84:87]
	v_mfma_f32_16x16x32_bf16 v[80:83], v[174:177], v[198:201], v[80:83]
	v_mfma_f32_16x16x32_bf16 v[68:71], v[166:169], v[212:215], v[68:71]
	v_mfma_f32_16x16x32_bf16 v[64:67], v[174:177], v[212:215], v[64:67]
	s_barrier
	s_mov_b32 m0, s59
	v_lshl_add_u64 v[202:203], s[30:31], 0, v[130:131]
	s_add_u32 s48, s30, 0x2b4000
	ds_read_b128 v[178:181], v143 offset:16384
	ds_read_b128 v[182:185], v143 offset:17408
	ds_read_b128 v[186:189], v143 offset:18432
	ds_read_b128 v[190:193], v143 offset:19456
	ds_read_b128 v[194:197], v143 offset:20480
	ds_read_b128 v[198:201], v143 offset:21504
	ds_read_b128 v[208:211], v143 offset:22528
	ds_read_b128 v[212:215], v143 offset:23552
	global_load_lds_dwordx4 v[202:203], off
	v_lshl_add_u64 v[216:217], s[30:31], 0, v[134:135]
	s_mov_b32 m0, s60
	s_addc_u32 s49, s31, 0
	global_load_lds_dwordx4 v[216:217], off
	v_lshl_add_u64 v[218:219], s[48:49], 0, v[130:131]
	s_mov_b32 m0, s61
	v_lshl_add_u64 v[220:221], s[38:39], 0, v[132:133]
	global_load_lds_dwordx4 v[218:219], off
	v_lshl_add_u64 v[218:219], s[48:49], 0, v[134:135]
	s_mov_b32 m0, s62
	s_nop 0
	global_load_lds_dwordx4 v[218:219], off
	v_lshl_add_u64 v[218:219], s[38:39], 0, v[128:129]
	s_mov_b32 m0, s17
	s_nop 0
	global_load_lds_dwordx4 v[218:219], off
	s_mov_b32 m0, s19
	s_nop 0
	global_load_lds_dwordx4 v[220:221], off
	s_waitcnt vmcnt(8)
	s_waitcnt lgkmcnt(0)
	s_barrier
; #define PG8_STAGE(bufoff, gbase, voff) do { _Pragma("unroll") for (int _i = 0; _i < 2; ++_i) \
;         __builtin_amdgcn_global_load_lds((const unsigned*)((const char*)(gbase) + (voff)[_i]), (PG8_LAS unsigned*)(lds + (bufoff) + ldsw + _i * 8192), 16, 0, 0); } while (0)
; #define PG8_LDA(dst, b, h) do { _Pragma("unroll") for (int m = 0; m < 4; ++m) _Pragma("unroll") for (int k = 0; k < 2; ++k) dst[m][k] = *(const PG8_LAS bf16x8*)(lds + PG8_SA(b, h) + aoff + m * 2048 + k * 1024); } while (0)
; #define PG8_LDB(dst, b, h) do { _Pragma("unroll") for (int n = 0; n < 2; ++n) _Pragma("unroll") for (int k = 0; k < 2; ++k) dst[n][k] = *(const PG8_LAS bf16x8*)(lds + PG8_SB(b, h) + boff + n * 2048 + k * 1024); } while (0)
; #define PG8_MMA(ai, bj, At, Bt) do { __builtin_amdgcn_s_setprio(1); _Pragma("unroll") for (int m = 0; m < 4; ++m) _Pragma("unroll") for (int n = 0; n < 2; ++n) _Pragma("unroll") for (int k = 0; k < 2; ++k) \
;         acc[ai][bj][m][n] = __builtin_amdgcn_mfma_f32_16x16x32_bf16(Bt[n][k], At[m][k], acc[ai][bj][m][n], 0, 0, 0); __builtin_amdgcn_s_setprio(0); } while (0)
; #define PG8_WAIT_V(n) asm volatile("s_waitcnt vmcnt(" #n ")" ::: "memory")
; #define PG8_WAIT_L(n) asm volatile("s_waitcnt lgkmcnt(" #n ")" ::: "memory")
; #define PG8_BAR __builtin_amdgcn_s_barrier()
; #define PG8_SCHED __builtin_amdgcn_sched_barrier(0)
; template <class Epi, class Sched, bool ALIGN_EPI = false, bool SP2 = false>
; __device__ __forceinline__ void gemm_phase(PG8_LAS unsigned char* lds, const Gemm g, const Sched& S, const Epi& E, int wid) {
;     ...
;             PG8_WAIT_V(8); PG8_WAIT_L(0); PG8_BAR; PG8_MMA(1, 0, At, B0); PG8_MMA(1, 1, At, B1); PG8_BAR; PG8_SCHED;
;             PG8_LDB(B0, 1, 0); PG8_LDB(B1, 1, 1); PG8_SCHED; PG8_LDA(At, 1, 0); PG8_STAGE(PG8_SA(0, 1), a2 + hstepA, voffA);
;             PG8_WAIT_V(8); PG8_WAIT_L(0); PG8_BAR; PG8_MMA(0, 0, At, B0); PG8_MMA(0, 1, At, B1); PG8_BAR; PG8_SCHED;
	v_mfma_f32_16x16x32_bf16 v[60:63], v[146:149], v[178:181], v[60:63]
	v_mfma_f32_16x16x32_bf16 v[56:59], v[154:157], v[178:181], v[56:59]
	v_mfma_f32_16x16x32_bf16 v[44:47], v[146:149], v[186:189], v[44:47]
	v_mfma_f32_16x16x32_bf16 v[40:43], v[154:157], v[186:189], v[40:43]
	v_mfma_f32_16x16x32_bf16 v[28:31], v[146:149], v[194:197], v[28:31]
	v_mfma_f32_16x16x32_bf16 v[24:27], v[154:157], v[194:197], v[24:27]
	v_mfma_f32_16x16x32_bf16 v[12:15], v[146:149], v[208:211], v[12:15]
	v_mfma_f32_16x16x32_bf16 v[8:11], v[154:157], v[208:211], v[8:11]
	v_mfma_f32_16x16x32_bf16 v[60:63], v[150:153], v[182:185], v[60:63]
	v_mfma_f32_16x16x32_bf16 v[56:59], v[158:161], v[182:185], v[56:59]
	v_mfma_f32_16x16x32_bf16 v[44:47], v[150:153], v[190:193], v[44:47]
	v_mfma_f32_16x16x32_bf16 v[40:43], v[158:161], v[190:193], v[40:43]
	v_mfma_f32_16x16x32_bf16 v[28:31], v[150:153], v[198:201], v[28:31]
	v_mfma_f32_16x16x32_bf16 v[24:27], v[158:161], v[198:201], v[24:27]
	v_mfma_f32_16x16x32_bf16 v[12:15], v[150:153], v[212:215], v[12:15]
	v_mfma_f32_16x16x32_bf16 v[8:11], v[158:161], v[212:215], v[8:11]
	v_mfma_f32_16x16x32_bf16 v[52:55], v[162:165], v[178:181], v[52:55]
	v_mfma_f32_16x16x32_bf16 v[48:51], v[170:173], v[178:181], v[48:51]
	v_mfma_f32_16x16x32_bf16 v[36:39], v[162:165], v[186:189], v[36:39]
	v_mfma_f32_16x16x32_bf16 v[32:35], v[170:173], v[186:189], v[32:35]
	v_mfma_f32_16x16x32_bf16 v[20:23], v[162:165], v[194:197], v[20:23]
	v_mfma_f32_16x16x32_bf16 v[16:19], v[170:173], v[194:197], v[16:19]
	v_mfma_f32_16x16x32_bf16 v[4:7], v[162:165], v[208:211], v[4:7]
	v_mfma_f32_16x16x32_bf16 v[0:3], v[170:173], v[208:211], v[0:3]
	v_mfma_f32_16x16x32_bf16 v[52:55], v[166:169], v[182:185], v[52:55]
	v_mfma_f32_16x16x32_bf16 v[48:51], v[174:177], v[182:185], v[48:51]
	v_mfma_f32_16x16x32_bf16 v[36:39], v[166:169], v[190:193], v[36:39]
	v_mfma_f32_16x16x32_bf16 v[32:35], v[174:177], v[190:193], v[32:35]
	v_mfma_f32_16x16x32_bf16 v[20:23], v[166:169], v[198:201], v[20:23]
	v_mfma_f32_16x16x32_bf16 v[16:19], v[174:177], v[198:201], v[16:19]
	v_mfma_f32_16x16x32_bf16 v[4:7], v[166:169], v[212:215], v[4:7]
	v_mfma_f32_16x16x32_bf16 v[0:3], v[174:177], v[212:215], v[0:3]
	s_barrier
	ds_read_b128 v[146:149], v144
	ds_read_b128 v[150:153], v144 offset:1024
	ds_read_b128 v[154:157], v144 offset:2048
	ds_read_b128 v[158:161], v144 offset:3072
	ds_read_b128 v[162:165], v145
	ds_read_b128 v[166:169], v145 offset:1024
	ds_read_b128 v[170:173], v145 offset:2048
	ds_read_b128 v[174:177], v145 offset:3072
	s_add_u32 s38, s38, 0x2b4000
	s_addc_u32 s39, s39, 0
	s_mov_b32 m0, s22
	v_lshl_add_u64 v[222:223], s[38:39], 0, v[128:129]
	ds_read_b128 v[178:181], v143 offset:32768
	ds_read_b128 v[182:185], v143 offset:33792
	ds_read_b128 v[186:189], v143 offset:34816
	ds_read_b128 v[190:193], v143 offset:35840
	ds_read_b128 v[194:197], v143 offset:36864
	ds_read_b128 v[198:201], v143 offset:37888
	ds_read_b128 v[208:211], v143 offset:38912
	ds_read_b128 v[212:215], v143 offset:39936
	global_load_lds_dwordx4 v[222:223], off
	v_lshl_add_u64 v[222:223], s[38:39], 0, v[132:133]
	s_mov_b32 m0, s23
	s_nop 0
	global_load_lds_dwordx4 v[222:223], off
	s_waitcnt vmcnt(8)
	s_waitcnt lgkmcnt(0)
	s_barrier
	v_mfma_f32_16x16x32_bf16 v[124:127], v[146:149], v[178:181], v[124:127]
	v_mfma_f32_16x16x32_bf16 v[120:123], v[154:157], v[178:181], v[120:123]
	v_mfma_f32_16x16x32_bf16 v[108:111], v[146:149], v[186:189], v[108:111]
	v_mfma_f32_16x16x32_bf16 v[104:107], v[154:157], v[186:189], v[104:107]
	v_mfma_f32_16x16x32_bf16 v[92:95], v[146:149], v[194:197], v[92:95]
	v_mfma_f32_16x16x32_bf16 v[88:91], v[154:157], v[194:197], v[88:91]
	v_mfma_f32_16x16x32_bf16 v[76:79], v[146:149], v[208:211], v[76:79]
	v_mfma_f32_16x16x32_bf16 v[72:75], v[154:157], v[208:211], v[72:75]
	v_mfma_f32_16x16x32_bf16 v[124:127], v[150:153], v[182:185], v[124:127]
	v_mfma_f32_16x16x32_bf16 v[120:123], v[158:161], v[182:185], v[120:123]
	v_mfma_f32_16x16x32_bf16 v[108:111], v[150:153], v[190:193], v[108:111]
	v_mfma_f32_16x16x32_bf16 v[104:107], v[158:161], v[190:193], v[104:107]
	v_mfma_f32_16x16x32_bf16 v[92:95], v[150:153], v[198:201], v[92:95]
	v_mfma_f32_16x16x32_bf16 v[88:91], v[158:161], v[198:201], v[88:91]
	v_mfma_f32_16x16x32_bf16 v[76:79], v[150:153], v[212:215], v[76:79]
	v_mfma_f32_16x16x32_bf16 v[72:75], v[158:161], v[212:215], v[72:75]
	v_mfma_f32_16x16x32_bf16 v[116:119], v[162:165], v[178:181], v[116:119]
	v_mfma_f32_16x16x32_bf16 v[112:115], v[170:173], v[178:181], v[112:115]
	v_mfma_f32_16x16x32_bf16 v[100:103], v[162:165], v[186:189], v[100:103]
	v_mfma_f32_16x16x32_bf16 v[96:99], v[170:173], v[186:189], v[96:99]
	v_mfma_f32_16x16x32_bf16 v[84:87], v[162:165], v[194:197], v[84:87]
	v_mfma_f32_16x16x32_bf16 v[80:83], v[170:173], v[194:197], v[80:83]
	v_mfma_f32_16x16x32_bf16 v[68:71], v[162:165], v[208:211], v[68:71]
	v_mfma_f32_16x16x32_bf16 v[64:67], v[170:173], v[208:211], v[64:67]
	v_mfma_f32_16x16x32_bf16 v[116:119], v[166:169], v[182:185], v[116:119]
	v_mfma_f32_16x16x32_bf16 v[112:115], v[174:177], v[182:185], v[112:115]
	v_mfma_f32_16x16x32_bf16 v[100:103], v[166:169], v[190:193], v[100:103]
	v_mfma_f32_16x16x32_bf16 v[96:99], v[174:177], v[190:193], v[96:99]
	v_mfma_f32_16x16x32_bf16 v[84:87], v[166:169], v[198:201], v[84:87]
	v_mfma_f32_16x16x32_bf16 v[80:83], v[174:177], v[198:201], v[80:83]
	v_mfma_f32_16x16x32_bf16 v[68:71], v[166:169], v[212:215], v[68:71]
	v_mfma_f32_16x16x32_bf16 v[64:67], v[174:177], v[212:215], v[64:67]
	s_barrier
; #define PG8_STAGE(bufoff, gbase, voff) do { _Pragma("unroll") for (int _i = 0; _i < 2; ++_i) \
;         __builtin_amdgcn_global_load_lds((const unsigned*)((const char*)(gbase) + (voff)[_i]), (PG8_LAS unsigned*)(lds + (bufoff) + ldsw + _i * 8192), 16, 0, 0); } while (0)
; #define PG8_STAGE_NT(bufoff, gbase, voff) do { _Pragma("unroll") for (int _i = 0; _i < 2; ++_i) \
;         __builtin_amdgcn_global_load_lds((const unsigned*)((const char*)(gbase) + (voff)[_i]), (PG8_LAS unsigned*)(lds + (bufoff) + ldsw + _i * 8192), 16, 0, PG8_B_AUX); } while (0)
; #define PG8_LDA(dst, b, h) do { _Pragma("unroll") for (int m = 0; m < 4; ++m) _Pragma("unroll") for (int k = 0; k < 2; ++k) dst[m][k] = *(const PG8_LAS bf16x8*)(lds + PG8_SA(b, h) + aoff + m * 2048 + k * 1024); } while (0)
; #define PG8_MMA(ai, bj, At, Bt) do { __builtin_amdgcn_s_setprio(1); _Pragma("unroll") for (int m = 0; m < 4; ++m) _Pragma("unroll") for (int n = 0; n < 2; ++n) _Pragma("unroll") for (int k = 0; k < 2; ++k) \
;         acc[ai][bj][m][n] = __builtin_amdgcn_mfma_f32_16x16x32_bf16(Bt[n][k], At[m][k], acc[ai][bj][m][n], 0, 0, 0); __builtin_amdgcn_s_setprio(0); } while (0)
; #define PG8_WAIT_V(n) asm volatile("s_waitcnt vmcnt(" #n ")" ::: "memory")
; #define PG8_WAIT_L(n) asm volatile("s_waitcnt lgkmcnt(" #n ")" ::: "memory")
; #define PG8_BAR __builtin_amdgcn_s_barrier()
; #define PG8_SCHED __builtin_amdgcn_sched_barrier(0)
; template <class Epi, class Sched, bool ALIGN_EPI = false, bool SP2 = false>
; __device__ __forceinline__ void gemm_phase(PG8_LAS unsigned char* lds, const Gemm g, const Sched& S, const Epi& E, int wid) {
;     ...
;             PG8_LDA(At, 1, 1); PG8_STAGE_NT(PG8_SB(1, 0), b3, voffB); PG8_STAGE_NT(PG8_SB(1, 1), b3 + hstepB, voffB); PG8_STAGE(PG8_SA(1, 0), a3, voffA);
;             PG8_WAIT_V(8); PG8_WAIT_L(0); PG8_BAR; PG8_MMA(1, 0, At, B0); PG8_MMA(1, 1, At, B1); PG8_BAR; PG8_SCHED;
;     ...
;     PG8_WAIT_V(0);
;     if constexpr (!ALIGN_EPI) { if (wr == 0) PG8_BAR; }
	s_mov_b32 m0, s63
	v_lshl_add_u64 v[202:203], v[202:203], 0, s[4:5]
	s_add_u32 s30, s30, 0x2b4080
	ds_read_b128 v[178:181], v143 offset:49152
	ds_read_b128 v[182:185], v143 offset:50176
	ds_read_b128 v[186:189], v143 offset:51200
	ds_read_b128 v[190:193], v143 offset:52224
	ds_read_b128 v[194:197], v143 offset:53248
	ds_read_b128 v[198:201], v143 offset:54272
	ds_read_b128 v[208:211], v143 offset:55296
	ds_read_b128 v[212:215], v143 offset:56320
	global_load_lds_dwordx4 v[202:203], off
	v_lshl_add_u64 v[202:203], v[216:217], 0, s[4:5]
	s_mov_b32 m0, s64
	s_addc_u32 s31, s31, 0
	global_load_lds_dwordx4 v[202:203], off
	v_lshl_add_u64 v[202:203], s[30:31], 0, v[130:131]
	s_mov_b32 m0, s65
	s_nop 0
	global_load_lds_dwordx4 v[202:203], off
	v_lshl_add_u64 v[202:203], s[30:31], 0, v[134:135]
	s_mov_b32 m0, s66
	s_nop 0
	global_load_lds_dwordx4 v[202:203], off
	v_lshl_add_u64 v[202:203], v[218:219], 0, s[4:5]
	s_mov_b32 m0, s25
	s_nop 0
	global_load_lds_dwordx4 v[202:203], off
	v_lshl_add_u64 v[202:203], v[220:221], 0, s[4:5]
	s_mov_b32 m0, s56
	s_nop 0
	global_load_lds_dwordx4 v[202:203], off
	s_nop 0
	s_waitcnt vmcnt(8)
	s_waitcnt lgkmcnt(0)
	s_barrier
	v_mfma_f32_16x16x32_bf16 v[60:63], v[146:149], v[178:181], v[60:63]
	v_mfma_f32_16x16x32_bf16 v[56:59], v[154:157], v[178:181], v[56:59]
	v_mfma_f32_16x16x32_bf16 v[44:47], v[146:149], v[186:189], v[44:47]
	v_mfma_f32_16x16x32_bf16 v[40:43], v[154:157], v[186:189], v[40:43]
	v_mfma_f32_16x16x32_bf16 v[28:31], v[146:149], v[194:197], v[28:31]
	v_mfma_f32_16x16x32_bf16 v[24:27], v[154:157], v[194:197], v[24:27]
	v_mfma_f32_16x16x32_bf16 v[12:15], v[146:149], v[208:211], v[12:15]
	v_mfma_f32_16x16x32_bf16 v[8:11], v[154:157], v[208:211], v[8:11]
	v_mfma_f32_16x16x32_bf16 v[60:63], v[150:153], v[182:185], v[60:63]
	v_mfma_f32_16x16x32_bf16 v[56:59], v[158:161], v[182:185], v[56:59]
	v_mfma_f32_16x16x32_bf16 v[44:47], v[150:153], v[190:193], v[44:47]
	v_mfma_f32_16x16x32_bf16 v[40:43], v[158:161], v[190:193], v[40:43]
	v_mfma_f32_16x16x32_bf16 v[28:31], v[150:153], v[198:201], v[28:31]
	v_mfma_f32_16x16x32_bf16 v[24:27], v[158:161], v[198:201], v[24:27]
	v_mfma_f32_16x16x32_bf16 v[12:15], v[150:153], v[212:215], v[12:15]
	v_mfma_f32_16x16x32_bf16 v[8:11], v[158:161], v[212:215], v[8:11]
	v_mfma_f32_16x16x32_bf16 v[52:55], v[162:165], v[178:181], v[52:55]
	v_mfma_f32_16x16x32_bf16 v[48:51], v[170:173], v[178:181], v[48:51]
	v_mfma_f32_16x16x32_bf16 v[36:39], v[162:165], v[186:189], v[36:39]
	v_mfma_f32_16x16x32_bf16 v[32:35], v[170:173], v[186:189], v[32:35]
	v_mfma_f32_16x16x32_bf16 v[20:23], v[162:165], v[194:197], v[20:23]
	v_mfma_f32_16x16x32_bf16 v[16:19], v[170:173], v[194:197], v[16:19]
	v_mfma_f32_16x16x32_bf16 v[4:7], v[162:165], v[208:211], v[4:7]
	v_mfma_f32_16x16x32_bf16 v[0:3], v[170:173], v[208:211], v[0:3]
	v_mfma_f32_16x16x32_bf16 v[52:55], v[166:169], v[182:185], v[52:55]
	v_mfma_f32_16x16x32_bf16 v[48:51], v[174:177], v[182:185], v[48:51]
	v_mfma_f32_16x16x32_bf16 v[36:39], v[166:169], v[190:193], v[36:39]
	v_mfma_f32_16x16x32_bf16 v[32:35], v[174:177], v[190:193], v[32:35]
	v_mfma_f32_16x16x32_bf16 v[20:23], v[166:169], v[198:201], v[20:23]
	v_mfma_f32_16x16x32_bf16 v[16:19], v[174:177], v[198:201], v[16:19]
	v_mfma_f32_16x16x32_bf16 v[4:7], v[166:169], v[212:215], v[4:7]
	v_mfma_f32_16x16x32_bf16 v[0:3], v[174:177], v[212:215], v[0:3]
	s_barrier
	s_add_i32 s41, s41, 2
	s_add_u32 s21, s21, 0x100
	s_addc_u32 s40, s40, 0
	s_add_u32 s8, s8, 0x100
	s_addc_u32 s9, s9, 0
	v_lshl_add_u64 v[136:137], v[136:137], 0, s[28:29]
	s_cmpk_lt_u32 s41, 0xaa
	v_lshl_add_u64 v[138:139], v[138:139], 0, s[28:29]
	s_cbranch_scc1 .LBB0_1307
	s_waitcnt vmcnt(0)
	s_andn2_b64 vcc, exec, s[44:45]
	s_cbranch_vccnz .LBB0_1310
	s_barrier
